# hand-scheduled scan loops (hgrn/rwkv ctx + rwkv16): LDS prefetch, batched y reductions; prep: batched serialized loads
# speedup vs baseline: 1.0275x; 1.0255x over previous
.LBB0_417:
	s_add_i32 s19, s26, 1
	s_bitcmp1_b32 s26, 0
	s_cselect_b32 s26, 0x6000, 0
	s_add_i32 s26, s78, s26
	v_add_u32_e32 v41, s26, v9
	v_lshl_add_u32 v43, v8, 2, s26
	v_add_u32_e32 v43, 0x5000, v43
	ds_read_b128 v[52:55], v41 offset:4096
	ds_read_b128 v[60:63], v41 offset:8192
	ds_read2_b32 v[68:69], v43 offset0:0 offset1:32
	ds_read_b128 v[56:59], v41 offset:4112
	ds_read_b128 v[64:67], v41 offset:8208
	ds_read_b128 v[44:47], v41 offset:0
	ds_read_b128 v[48:51], v41 offset:16
	v_and_b32_e32 v124, 1, v11
	v_and_b32_e32 v125, 2, v11
	v_cmp_ne_u32_e64 s[4:5], 0, v124
	v_cmp_ne_u32_e64 s[6:7], 0, v125
	ds_read_b128 v[88:91], v41 offset:4352
	ds_read_b128 v[96:99], v41 offset:8448
	ds_read2_b32 v[104:105], v43 offset0:64 offset1:96
	ds_read_b128 v[92:95], v41 offset:4368
	ds_read_b128 v[100:103], v41 offset:8464
	ds_read_b128 v[80:83], v41 offset:256
	ds_read_b128 v[84:87], v41 offset:272
	s_waitcnt lgkmcnt(7)
	v_pk_mul_f32 v[70:71], v[60:61], v[68:69] op_sel_hi:[1,0]
	v_pk_mul_f32 v[72:73], v[62:63], v[68:69] op_sel_hi:[1,0]
	v_pk_mul_f32 v[74:75], v[64:65], v[68:69] op_sel_hi:[1,0]
	v_pk_mul_f32 v[76:77], v[66:67], v[68:69] op_sel_hi:[1,0]
	v_pk_mul_f32 v[78:79], v[60:61], v[68:69] op_sel:[0,1] op_sel_hi:[1,1]
	v_pk_mul_f32 v[136:137], v[62:63], v[68:69] op_sel:[0,1] op_sel_hi:[1,1]
	v_pk_mul_f32 v[138:139], v[64:65], v[68:69] op_sel:[0,1] op_sel_hi:[1,1]
	v_pk_mul_f32 v[140:141], v[66:67], v[68:69] op_sel:[0,1] op_sel_hi:[1,1]
	v_pk_fma_f32 v[34:35], v[34:35], v[52:53], v[70:71]
	v_pk_fma_f32 v[32:33], v[32:33], v[54:55], v[72:73]
	v_pk_fma_f32 v[30:31], v[30:31], v[56:57], v[74:75]
	v_pk_fma_f32 v[28:29], v[28:29], v[58:59], v[76:77]
	v_pk_fma_f32 v[26:27], v[26:27], v[52:53], v[78:79]
	v_pk_fma_f32 v[24:25], v[24:25], v[54:55], v[136:137]
	v_pk_fma_f32 v[22:23], v[22:23], v[56:57], v[138:139]
	v_pk_fma_f32 v[6:7], v[6:7], v[58:59], v[140:141]
	v_pk_mul_f32 v[142:143], v[46:47], v[32:33]
	v_pk_mul_f32 v[144:145], v[46:47], v[24:25]
	v_pk_fma_f32 v[142:143], v[44:45], v[34:35], v[142:143]
	v_pk_fma_f32 v[144:145], v[44:45], v[26:27], v[144:145]
	v_pk_fma_f32 v[142:143], v[48:49], v[30:31], v[142:143]
	v_pk_fma_f32 v[144:145], v[48:49], v[22:23], v[144:145]
	v_pk_fma_f32 v[142:143], v[50:51], v[28:29], v[142:143]
	v_pk_fma_f32 v[144:145], v[50:51], v[6:7], v[144:145]
	v_add_f32_e32 v108, v142, v143
	v_add_f32_e32 v116, v144, v145
	ds_read_b128 v[52:55], v41 offset:4608
	ds_read_b128 v[60:63], v41 offset:8704
	ds_read2_b32 v[68:69], v43 offset0:128 offset1:160
	ds_read_b128 v[56:59], v41 offset:4624
	ds_read_b128 v[64:67], v41 offset:8720
	ds_read_b128 v[44:47], v41 offset:512
	ds_read_b128 v[48:51], v41 offset:528
	s_waitcnt lgkmcnt(7)
	v_pk_mul_f32 v[70:71], v[96:97], v[104:105] op_sel_hi:[1,0]
	v_pk_mul_f32 v[72:73], v[98:99], v[104:105] op_sel_hi:[1,0]
	v_pk_mul_f32 v[74:75], v[100:101], v[104:105] op_sel_hi:[1,0]
	v_pk_mul_f32 v[76:77], v[102:103], v[104:105] op_sel_hi:[1,0]
	v_pk_mul_f32 v[78:79], v[96:97], v[104:105] op_sel:[0,1] op_sel_hi:[1,1]
	v_pk_mul_f32 v[136:137], v[98:99], v[104:105] op_sel:[0,1] op_sel_hi:[1,1]
	v_pk_mul_f32 v[138:139], v[100:101], v[104:105] op_sel:[0,1] op_sel_hi:[1,1]
	v_pk_mul_f32 v[140:141], v[102:103], v[104:105] op_sel:[0,1] op_sel_hi:[1,1]
	v_pk_fma_f32 v[34:35], v[34:35], v[88:89], v[70:71]
	v_pk_fma_f32 v[32:33], v[32:33], v[90:91], v[72:73]
	v_pk_fma_f32 v[30:31], v[30:31], v[92:93], v[74:75]
	v_pk_fma_f32 v[28:29], v[28:29], v[94:95], v[76:77]
	v_pk_fma_f32 v[26:27], v[26:27], v[88:89], v[78:79]
	v_pk_fma_f32 v[24:25], v[24:25], v[90:91], v[136:137]
	v_pk_fma_f32 v[22:23], v[22:23], v[92:93], v[138:139]
	v_pk_fma_f32 v[6:7], v[6:7], v[94:95], v[140:141]
	v_pk_mul_f32 v[142:143], v[82:83], v[32:33]
	v_pk_mul_f32 v[144:145], v[82:83], v[24:25]
	v_pk_fma_f32 v[142:143], v[80:81], v[34:35], v[142:143]
	v_pk_fma_f32 v[144:145], v[80:81], v[26:27], v[144:145]
	v_pk_fma_f32 v[142:143], v[84:85], v[30:31], v[142:143]
	v_pk_fma_f32 v[144:145], v[84:85], v[22:23], v[144:145]
	v_pk_fma_f32 v[142:143], v[86:87], v[28:29], v[142:143]
	v_pk_fma_f32 v[144:145], v[86:87], v[6:7], v[144:145]
	v_add_f32_e32 v109, v142, v143
	v_add_f32_e32 v117, v144, v145
	ds_read_b128 v[88:91], v41 offset:4864
	ds_read_b128 v[96:99], v41 offset:8960
	ds_read2_b32 v[104:105], v43 offset0:192 offset1:224
	ds_read_b128 v[92:95], v41 offset:4880
	ds_read_b128 v[100:103], v41 offset:8976
	ds_read_b128 v[80:83], v41 offset:768
	ds_read_b128 v[84:87], v41 offset:784
	s_waitcnt lgkmcnt(7)
	v_pk_mul_f32 v[70:71], v[60:61], v[68:69] op_sel_hi:[1,0]
	v_pk_mul_f32 v[72:73], v[62:63], v[68:69] op_sel_hi:[1,0]
	v_pk_mul_f32 v[74:75], v[64:65], v[68:69] op_sel_hi:[1,0]
	v_pk_mul_f32 v[76:77], v[66:67], v[68:69] op_sel_hi:[1,0]
	v_pk_mul_f32 v[78:79], v[60:61], v[68:69] op_sel:[0,1] op_sel_hi:[1,1]
	v_pk_mul_f32 v[136:137], v[62:63], v[68:69] op_sel:[0,1] op_sel_hi:[1,1]
	v_pk_mul_f32 v[138:139], v[64:65], v[68:69] op_sel:[0,1] op_sel_hi:[1,1]
	v_pk_mul_f32 v[140:141], v[66:67], v[68:69] op_sel:[0,1] op_sel_hi:[1,1]
	v_pk_fma_f32 v[34:35], v[34:35], v[52:53], v[70:71]
	v_pk_fma_f32 v[32:33], v[32:33], v[54:55], v[72:73]
	v_pk_fma_f32 v[30:31], v[30:31], v[56:57], v[74:75]
	v_pk_fma_f32 v[28:29], v[28:29], v[58:59], v[76:77]
	v_pk_fma_f32 v[26:27], v[26:27], v[52:53], v[78:79]
	v_pk_fma_f32 v[24:25], v[24:25], v[54:55], v[136:137]
	v_pk_fma_f32 v[22:23], v[22:23], v[56:57], v[138:139]
	v_pk_fma_f32 v[6:7], v[6:7], v[58:59], v[140:141]
	v_pk_mul_f32 v[142:143], v[46:47], v[32:33]
	v_pk_mul_f32 v[144:145], v[46:47], v[24:25]
	v_pk_fma_f32 v[142:143], v[44:45], v[34:35], v[142:143]
	v_pk_fma_f32 v[144:145], v[44:45], v[26:27], v[144:145]
	v_pk_fma_f32 v[142:143], v[48:49], v[30:31], v[142:143]
	v_pk_fma_f32 v[144:145], v[48:49], v[22:23], v[144:145]
	v_pk_fma_f32 v[142:143], v[50:51], v[28:29], v[142:143]
	v_pk_fma_f32 v[144:145], v[50:51], v[6:7], v[144:145]
	v_add_f32_e32 v110, v142, v143
	v_add_f32_e32 v118, v144, v145
	v_add_u32_e32 v43, 0x400, v43
	ds_read_b128 v[52:55], v41 offset:5120
	ds_read_b128 v[60:63], v41 offset:9216
	ds_read2_b32 v[68:69], v43 offset0:0 offset1:32
	ds_read_b128 v[56:59], v41 offset:5136
	ds_read_b128 v[64:67], v41 offset:9232
	ds_read_b128 v[44:47], v41 offset:1024
	ds_read_b128 v[48:51], v41 offset:1040
	s_waitcnt lgkmcnt(7)
	v_pk_mul_f32 v[70:71], v[96:97], v[104:105] op_sel_hi:[1,0]
	v_pk_mul_f32 v[72:73], v[98:99], v[104:105] op_sel_hi:[1,0]
	v_pk_mul_f32 v[74:75], v[100:101], v[104:105] op_sel_hi:[1,0]
	v_pk_mul_f32 v[76:77], v[102:103], v[104:105] op_sel_hi:[1,0]
	v_pk_mul_f32 v[78:79], v[96:97], v[104:105] op_sel:[0,1] op_sel_hi:[1,1]
	v_pk_mul_f32 v[136:137], v[98:99], v[104:105] op_sel:[0,1] op_sel_hi:[1,1]
	v_pk_mul_f32 v[138:139], v[100:101], v[104:105] op_sel:[0,1] op_sel_hi:[1,1]
	v_pk_mul_f32 v[140:141], v[102:103], v[104:105] op_sel:[0,1] op_sel_hi:[1,1]
	v_pk_fma_f32 v[34:35], v[34:35], v[88:89], v[70:71]
	v_pk_fma_f32 v[32:33], v[32:33], v[90:91], v[72:73]
	v_pk_fma_f32 v[30:31], v[30:31], v[92:93], v[74:75]
	v_pk_fma_f32 v[28:29], v[28:29], v[94:95], v[76:77]
	v_pk_fma_f32 v[26:27], v[26:27], v[88:89], v[78:79]
	v_pk_fma_f32 v[24:25], v[24:25], v[90:91], v[136:137]
	v_pk_fma_f32 v[22:23], v[22:23], v[92:93], v[138:139]
	v_pk_fma_f32 v[6:7], v[6:7], v[94:95], v[140:141]
	v_pk_mul_f32 v[142:143], v[82:83], v[32:33]
	v_pk_mul_f32 v[144:145], v[82:83], v[24:25]
	v_pk_fma_f32 v[142:143], v[80:81], v[34:35], v[142:143]
	v_pk_fma_f32 v[144:145], v[80:81], v[26:27], v[144:145]
	v_pk_fma_f32 v[142:143], v[84:85], v[30:31], v[142:143]
	v_pk_fma_f32 v[144:145], v[84:85], v[22:23], v[144:145]
	v_pk_fma_f32 v[142:143], v[86:87], v[28:29], v[142:143]
	v_pk_fma_f32 v[144:145], v[86:87], v[6:7], v[144:145]
	v_add_f32_e32 v111, v142, v143
	v_add_f32_e32 v119, v144, v145
	ds_read_b128 v[88:91], v41 offset:5376
	ds_read_b128 v[96:99], v41 offset:9472
	ds_read2_b32 v[104:105], v43 offset0:64 offset1:96
	ds_read_b128 v[92:95], v41 offset:5392
	ds_read_b128 v[100:103], v41 offset:9488
	ds_read_b128 v[80:83], v41 offset:1280
	ds_read_b128 v[84:87], v41 offset:1296
	s_waitcnt lgkmcnt(7)
	v_pk_mul_f32 v[70:71], v[60:61], v[68:69] op_sel_hi:[1,0]
	v_pk_mul_f32 v[72:73], v[62:63], v[68:69] op_sel_hi:[1,0]
	v_pk_mul_f32 v[74:75], v[64:65], v[68:69] op_sel_hi:[1,0]
	v_pk_mul_f32 v[76:77], v[66:67], v[68:69] op_sel_hi:[1,0]
	v_pk_mul_f32 v[78:79], v[60:61], v[68:69] op_sel:[0,1] op_sel_hi:[1,1]
	v_pk_mul_f32 v[136:137], v[62:63], v[68:69] op_sel:[0,1] op_sel_hi:[1,1]
	v_pk_mul_f32 v[138:139], v[64:65], v[68:69] op_sel:[0,1] op_sel_hi:[1,1]
	v_pk_mul_f32 v[140:141], v[66:67], v[68:69] op_sel:[0,1] op_sel_hi:[1,1]
	v_pk_fma_f32 v[34:35], v[34:35], v[52:53], v[70:71]
	v_pk_fma_f32 v[32:33], v[32:33], v[54:55], v[72:73]
	v_pk_fma_f32 v[30:31], v[30:31], v[56:57], v[74:75]
	v_pk_fma_f32 v[28:29], v[28:29], v[58:59], v[76:77]
	v_pk_fma_f32 v[26:27], v[26:27], v[52:53], v[78:79]
	v_pk_fma_f32 v[24:25], v[24:25], v[54:55], v[136:137]
	v_pk_fma_f32 v[22:23], v[22:23], v[56:57], v[138:139]
	v_pk_fma_f32 v[6:7], v[6:7], v[58:59], v[140:141]
	v_pk_mul_f32 v[142:143], v[46:47], v[32:33]
	v_pk_mul_f32 v[144:145], v[46:47], v[24:25]
	v_pk_fma_f32 v[142:143], v[44:45], v[34:35], v[142:143]
	v_pk_fma_f32 v[144:145], v[44:45], v[26:27], v[144:145]
	v_pk_fma_f32 v[142:143], v[48:49], v[30:31], v[142:143]
	v_pk_fma_f32 v[144:145], v[48:49], v[22:23], v[144:145]
	v_pk_fma_f32 v[142:143], v[50:51], v[28:29], v[142:143]
	v_pk_fma_f32 v[144:145], v[50:51], v[6:7], v[144:145]
	v_add_f32_e32 v112, v142, v143
	v_add_f32_e32 v120, v144, v145
	ds_read_b128 v[52:55], v41 offset:5632
	ds_read_b128 v[60:63], v41 offset:9728
	ds_read2_b32 v[68:69], v43 offset0:128 offset1:160
	ds_read_b128 v[56:59], v41 offset:5648
	ds_read_b128 v[64:67], v41 offset:9744
	ds_read_b128 v[44:47], v41 offset:1536
	ds_read_b128 v[48:51], v41 offset:1552
	s_waitcnt lgkmcnt(7)
	v_pk_mul_f32 v[70:71], v[96:97], v[104:105] op_sel_hi:[1,0]
	v_pk_mul_f32 v[72:73], v[98:99], v[104:105] op_sel_hi:[1,0]
	v_pk_mul_f32 v[74:75], v[100:101], v[104:105] op_sel_hi:[1,0]
	v_pk_mul_f32 v[76:77], v[102:103], v[104:105] op_sel_hi:[1,0]
	v_pk_mul_f32 v[78:79], v[96:97], v[104:105] op_sel:[0,1] op_sel_hi:[1,1]
	v_pk_mul_f32 v[136:137], v[98:99], v[104:105] op_sel:[0,1] op_sel_hi:[1,1]
	v_pk_mul_f32 v[138:139], v[100:101], v[104:105] op_sel:[0,1] op_sel_hi:[1,1]
	v_pk_mul_f32 v[140:141], v[102:103], v[104:105] op_sel:[0,1] op_sel_hi:[1,1]
	v_pk_fma_f32 v[34:35], v[34:35], v[88:89], v[70:71]
	v_pk_fma_f32 v[32:33], v[32:33], v[90:91], v[72:73]
	v_pk_fma_f32 v[30:31], v[30:31], v[92:93], v[74:75]
	v_pk_fma_f32 v[28:29], v[28:29], v[94:95], v[76:77]
	v_pk_fma_f32 v[26:27], v[26:27], v[88:89], v[78:79]
	v_pk_fma_f32 v[24:25], v[24:25], v[90:91], v[136:137]
	v_pk_fma_f32 v[22:23], v[22:23], v[92:93], v[138:139]
	v_pk_fma_f32 v[6:7], v[6:7], v[94:95], v[140:141]
	v_pk_mul_f32 v[142:143], v[82:83], v[32:33]
	v_pk_mul_f32 v[144:145], v[82:83], v[24:25]
	v_pk_fma_f32 v[142:143], v[80:81], v[34:35], v[142:143]
	v_pk_fma_f32 v[144:145], v[80:81], v[26:27], v[144:145]
	v_pk_fma_f32 v[142:143], v[84:85], v[30:31], v[142:143]
	v_pk_fma_f32 v[144:145], v[84:85], v[22:23], v[144:145]
	v_pk_fma_f32 v[142:143], v[86:87], v[28:29], v[142:143]
	v_pk_fma_f32 v[144:145], v[86:87], v[6:7], v[144:145]
	v_add_f32_e32 v113, v142, v143
	v_add_f32_e32 v121, v144, v145
	ds_read_b128 v[88:91], v41 offset:5888
	ds_read_b128 v[96:99], v41 offset:9984
	ds_read2_b32 v[104:105], v43 offset0:192 offset1:224
	ds_read_b128 v[92:95], v41 offset:5904
	ds_read_b128 v[100:103], v41 offset:10000
	ds_read_b128 v[80:83], v41 offset:1792
	ds_read_b128 v[84:87], v41 offset:1808
	s_waitcnt lgkmcnt(7)
	v_pk_mul_f32 v[70:71], v[60:61], v[68:69] op_sel_hi:[1,0]
	v_pk_mul_f32 v[72:73], v[62:63], v[68:69] op_sel_hi:[1,0]
	v_pk_mul_f32 v[74:75], v[64:65], v[68:69] op_sel_hi:[1,0]
	v_pk_mul_f32 v[76:77], v[66:67], v[68:69] op_sel_hi:[1,0]
	v_pk_mul_f32 v[78:79], v[60:61], v[68:69] op_sel:[0,1] op_sel_hi:[1,1]
	v_pk_mul_f32 v[136:137], v[62:63], v[68:69] op_sel:[0,1] op_sel_hi:[1,1]
	v_pk_mul_f32 v[138:139], v[64:65], v[68:69] op_sel:[0,1] op_sel_hi:[1,1]
	v_pk_mul_f32 v[140:141], v[66:67], v[68:69] op_sel:[0,1] op_sel_hi:[1,1]
	v_pk_fma_f32 v[34:35], v[34:35], v[52:53], v[70:71]
	v_pk_fma_f32 v[32:33], v[32:33], v[54:55], v[72:73]
	v_pk_fma_f32 v[30:31], v[30:31], v[56:57], v[74:75]
	v_pk_fma_f32 v[28:29], v[28:29], v[58:59], v[76:77]
	v_pk_fma_f32 v[26:27], v[26:27], v[52:53], v[78:79]
	v_pk_fma_f32 v[24:25], v[24:25], v[54:55], v[136:137]
	v_pk_fma_f32 v[22:23], v[22:23], v[56:57], v[138:139]
	v_pk_fma_f32 v[6:7], v[6:7], v[58:59], v[140:141]
	v_pk_mul_f32 v[142:143], v[46:47], v[32:33]
	v_pk_mul_f32 v[144:145], v[46:47], v[24:25]
	v_pk_fma_f32 v[142:143], v[44:45], v[34:35], v[142:143]
	v_pk_fma_f32 v[144:145], v[44:45], v[26:27], v[144:145]
	v_pk_fma_f32 v[142:143], v[48:49], v[30:31], v[142:143]
	v_pk_fma_f32 v[144:145], v[48:49], v[22:23], v[144:145]
	v_pk_fma_f32 v[142:143], v[50:51], v[28:29], v[142:143]
	v_pk_fma_f32 v[144:145], v[50:51], v[6:7], v[144:145]
	v_add_f32_e32 v114, v142, v143
	v_add_f32_e32 v122, v144, v145
	v_add_u32_e32 v43, 0x400, v43
	ds_read_b128 v[52:55], v41 offset:6144
	ds_read_b128 v[60:63], v41 offset:10240
	ds_read2_b32 v[68:69], v43 offset0:0 offset1:32
	ds_read_b128 v[56:59], v41 offset:6160
	ds_read_b128 v[64:67], v41 offset:10256
	ds_read_b128 v[44:47], v41 offset:2048
	ds_read_b128 v[48:51], v41 offset:2064
	s_waitcnt lgkmcnt(7)
	v_pk_mul_f32 v[70:71], v[96:97], v[104:105] op_sel_hi:[1,0]
	v_pk_mul_f32 v[72:73], v[98:99], v[104:105] op_sel_hi:[1,0]
	v_pk_mul_f32 v[74:75], v[100:101], v[104:105] op_sel_hi:[1,0]
	v_pk_mul_f32 v[76:77], v[102:103], v[104:105] op_sel_hi:[1,0]
	v_pk_mul_f32 v[78:79], v[96:97], v[104:105] op_sel:[0,1] op_sel_hi:[1,1]
	v_pk_mul_f32 v[136:137], v[98:99], v[104:105] op_sel:[0,1] op_sel_hi:[1,1]
	v_pk_mul_f32 v[138:139], v[100:101], v[104:105] op_sel:[0,1] op_sel_hi:[1,1]
	v_pk_mul_f32 v[140:141], v[102:103], v[104:105] op_sel:[0,1] op_sel_hi:[1,1]
	v_pk_fma_f32 v[34:35], v[34:35], v[88:89], v[70:71]
	v_pk_fma_f32 v[32:33], v[32:33], v[90:91], v[72:73]
	v_pk_fma_f32 v[30:31], v[30:31], v[92:93], v[74:75]
	v_pk_fma_f32 v[28:29], v[28:29], v[94:95], v[76:77]
	v_pk_fma_f32 v[26:27], v[26:27], v[88:89], v[78:79]
	v_pk_fma_f32 v[24:25], v[24:25], v[90:91], v[136:137]
	v_pk_fma_f32 v[22:23], v[22:23], v[92:93], v[138:139]
	v_pk_fma_f32 v[6:7], v[6:7], v[94:95], v[140:141]
	v_pk_mul_f32 v[142:143], v[82:83], v[32:33]
	v_pk_mul_f32 v[144:145], v[82:83], v[24:25]
	v_pk_fma_f32 v[142:143], v[80:81], v[34:35], v[142:143]
	v_pk_fma_f32 v[144:145], v[80:81], v[26:27], v[144:145]
	v_pk_fma_f32 v[142:143], v[84:85], v[30:31], v[142:143]
	v_pk_fma_f32 v[144:145], v[84:85], v[22:23], v[144:145]
	v_pk_fma_f32 v[142:143], v[86:87], v[28:29], v[142:143]
	v_pk_fma_f32 v[144:145], v[86:87], v[6:7], v[144:145]
	v_add_f32_e32 v115, v142, v143
	v_add_f32_e32 v123, v144, v145
	v_cndmask_b32_e64 v70, v108, v109, s[4:5]
	v_cndmask_b32_e64 v72, v109, v108, s[4:5]
	v_cndmask_b32_e64 v74, v110, v111, s[4:5]
	v_cndmask_b32_e64 v76, v111, v110, s[4:5]
	v_cndmask_b32_e64 v78, v112, v113, s[4:5]
	v_cndmask_b32_e64 v136, v113, v112, s[4:5]
	v_cndmask_b32_e64 v138, v114, v115, s[4:5]
	v_cndmask_b32_e64 v140, v115, v114, s[4:5]
	v_add_f32_dpp v71, v72, v70 quad_perm:[1,0,3,2] row_mask:0xf bank_mask:0xf bound_ctrl:1
	v_add_f32_dpp v73, v76, v74 quad_perm:[1,0,3,2] row_mask:0xf bank_mask:0xf bound_ctrl:1
	v_add_f32_dpp v75, v136, v78 quad_perm:[1,0,3,2] row_mask:0xf bank_mask:0xf bound_ctrl:1
	v_add_f32_dpp v77, v140, v138 quad_perm:[1,0,3,2] row_mask:0xf bank_mask:0xf bound_ctrl:1
	s_nop 0
	v_cndmask_b32_e64 v70, v71, v73, s[6:7]
	v_cndmask_b32_e64 v72, v73, v71, s[6:7]
	v_cndmask_b32_e64 v74, v75, v77, s[6:7]
	v_cndmask_b32_e64 v76, v77, v75, s[6:7]
	s_nop 0
	v_add_f32_dpp v79, v72, v70 quad_perm:[2,3,0,1] row_mask:0xf bank_mask:0xf bound_ctrl:1
	v_add_f32_dpp v137, v76, v74 quad_perm:[2,3,0,1] row_mask:0xf bank_mask:0xf bound_ctrl:1
	s_nop 1
	v_add_f32_dpp v106, v79, v79 row_shl:4 row_mask:0xf bank_mask:0x5 bound_ctrl:1
	s_nop 1
	v_add_f32_dpp v106, v137, v137 row_shr:4 row_mask:0xf bank_mask:0xa bound_ctrl:1
	v_cndmask_b32_e64 v70, v116, v117, s[4:5]
	v_cndmask_b32_e64 v72, v117, v116, s[4:5]
	v_cndmask_b32_e64 v74, v118, v119, s[4:5]
	v_cndmask_b32_e64 v76, v119, v118, s[4:5]
	v_cndmask_b32_e64 v78, v120, v121, s[4:5]
	v_cndmask_b32_e64 v136, v121, v120, s[4:5]
	v_cndmask_b32_e64 v138, v122, v123, s[4:5]
	v_cndmask_b32_e64 v140, v123, v122, s[4:5]
	v_add_f32_dpp v71, v72, v70 quad_perm:[1,0,3,2] row_mask:0xf bank_mask:0xf bound_ctrl:1
	v_add_f32_dpp v73, v76, v74 quad_perm:[1,0,3,2] row_mask:0xf bank_mask:0xf bound_ctrl:1
	v_add_f32_dpp v75, v136, v78 quad_perm:[1,0,3,2] row_mask:0xf bank_mask:0xf bound_ctrl:1
	v_add_f32_dpp v77, v140, v138 quad_perm:[1,0,3,2] row_mask:0xf bank_mask:0xf bound_ctrl:1
	s_nop 0
	v_cndmask_b32_e64 v70, v71, v73, s[6:7]
	v_cndmask_b32_e64 v72, v73, v71, s[6:7]
	v_cndmask_b32_e64 v74, v75, v77, s[6:7]
	v_cndmask_b32_e64 v76, v77, v75, s[6:7]
	s_nop 0
	v_add_f32_dpp v79, v72, v70 quad_perm:[2,3,0,1] row_mask:0xf bank_mask:0xf bound_ctrl:1
	v_add_f32_dpp v137, v76, v74 quad_perm:[2,3,0,1] row_mask:0xf bank_mask:0xf bound_ctrl:1
	s_nop 1
	v_add_f32_dpp v107, v79, v79 row_shl:4 row_mask:0xf bank_mask:0x5 bound_ctrl:1
	s_nop 1
	v_add_f32_dpp v107, v137, v137 row_shr:4 row_mask:0xf bank_mask:0xa bound_ctrl:1
	ds_read_b128 v[88:91], v41 offset:6400
	ds_read_b128 v[96:99], v41 offset:10496
	ds_read2_b32 v[104:105], v43 offset0:64 offset1:96
	ds_read_b128 v[92:95], v41 offset:6416
	ds_read_b128 v[100:103], v41 offset:10512
	ds_read_b128 v[80:83], v41 offset:2304
	ds_read_b128 v[84:87], v41 offset:2320
	s_waitcnt lgkmcnt(7)
	v_pk_mul_f32 v[70:71], v[60:61], v[68:69] op_sel_hi:[1,0]
	v_pk_mul_f32 v[72:73], v[62:63], v[68:69] op_sel_hi:[1,0]
	v_pk_mul_f32 v[74:75], v[64:65], v[68:69] op_sel_hi:[1,0]
	v_pk_mul_f32 v[76:77], v[66:67], v[68:69] op_sel_hi:[1,0]
	v_pk_mul_f32 v[78:79], v[60:61], v[68:69] op_sel:[0,1] op_sel_hi:[1,1]
	v_pk_mul_f32 v[136:137], v[62:63], v[68:69] op_sel:[0,1] op_sel_hi:[1,1]
	v_pk_mul_f32 v[138:139], v[64:65], v[68:69] op_sel:[0,1] op_sel_hi:[1,1]
	v_pk_mul_f32 v[140:141], v[66:67], v[68:69] op_sel:[0,1] op_sel_hi:[1,1]
	v_pk_fma_f32 v[34:35], v[34:35], v[52:53], v[70:71]
	v_pk_fma_f32 v[32:33], v[32:33], v[54:55], v[72:73]
	v_pk_fma_f32 v[30:31], v[30:31], v[56:57], v[74:75]
	v_pk_fma_f32 v[28:29], v[28:29], v[58:59], v[76:77]
	v_pk_fma_f32 v[26:27], v[26:27], v[52:53], v[78:79]
	v_pk_fma_f32 v[24:25], v[24:25], v[54:55], v[136:137]
	v_pk_fma_f32 v[22:23], v[22:23], v[56:57], v[138:139]
	v_pk_fma_f32 v[6:7], v[6:7], v[58:59], v[140:141]
	v_pk_mul_f32 v[142:143], v[46:47], v[32:33]
	v_pk_mul_f32 v[144:145], v[46:47], v[24:25]
	v_pk_fma_f32 v[142:143], v[44:45], v[34:35], v[142:143]
	v_pk_fma_f32 v[144:145], v[44:45], v[26:27], v[144:145]
	v_pk_fma_f32 v[142:143], v[48:49], v[30:31], v[142:143]
	v_pk_fma_f32 v[144:145], v[48:49], v[22:23], v[144:145]
	v_pk_fma_f32 v[142:143], v[50:51], v[28:29], v[142:143]
	v_pk_fma_f32 v[144:145], v[50:51], v[6:7], v[144:145]
	v_add_f32_e32 v108, v142, v143
	v_add_f32_e32 v116, v144, v145
	ds_read_b128 v[52:55], v41 offset:6656
	ds_read_b128 v[60:63], v41 offset:10752
	ds_read2_b32 v[68:69], v43 offset0:128 offset1:160
	ds_read_b128 v[56:59], v41 offset:6672
	ds_read_b128 v[64:67], v41 offset:10768
	ds_read_b128 v[44:47], v41 offset:2560
	ds_read_b128 v[48:51], v41 offset:2576
	s_waitcnt lgkmcnt(7)
	v_pk_mul_f32 v[70:71], v[96:97], v[104:105] op_sel_hi:[1,0]
	v_pk_mul_f32 v[72:73], v[98:99], v[104:105] op_sel_hi:[1,0]
	v_pk_mul_f32 v[74:75], v[100:101], v[104:105] op_sel_hi:[1,0]
	v_pk_mul_f32 v[76:77], v[102:103], v[104:105] op_sel_hi:[1,0]
	v_pk_mul_f32 v[78:79], v[96:97], v[104:105] op_sel:[0,1] op_sel_hi:[1,1]
	v_pk_mul_f32 v[136:137], v[98:99], v[104:105] op_sel:[0,1] op_sel_hi:[1,1]
	v_pk_mul_f32 v[138:139], v[100:101], v[104:105] op_sel:[0,1] op_sel_hi:[1,1]
	v_pk_mul_f32 v[140:141], v[102:103], v[104:105] op_sel:[0,1] op_sel_hi:[1,1]
	v_pk_fma_f32 v[34:35], v[34:35], v[88:89], v[70:71]
	v_pk_fma_f32 v[32:33], v[32:33], v[90:91], v[72:73]
	v_pk_fma_f32 v[30:31], v[30:31], v[92:93], v[74:75]
	v_pk_fma_f32 v[28:29], v[28:29], v[94:95], v[76:77]
	v_pk_fma_f32 v[26:27], v[26:27], v[88:89], v[78:79]
	v_pk_fma_f32 v[24:25], v[24:25], v[90:91], v[136:137]
	v_pk_fma_f32 v[22:23], v[22:23], v[92:93], v[138:139]
	v_pk_fma_f32 v[6:7], v[6:7], v[94:95], v[140:141]
	v_pk_mul_f32 v[142:143], v[82:83], v[32:33]
	v_pk_mul_f32 v[144:145], v[82:83], v[24:25]
	v_pk_fma_f32 v[142:143], v[80:81], v[34:35], v[142:143]
	v_pk_fma_f32 v[144:145], v[80:81], v[26:27], v[144:145]
	v_pk_fma_f32 v[142:143], v[84:85], v[30:31], v[142:143]
	v_pk_fma_f32 v[144:145], v[84:85], v[22:23], v[144:145]
	v_pk_fma_f32 v[142:143], v[86:87], v[28:29], v[142:143]
	v_pk_fma_f32 v[144:145], v[86:87], v[6:7], v[144:145]
	v_add_f32_e32 v109, v142, v143
	v_add_f32_e32 v117, v144, v145
	ds_read_b128 v[88:91], v41 offset:6912
	ds_read_b128 v[96:99], v41 offset:11008
	ds_read2_b32 v[104:105], v43 offset0:192 offset1:224
	ds_read_b128 v[92:95], v41 offset:6928
	ds_read_b128 v[100:103], v41 offset:11024
	ds_read_b128 v[80:83], v41 offset:2816
	ds_read_b128 v[84:87], v41 offset:2832
	s_waitcnt lgkmcnt(7)
	v_pk_mul_f32 v[70:71], v[60:61], v[68:69] op_sel_hi:[1,0]
	v_pk_mul_f32 v[72:73], v[62:63], v[68:69] op_sel_hi:[1,0]
	v_pk_mul_f32 v[74:75], v[64:65], v[68:69] op_sel_hi:[1,0]
	v_pk_mul_f32 v[76:77], v[66:67], v[68:69] op_sel_hi:[1,0]
	v_pk_mul_f32 v[78:79], v[60:61], v[68:69] op_sel:[0,1] op_sel_hi:[1,1]
	v_pk_mul_f32 v[136:137], v[62:63], v[68:69] op_sel:[0,1] op_sel_hi:[1,1]
	v_pk_mul_f32 v[138:139], v[64:65], v[68:69] op_sel:[0,1] op_sel_hi:[1,1]
	v_pk_mul_f32 v[140:141], v[66:67], v[68:69] op_sel:[0,1] op_sel_hi:[1,1]
	v_pk_fma_f32 v[34:35], v[34:35], v[52:53], v[70:71]
	v_pk_fma_f32 v[32:33], v[32:33], v[54:55], v[72:73]
	v_pk_fma_f32 v[30:31], v[30:31], v[56:57], v[74:75]
	v_pk_fma_f32 v[28:29], v[28:29], v[58:59], v[76:77]
	v_pk_fma_f32 v[26:27], v[26:27], v[52:53], v[78:79]
	v_pk_fma_f32 v[24:25], v[24:25], v[54:55], v[136:137]
	v_pk_fma_f32 v[22:23], v[22:23], v[56:57], v[138:139]
	v_pk_fma_f32 v[6:7], v[6:7], v[58:59], v[140:141]
	v_pk_mul_f32 v[142:143], v[46:47], v[32:33]
	v_pk_mul_f32 v[144:145], v[46:47], v[24:25]
	v_pk_fma_f32 v[142:143], v[44:45], v[34:35], v[142:143]
	v_pk_fma_f32 v[144:145], v[44:45], v[26:27], v[144:145]
	v_pk_fma_f32 v[142:143], v[48:49], v[30:31], v[142:143]
	v_pk_fma_f32 v[144:145], v[48:49], v[22:23], v[144:145]
	v_pk_fma_f32 v[142:143], v[50:51], v[28:29], v[142:143]
	v_pk_fma_f32 v[144:145], v[50:51], v[6:7], v[144:145]
	v_add_f32_e32 v110, v142, v143
	v_add_f32_e32 v118, v144, v145
	v_add_u32_e32 v43, 0x400, v43
	ds_read_b128 v[52:55], v41 offset:7168
	ds_read_b128 v[60:63], v41 offset:11264
	ds_read2_b32 v[68:69], v43 offset0:0 offset1:32
	ds_read_b128 v[56:59], v41 offset:7184
	ds_read_b128 v[64:67], v41 offset:11280
	ds_read_b128 v[44:47], v41 offset:3072
	ds_read_b128 v[48:51], v41 offset:3088
	s_waitcnt lgkmcnt(7)
	v_pk_mul_f32 v[70:71], v[96:97], v[104:105] op_sel_hi:[1,0]
	v_pk_mul_f32 v[72:73], v[98:99], v[104:105] op_sel_hi:[1,0]
	v_pk_mul_f32 v[74:75], v[100:101], v[104:105] op_sel_hi:[1,0]
	v_pk_mul_f32 v[76:77], v[102:103], v[104:105] op_sel_hi:[1,0]
	v_pk_mul_f32 v[78:79], v[96:97], v[104:105] op_sel:[0,1] op_sel_hi:[1,1]
	v_pk_mul_f32 v[136:137], v[98:99], v[104:105] op_sel:[0,1] op_sel_hi:[1,1]
	v_pk_mul_f32 v[138:139], v[100:101], v[104:105] op_sel:[0,1] op_sel_hi:[1,1]
	v_pk_mul_f32 v[140:141], v[102:103], v[104:105] op_sel:[0,1] op_sel_hi:[1,1]
	v_pk_fma_f32 v[34:35], v[34:35], v[88:89], v[70:71]
	v_pk_fma_f32 v[32:33], v[32:33], v[90:91], v[72:73]
	v_pk_fma_f32 v[30:31], v[30:31], v[92:93], v[74:75]
	v_pk_fma_f32 v[28:29], v[28:29], v[94:95], v[76:77]
	v_pk_fma_f32 v[26:27], v[26:27], v[88:89], v[78:79]
	v_pk_fma_f32 v[24:25], v[24:25], v[90:91], v[136:137]
	v_pk_fma_f32 v[22:23], v[22:23], v[92:93], v[138:139]
	v_pk_fma_f32 v[6:7], v[6:7], v[94:95], v[140:141]
	v_pk_mul_f32 v[142:143], v[82:83], v[32:33]
	v_pk_mul_f32 v[144:145], v[82:83], v[24:25]
	v_pk_fma_f32 v[142:143], v[80:81], v[34:35], v[142:143]
	v_pk_fma_f32 v[144:145], v[80:81], v[26:27], v[144:145]
	v_pk_fma_f32 v[142:143], v[84:85], v[30:31], v[142:143]
	v_pk_fma_f32 v[144:145], v[84:85], v[22:23], v[144:145]
	v_pk_fma_f32 v[142:143], v[86:87], v[28:29], v[142:143]
	v_pk_fma_f32 v[144:145], v[86:87], v[6:7], v[144:145]
	v_add_f32_e32 v111, v142, v143
	v_add_f32_e32 v119, v144, v145
	ds_read_b128 v[88:91], v41 offset:7424
	ds_read_b128 v[96:99], v41 offset:11520
	ds_read2_b32 v[104:105], v43 offset0:64 offset1:96
	ds_read_b128 v[92:95], v41 offset:7440
	ds_read_b128 v[100:103], v41 offset:11536
	ds_read_b128 v[80:83], v41 offset:3328
	ds_read_b128 v[84:87], v41 offset:3344
	s_waitcnt lgkmcnt(7)
	v_pk_mul_f32 v[70:71], v[60:61], v[68:69] op_sel_hi:[1,0]
	v_pk_mul_f32 v[72:73], v[62:63], v[68:69] op_sel_hi:[1,0]
	v_pk_mul_f32 v[74:75], v[64:65], v[68:69] op_sel_hi:[1,0]
	v_pk_mul_f32 v[76:77], v[66:67], v[68:69] op_sel_hi:[1,0]
	v_pk_mul_f32 v[78:79], v[60:61], v[68:69] op_sel:[0,1] op_sel_hi:[1,1]
	v_pk_mul_f32 v[136:137], v[62:63], v[68:69] op_sel:[0,1] op_sel_hi:[1,1]
	v_pk_mul_f32 v[138:139], v[64:65], v[68:69] op_sel:[0,1] op_sel_hi:[1,1]
	v_pk_mul_f32 v[140:141], v[66:67], v[68:69] op_sel:[0,1] op_sel_hi:[1,1]
	v_pk_fma_f32 v[34:35], v[34:35], v[52:53], v[70:71]
	v_pk_fma_f32 v[32:33], v[32:33], v[54:55], v[72:73]
	v_pk_fma_f32 v[30:31], v[30:31], v[56:57], v[74:75]
	v_pk_fma_f32 v[28:29], v[28:29], v[58:59], v[76:77]
	v_pk_fma_f32 v[26:27], v[26:27], v[52:53], v[78:79]
	v_pk_fma_f32 v[24:25], v[24:25], v[54:55], v[136:137]
	v_pk_fma_f32 v[22:23], v[22:23], v[56:57], v[138:139]
	v_pk_fma_f32 v[6:7], v[6:7], v[58:59], v[140:141]
	v_pk_mul_f32 v[142:143], v[46:47], v[32:33]
	v_pk_mul_f32 v[144:145], v[46:47], v[24:25]
	v_pk_fma_f32 v[142:143], v[44:45], v[34:35], v[142:143]
	v_pk_fma_f32 v[144:145], v[44:45], v[26:27], v[144:145]
	v_pk_fma_f32 v[142:143], v[48:49], v[30:31], v[142:143]
	v_pk_fma_f32 v[144:145], v[48:49], v[22:23], v[144:145]
	v_pk_fma_f32 v[142:143], v[50:51], v[28:29], v[142:143]
	v_pk_fma_f32 v[144:145], v[50:51], v[6:7], v[144:145]
	v_add_f32_e32 v112, v142, v143
	v_add_f32_e32 v120, v144, v145
	ds_read_b128 v[52:55], v41 offset:7680
	ds_read_b128 v[60:63], v41 offset:11776
	ds_read2_b32 v[68:69], v43 offset0:128 offset1:160
	ds_read_b128 v[56:59], v41 offset:7696
	ds_read_b128 v[64:67], v41 offset:11792
	ds_read_b128 v[44:47], v41 offset:3584
	ds_read_b128 v[48:51], v41 offset:3600
	s_waitcnt lgkmcnt(7)
	v_pk_mul_f32 v[70:71], v[96:97], v[104:105] op_sel_hi:[1,0]
	v_pk_mul_f32 v[72:73], v[98:99], v[104:105] op_sel_hi:[1,0]
	v_pk_mul_f32 v[74:75], v[100:101], v[104:105] op_sel_hi:[1,0]
	v_pk_mul_f32 v[76:77], v[102:103], v[104:105] op_sel_hi:[1,0]
	v_pk_mul_f32 v[78:79], v[96:97], v[104:105] op_sel:[0,1] op_sel_hi:[1,1]
	v_pk_mul_f32 v[136:137], v[98:99], v[104:105] op_sel:[0,1] op_sel_hi:[1,1]
	v_pk_mul_f32 v[138:139], v[100:101], v[104:105] op_sel:[0,1] op_sel_hi:[1,1]
	v_pk_mul_f32 v[140:141], v[102:103], v[104:105] op_sel:[0,1] op_sel_hi:[1,1]
	v_pk_fma_f32 v[34:35], v[34:35], v[88:89], v[70:71]
	v_pk_fma_f32 v[32:33], v[32:33], v[90:91], v[72:73]
	v_pk_fma_f32 v[30:31], v[30:31], v[92:93], v[74:75]
	v_pk_fma_f32 v[28:29], v[28:29], v[94:95], v[76:77]
	v_pk_fma_f32 v[26:27], v[26:27], v[88:89], v[78:79]
	v_pk_fma_f32 v[24:25], v[24:25], v[90:91], v[136:137]
	v_pk_fma_f32 v[22:23], v[22:23], v[92:93], v[138:139]
	v_pk_fma_f32 v[6:7], v[6:7], v[94:95], v[140:141]
	v_pk_mul_f32 v[142:143], v[82:83], v[32:33]
	v_pk_mul_f32 v[144:145], v[82:83], v[24:25]
	v_pk_fma_f32 v[142:143], v[80:81], v[34:35], v[142:143]
	v_pk_fma_f32 v[144:145], v[80:81], v[26:27], v[144:145]
	v_pk_fma_f32 v[142:143], v[84:85], v[30:31], v[142:143]
	v_pk_fma_f32 v[144:145], v[84:85], v[22:23], v[144:145]
	v_pk_fma_f32 v[142:143], v[86:87], v[28:29], v[142:143]
	v_pk_fma_f32 v[144:145], v[86:87], v[6:7], v[144:145]
	v_add_f32_e32 v113, v142, v143
	v_add_f32_e32 v121, v144, v145
	ds_read_b128 v[88:91], v41 offset:7936
	ds_read_b128 v[96:99], v41 offset:12032
	ds_read2_b32 v[104:105], v43 offset0:192 offset1:224
	ds_read_b128 v[92:95], v41 offset:7952
	ds_read_b128 v[100:103], v41 offset:12048
	ds_read_b128 v[80:83], v41 offset:3840
	ds_read_b128 v[84:87], v41 offset:3856
	s_waitcnt lgkmcnt(7)
	v_pk_mul_f32 v[70:71], v[60:61], v[68:69] op_sel_hi:[1,0]
	v_pk_mul_f32 v[72:73], v[62:63], v[68:69] op_sel_hi:[1,0]
	v_pk_mul_f32 v[74:75], v[64:65], v[68:69] op_sel_hi:[1,0]
	v_pk_mul_f32 v[76:77], v[66:67], v[68:69] op_sel_hi:[1,0]
	v_pk_mul_f32 v[78:79], v[60:61], v[68:69] op_sel:[0,1] op_sel_hi:[1,1]
	v_pk_mul_f32 v[136:137], v[62:63], v[68:69] op_sel:[0,1] op_sel_hi:[1,1]
	v_pk_mul_f32 v[138:139], v[64:65], v[68:69] op_sel:[0,1] op_sel_hi:[1,1]
	v_pk_mul_f32 v[140:141], v[66:67], v[68:69] op_sel:[0,1] op_sel_hi:[1,1]
	v_pk_fma_f32 v[34:35], v[34:35], v[52:53], v[70:71]
	v_pk_fma_f32 v[32:33], v[32:33], v[54:55], v[72:73]
	v_pk_fma_f32 v[30:31], v[30:31], v[56:57], v[74:75]
	v_pk_fma_f32 v[28:29], v[28:29], v[58:59], v[76:77]
	v_pk_fma_f32 v[26:27], v[26:27], v[52:53], v[78:79]
	v_pk_fma_f32 v[24:25], v[24:25], v[54:55], v[136:137]
	v_pk_fma_f32 v[22:23], v[22:23], v[56:57], v[138:139]
	v_pk_fma_f32 v[6:7], v[6:7], v[58:59], v[140:141]
	v_pk_mul_f32 v[142:143], v[46:47], v[32:33]
	v_pk_mul_f32 v[144:145], v[46:47], v[24:25]
	v_pk_fma_f32 v[142:143], v[44:45], v[34:35], v[142:143]
	v_pk_fma_f32 v[144:145], v[44:45], v[26:27], v[144:145]
	v_pk_fma_f32 v[142:143], v[48:49], v[30:31], v[142:143]
	v_pk_fma_f32 v[144:145], v[48:49], v[22:23], v[144:145]
	v_pk_fma_f32 v[142:143], v[50:51], v[28:29], v[142:143]
	v_pk_fma_f32 v[144:145], v[50:51], v[6:7], v[144:145]
	v_add_f32_e32 v114, v142, v143
	v_add_f32_e32 v122, v144, v145
	s_waitcnt lgkmcnt(0)
	v_pk_mul_f32 v[70:71], v[96:97], v[104:105] op_sel_hi:[1,0]
	v_pk_mul_f32 v[72:73], v[98:99], v[104:105] op_sel_hi:[1,0]
	v_pk_mul_f32 v[74:75], v[100:101], v[104:105] op_sel_hi:[1,0]
	v_pk_mul_f32 v[76:77], v[102:103], v[104:105] op_sel_hi:[1,0]
	v_pk_mul_f32 v[78:79], v[96:97], v[104:105] op_sel:[0,1] op_sel_hi:[1,1]
	v_pk_mul_f32 v[136:137], v[98:99], v[104:105] op_sel:[0,1] op_sel_hi:[1,1]
	v_pk_mul_f32 v[138:139], v[100:101], v[104:105] op_sel:[0,1] op_sel_hi:[1,1]
	v_pk_mul_f32 v[140:141], v[102:103], v[104:105] op_sel:[0,1] op_sel_hi:[1,1]
	v_pk_fma_f32 v[34:35], v[34:35], v[88:89], v[70:71]
	v_pk_fma_f32 v[32:33], v[32:33], v[90:91], v[72:73]
	v_pk_fma_f32 v[30:31], v[30:31], v[92:93], v[74:75]
	v_pk_fma_f32 v[28:29], v[28:29], v[94:95], v[76:77]
	v_pk_fma_f32 v[26:27], v[26:27], v[88:89], v[78:79]
	v_pk_fma_f32 v[24:25], v[24:25], v[90:91], v[136:137]
	v_pk_fma_f32 v[22:23], v[22:23], v[92:93], v[138:139]
	v_pk_fma_f32 v[6:7], v[6:7], v[94:95], v[140:141]
	v_pk_mul_f32 v[142:143], v[82:83], v[32:33]
	v_pk_mul_f32 v[144:145], v[82:83], v[24:25]
	v_pk_fma_f32 v[142:143], v[80:81], v[34:35], v[142:143]
	v_pk_fma_f32 v[144:145], v[80:81], v[26:27], v[144:145]
	v_pk_fma_f32 v[142:143], v[84:85], v[30:31], v[142:143]
	v_pk_fma_f32 v[144:145], v[84:85], v[22:23], v[144:145]
	v_pk_fma_f32 v[142:143], v[86:87], v[28:29], v[142:143]
	v_pk_fma_f32 v[144:145], v[86:87], v[6:7], v[144:145]
	v_add_f32_e32 v115, v142, v143
	v_add_f32_e32 v123, v144, v145
	v_cndmask_b32_e64 v70, v108, v109, s[4:5]
	v_cndmask_b32_e64 v72, v109, v108, s[4:5]
	v_cndmask_b32_e64 v74, v110, v111, s[4:5]
	v_cndmask_b32_e64 v76, v111, v110, s[4:5]
	v_cndmask_b32_e64 v78, v112, v113, s[4:5]
	v_cndmask_b32_e64 v136, v113, v112, s[4:5]
	v_cndmask_b32_e64 v138, v114, v115, s[4:5]
	v_cndmask_b32_e64 v140, v115, v114, s[4:5]
	v_add_f32_dpp v71, v72, v70 quad_perm:[1,0,3,2] row_mask:0xf bank_mask:0xf bound_ctrl:1
	v_add_f32_dpp v73, v76, v74 quad_perm:[1,0,3,2] row_mask:0xf bank_mask:0xf bound_ctrl:1
	v_add_f32_dpp v75, v136, v78 quad_perm:[1,0,3,2] row_mask:0xf bank_mask:0xf bound_ctrl:1
	v_add_f32_dpp v77, v140, v138 quad_perm:[1,0,3,2] row_mask:0xf bank_mask:0xf bound_ctrl:1
	s_nop 0
	v_cndmask_b32_e64 v70, v71, v73, s[6:7]
	v_cndmask_b32_e64 v72, v73, v71, s[6:7]
	v_cndmask_b32_e64 v74, v75, v77, s[6:7]
	v_cndmask_b32_e64 v76, v77, v75, s[6:7]
	s_nop 0
	v_add_f32_dpp v79, v72, v70 quad_perm:[2,3,0,1] row_mask:0xf bank_mask:0xf bound_ctrl:1
	v_add_f32_dpp v137, v76, v74 quad_perm:[2,3,0,1] row_mask:0xf bank_mask:0xf bound_ctrl:1
	s_nop 1
	v_add_f32_dpp v126, v79, v79 row_shl:4 row_mask:0xf bank_mask:0x5 bound_ctrl:1
	s_nop 1
	v_add_f32_dpp v126, v137, v137 row_shr:4 row_mask:0xf bank_mask:0xa bound_ctrl:1
	v_cndmask_b32_e64 v70, v116, v117, s[4:5]
	v_cndmask_b32_e64 v72, v117, v116, s[4:5]
	v_cndmask_b32_e64 v74, v118, v119, s[4:5]
	v_cndmask_b32_e64 v76, v119, v118, s[4:5]
	v_cndmask_b32_e64 v78, v120, v121, s[4:5]
	v_cndmask_b32_e64 v136, v121, v120, s[4:5]
	v_cndmask_b32_e64 v138, v122, v123, s[4:5]
	v_cndmask_b32_e64 v140, v123, v122, s[4:5]
	v_add_f32_dpp v71, v72, v70 quad_perm:[1,0,3,2] row_mask:0xf bank_mask:0xf bound_ctrl:1
	v_add_f32_dpp v73, v76, v74 quad_perm:[1,0,3,2] row_mask:0xf bank_mask:0xf bound_ctrl:1
	v_add_f32_dpp v75, v136, v78 quad_perm:[1,0,3,2] row_mask:0xf bank_mask:0xf bound_ctrl:1
	v_add_f32_dpp v77, v140, v138 quad_perm:[1,0,3,2] row_mask:0xf bank_mask:0xf bound_ctrl:1
	s_nop 0
	v_cndmask_b32_e64 v70, v71, v73, s[6:7]
	v_cndmask_b32_e64 v72, v73, v71, s[6:7]
	v_cndmask_b32_e64 v74, v75, v77, s[6:7]
	v_cndmask_b32_e64 v76, v77, v75, s[6:7]
	s_nop 0
	v_add_f32_dpp v79, v72, v70 quad_perm:[2,3,0,1] row_mask:0xf bank_mask:0xf bound_ctrl:1
	v_add_f32_dpp v137, v76, v74 quad_perm:[2,3,0,1] row_mask:0xf bank_mask:0xf bound_ctrl:1
	s_nop 1
	v_add_f32_dpp v127, v79, v79 row_shl:4 row_mask:0xf bank_mask:0x5 bound_ctrl:1
	s_nop 1
	v_add_f32_dpp v127, v137, v137 row_shr:4 row_mask:0xf bank_mask:0xa bound_ctrl:1
	v_add_u32_e32 v44, 8, v37
	v_add_u32_e32 v42, s25, v11
	v_cndmask_b32_e64 v44, v44, v42, s[36:37]
	v_add_u32_e32 v42, 8, v42
	v_add_lshl_u32 v128, v44, s24, 10
	v_cndmask_b32_e64 v42, v37, v42, s[36:37]
	v_lshl_add_u64 v[44:45], v[4:5], 0, v[128:129]
	v_add_lshl_u32 v128, v42, s24, 10
	v_lshl_add_u64 v[42:43], v[4:5], 0, v[128:129]
	global_store_dword v[44:45], v106, off
	global_store_dword v[44:45], v107, off offset:128
	global_store_dword v[42:43], v126, off
	global_store_dword v[42:43], v127, off offset:128
	s_andn2_b64 vcc, exec, s[20:21]
	s_cbranch_vccnz .LBB0_414
	s_waitcnt vmcnt(5)
	v_lshlrev_b32_e32 v41, 16, v16
	v_mul_f32_e32 v41, 0xbfb8aa3b, v41
	v_exp_f32_e32 v41, v41
	v_lshlrev_b32_e32 v42, 16, v14
	v_and_b32_e32 v43, 0xffff0000, v14
	v_mul_f32_e32 v50, 0xbfb8aa3b, v42
	v_add_f32_e32 v41, 1.0, v41
	v_rcp_f32_e32 v46, v41
	v_and_b32_e32 v41, 0xffff0000, v16
	v_mul_f32_e32 v41, 0xbfb8aa3b, v41
	v_exp_f32_e32 v41, v41
	v_mul_f32_e32 v51, 0xbfb8aa3b, v43
	v_exp_f32_e32 v50, v50
	v_exp_f32_e32 v51, v51
	v_add_f32_e32 v41, 1.0, v41
	v_rcp_f32_e32 v47, v41
	v_lshlrev_b32_e32 v41, 16, v17
	v_mul_f32_e32 v41, 0xbfb8aa3b, v41
	v_exp_f32_e32 v41, v41
	v_add_f32_e32 v50, 1.0, v50
	v_add_f32_e32 v51, 1.0, v51
	v_rcp_f32_e32 v50, v50
	v_rcp_f32_e32 v51, v51
	v_lshlrev_b32_e32 v44, 16, v15
	v_and_b32_e32 v45, 0xffff0000, v15
	v_add_f32_e32 v41, 1.0, v41
	v_rcp_f32_e32 v48, v41
	v_and_b32_e32 v41, 0xffff0000, v17
	v_pk_mul_f32 v[42:43], v[50:51], v[42:43]
	v_mul_f32_e32 v50, 0xbfb8aa3b, v44
	v_mul_f32_e32 v51, 0xbfb8aa3b, v45
	v_mul_f32_e32 v41, 0xbfb8aa3b, v41
	v_exp_f32_e32 v50, v50
	v_exp_f32_e32 v51, v51
	v_exp_f32_e32 v41, v41
	s_bitcmp1_b32 s19, 0
	v_add_f32_e32 v50, 1.0, v50
	v_add_f32_e32 v51, 1.0, v51
	v_add_f32_e32 v41, 1.0, v41
	v_rcp_f32_e32 v50, v50
	v_rcp_f32_e32 v51, v51
	v_rcp_f32_e32 v49, v41
	s_cselect_b32 s20, 0x6000, 0
	s_add_i32 s20, s78, s20
	v_lshl_add_u32 v41, v36, 4, s20
	v_pk_mul_f32 v[44:45], v[50:51], v[44:45]
	ds_write_b128 v41, v[42:45]
	v_pk_fma_f32 v[42:43], v[12:13], v[46:47], v[0:1]
	v_pk_fma_f32 v[44:45], v[18:19], v[48:49], v[2:3]
	ds_write_b128 v41, v[42:45] offset:4096
	v_pk_add_f32 v[42:43], v[46:47], 1.0 op_sel_hi:[1,0] neg_lo:[1,0] neg_hi:[1,0]
	v_pk_add_f32 v[44:45], v[48:49], 1.0 op_sel_hi:[1,0] neg_lo:[1,0] neg_hi:[1,0]
	v_pk_mul_f32 v[42:43], v[12:13], v[42:43]
	v_pk_mul_f32 v[44:45], v[18:19], v[44:45]
	ds_write_b128 v41, v[42:45] offset:8192
	v_lshlrev_b32_e32 v41, 2, v10
	s_waitcnt vmcnt(4)
	v_lshlrev_b32_e32 v42, 16, v20
	v_and_b32_e32 v43, 0xffff0000, v20
	v_lshlrev_b32_e32 v44, 16, v21
	v_and_b32_e32 v45, 0xffff0000, v21
	v_add3_u32 v41, s20, v40, v41
	ds_write_b128 v41, v[42:45] offset:20480
	s_branch .LBB0_414

.LBB0_425:
	s_add_i32 s25, s26, 1
	s_bitcmp1_b32 s26, 0
	s_cselect_b32 s26, 0x6000, 0
	s_add_i32 s26, s78, s26
	v_add_u32_e32 v51, s26, v44
	v_lshl_add_u32 v53, v16, 2, s26
	v_add_u32_e32 v53, 0x5000, v53
	ds_read_b128 v[54:57], v51 offset:12288
	ds_read_b128 v[58:61], v51 offset:12304
	ds_read_b128 v[70:73], v51 offset:8192
	ds_read_b128 v[74:77], v51 offset:8208
	ds_read2_b32 v[86:87], v53 offset0:0 offset1:32
	ds_read_b128 v[62:65], v51 offset:4096
	ds_read_b128 v[66:69], v51 offset:4112
	ds_read_b128 v[78:81], v51 offset:16384
	ds_read_b128 v[82:85], v51 offset:16400
	ds_read_b128 v[88:91], v51 offset:0
	ds_read_b128 v[92:95], v51 offset:16
	v_and_b32_e32 v52, 1, v46
	v_and_b32_e32 v128, 2, v46
	v_cmp_ne_u32_e64 s[4:5], 0, v52
	v_cmp_ne_u32_e64 s[6:7], 0, v128
	s_waitcnt lgkmcnt(9)
	v_pk_mul_f32 v[134:135], v[14:15], v[56:57]
	v_pk_mul_f32 v[136:137], v[6:7], v[56:57]
	v_pk_fma_f32 v[134:135], v[12:13], v[54:55], v[134:135]
	v_pk_fma_f32 v[136:137], v[4:5], v[54:55], v[136:137]
	v_pk_fma_f32 v[134:135], v[8:9], v[58:59], v[134:135]
	v_pk_fma_f32 v[136:137], v[0:1], v[58:59], v[136:137]
	v_pk_fma_f32 v[134:135], v[10:11], v[60:61], v[134:135]
	v_pk_fma_f32 v[136:137], v[2:3], v[60:61], v[136:137]
	v_add_f32_e32 v134, v134, v135
	v_add_f32_e32 v136, v136, v137
	ds_read_b128 v[54:57], v51 offset:12544
	ds_read_b128 v[58:61], v51 offset:12560
	s_waitcnt lgkmcnt(6)
	v_pk_mul_f32 v[112:113], v[70:71], v[86:87] op_sel_hi:[1,0]
	v_pk_mul_f32 v[120:121], v[70:71], v[86:87] op_sel:[0,1] op_sel_hi:[1,1]
	v_add_f32_dpp v134, v134, v134 quad_perm:[1,0,3,2] row_mask:0xf bank_mask:0xf bound_ctrl:1
	v_add_f32_dpp v136, v136, v136 quad_perm:[1,0,3,2] row_mask:0xf bank_mask:0xf bound_ctrl:1
	v_pk_mul_f32 v[114:115], v[72:73], v[86:87] op_sel_hi:[1,0]
	v_add_f32_dpp v134, v134, v134 quad_perm:[2,3,0,1] row_mask:0xf bank_mask:0xf bound_ctrl:1
	v_add_f32_dpp v136, v136, v136 quad_perm:[2,3,0,1] row_mask:0xf bank_mask:0xf bound_ctrl:1
	v_pk_mul_f32 v[122:123], v[72:73], v[86:87] op_sel:[0,1] op_sel_hi:[1,1]
	v_add_f32_dpp v134, v134, v134 row_half_mirror row_mask:0xf bank_mask:0xf bound_ctrl:1
	v_add_f32_dpp v136, v136, v136 row_half_mirror row_mask:0xf bank_mask:0xf bound_ctrl:1
	v_pk_mul_f32 v[116:117], v[74:75], v[86:87] op_sel_hi:[1,0]
	v_pk_mul_f32 v[124:125], v[74:75], v[86:87] op_sel:[0,1] op_sel_hi:[1,1]
	v_pk_mul_f32 v[118:119], v[76:77], v[86:87] op_sel_hi:[1,0]
	v_pk_mul_f32 v[126:127], v[76:77], v[86:87] op_sel:[0,1] op_sel_hi:[1,1]
	v_pk_fma_f32 v[112:113], v[12:13], v[62:63], v[112:113]
	v_pk_fma_f32 v[120:121], v[4:5], v[62:63], v[120:121]
	v_pk_fma_f32 v[114:115], v[14:15], v[64:65], v[114:115]
	v_pk_fma_f32 v[122:123], v[6:7], v[64:65], v[122:123]
	v_pk_fma_f32 v[116:117], v[8:9], v[66:67], v[116:117]
	v_pk_fma_f32 v[124:125], v[0:1], v[66:67], v[124:125]
	v_pk_fma_f32 v[118:119], v[10:11], v[68:69], v[118:119]
	v_pk_fma_f32 v[126:127], v[2:3], v[68:69], v[126:127]
	ds_read_b128 v[70:73], v51 offset:8448
	ds_read_b128 v[74:77], v51 offset:8464
	ds_read2_b32 v[86:87], v53 offset0:64 offset1:96
	ds_read_b128 v[62:65], v51 offset:4352
	ds_read_b128 v[66:69], v51 offset:4368
	s_waitcnt lgkmcnt(9)
	v_pk_fma_f32 v[12:13], v[78:79], v[134:135], v[112:113] op_sel_hi:[1,0,1] neg_lo:[0,1,0] neg_hi:[0,1,0]
	v_pk_fma_f32 v[4:5], v[78:79], v[136:137], v[120:121] op_sel_hi:[1,0,1] neg_lo:[0,1,0] neg_hi:[0,1,0]
	v_pk_fma_f32 v[14:15], v[80:81], v[134:135], v[114:115] op_sel_hi:[1,0,1] neg_lo:[0,1,0] neg_hi:[0,1,0]
	v_pk_fma_f32 v[6:7], v[80:81], v[136:137], v[122:123] op_sel_hi:[1,0,1] neg_lo:[0,1,0] neg_hi:[0,1,0]
	v_pk_fma_f32 v[8:9], v[82:83], v[134:135], v[116:117] op_sel_hi:[1,0,1] neg_lo:[0,1,0] neg_hi:[0,1,0]
	v_pk_fma_f32 v[0:1], v[82:83], v[136:137], v[124:125] op_sel_hi:[1,0,1] neg_lo:[0,1,0] neg_hi:[0,1,0]
	v_pk_fma_f32 v[10:11], v[84:85], v[134:135], v[118:119] op_sel_hi:[1,0,1] neg_lo:[0,1,0] neg_hi:[0,1,0]
	v_pk_fma_f32 v[2:3], v[84:85], v[136:137], v[126:127] op_sel_hi:[1,0,1] neg_lo:[0,1,0] neg_hi:[0,1,0]
	ds_read_b128 v[78:81], v51 offset:16640
	ds_read_b128 v[82:85], v51 offset:16656
	ds_read_b128 v[96:99], v51 offset:256
	ds_read_b128 v[100:103], v51 offset:272
	s_waitcnt lgkmcnt(9)
	v_pk_mul_f32 v[134:135], v[14:15], v[56:57]
	v_pk_mul_f32 v[136:137], v[6:7], v[56:57]
	v_pk_fma_f32 v[134:135], v[12:13], v[54:55], v[134:135]
	v_pk_fma_f32 v[136:137], v[4:5], v[54:55], v[136:137]
	v_pk_fma_f32 v[134:135], v[8:9], v[58:59], v[134:135]
	v_pk_fma_f32 v[136:137], v[0:1], v[58:59], v[136:137]
	v_pk_fma_f32 v[134:135], v[10:11], v[60:61], v[134:135]
	v_pk_fma_f32 v[136:137], v[2:3], v[60:61], v[136:137]
	v_add_f32_e32 v134, v134, v135
	v_add_f32_e32 v136, v136, v137
	ds_read_b128 v[54:57], v51 offset:12800
	ds_read_b128 v[58:61], v51 offset:12816
	s_waitcnt lgkmcnt(6)
	v_pk_mul_f32 v[112:113], v[70:71], v[86:87] op_sel_hi:[1,0]
	v_pk_mul_f32 v[120:121], v[70:71], v[86:87] op_sel:[0,1] op_sel_hi:[1,1]
	v_add_f32_dpp v134, v134, v134 quad_perm:[1,0,3,2] row_mask:0xf bank_mask:0xf bound_ctrl:1
	v_add_f32_dpp v136, v136, v136 quad_perm:[1,0,3,2] row_mask:0xf bank_mask:0xf bound_ctrl:1
	v_pk_mul_f32 v[114:115], v[72:73], v[86:87] op_sel_hi:[1,0]
	v_add_f32_dpp v134, v134, v134 quad_perm:[2,3,0,1] row_mask:0xf bank_mask:0xf bound_ctrl:1
	v_add_f32_dpp v136, v136, v136 quad_perm:[2,3,0,1] row_mask:0xf bank_mask:0xf bound_ctrl:1
	v_pk_mul_f32 v[122:123], v[72:73], v[86:87] op_sel:[0,1] op_sel_hi:[1,1]
	v_add_f32_dpp v134, v134, v134 row_half_mirror row_mask:0xf bank_mask:0xf bound_ctrl:1
	v_add_f32_dpp v136, v136, v136 row_half_mirror row_mask:0xf bank_mask:0xf bound_ctrl:1
	v_pk_mul_f32 v[116:117], v[74:75], v[86:87] op_sel_hi:[1,0]
	v_pk_mul_f32 v[124:125], v[74:75], v[86:87] op_sel:[0,1] op_sel_hi:[1,1]
	v_pk_mul_f32 v[118:119], v[76:77], v[86:87] op_sel_hi:[1,0]
	v_pk_mul_f32 v[126:127], v[76:77], v[86:87] op_sel:[0,1] op_sel_hi:[1,1]
	v_pk_fma_f32 v[112:113], v[12:13], v[62:63], v[112:113]
	v_pk_fma_f32 v[120:121], v[4:5], v[62:63], v[120:121]
	v_pk_fma_f32 v[114:115], v[14:15], v[64:65], v[114:115]
	v_pk_fma_f32 v[122:123], v[6:7], v[64:65], v[122:123]
	v_pk_fma_f32 v[116:117], v[8:9], v[66:67], v[116:117]
	v_pk_fma_f32 v[124:125], v[0:1], v[66:67], v[124:125]
	v_pk_fma_f32 v[118:119], v[10:11], v[68:69], v[118:119]
	v_pk_fma_f32 v[126:127], v[2:3], v[68:69], v[126:127]
	ds_read_b128 v[70:73], v51 offset:8704
	ds_read_b128 v[74:77], v51 offset:8720
	ds_read2_b32 v[86:87], v53 offset0:128 offset1:160
	ds_read_b128 v[62:65], v51 offset:4608
	ds_read_b128 v[66:69], v51 offset:4624
	v_mul_f32_e32 v138, v90, v14
	v_mul_f32_e32 v146, v90, v6
	v_fmac_f32_e32 v138, v91, v15
	v_fmac_f32_e32 v146, v91, v7
	v_fmac_f32_e32 v138, v88, v12
	v_fmac_f32_e32 v146, v88, v4
	v_fmac_f32_e32 v138, v89, v13
	v_fmac_f32_e32 v146, v89, v5
	v_fmac_f32_e32 v138, v92, v8
	v_fmac_f32_e32 v146, v92, v0
	v_fmac_f32_e32 v138, v93, v9
	v_fmac_f32_e32 v146, v93, v1
	v_fmac_f32_e32 v138, v94, v10
	v_fmac_f32_e32 v146, v94, v2
	v_fmac_f32_e32 v138, v95, v11
	v_fmac_f32_e32 v146, v95, v3
	s_waitcnt lgkmcnt(9)
	v_pk_fma_f32 v[12:13], v[78:79], v[134:135], v[112:113] op_sel_hi:[1,0,1] neg_lo:[0,1,0] neg_hi:[0,1,0]
	v_pk_fma_f32 v[4:5], v[78:79], v[136:137], v[120:121] op_sel_hi:[1,0,1] neg_lo:[0,1,0] neg_hi:[0,1,0]
	v_pk_fma_f32 v[14:15], v[80:81], v[134:135], v[114:115] op_sel_hi:[1,0,1] neg_lo:[0,1,0] neg_hi:[0,1,0]
	v_pk_fma_f32 v[6:7], v[80:81], v[136:137], v[122:123] op_sel_hi:[1,0,1] neg_lo:[0,1,0] neg_hi:[0,1,0]
	v_pk_fma_f32 v[8:9], v[82:83], v[134:135], v[116:117] op_sel_hi:[1,0,1] neg_lo:[0,1,0] neg_hi:[0,1,0]
	v_pk_fma_f32 v[0:1], v[82:83], v[136:137], v[124:125] op_sel_hi:[1,0,1] neg_lo:[0,1,0] neg_hi:[0,1,0]
	v_pk_fma_f32 v[10:11], v[84:85], v[134:135], v[118:119] op_sel_hi:[1,0,1] neg_lo:[0,1,0] neg_hi:[0,1,0]
	v_pk_fma_f32 v[2:3], v[84:85], v[136:137], v[126:127] op_sel_hi:[1,0,1] neg_lo:[0,1,0] neg_hi:[0,1,0]
	ds_read_b128 v[78:81], v51 offset:16896
	ds_read_b128 v[82:85], v51 offset:16912
	ds_read_b128 v[104:107], v51 offset:512
	ds_read_b128 v[108:111], v51 offset:528
	s_waitcnt lgkmcnt(9)
	v_pk_mul_f32 v[134:135], v[14:15], v[56:57]
	v_pk_mul_f32 v[136:137], v[6:7], v[56:57]
	v_pk_fma_f32 v[134:135], v[12:13], v[54:55], v[134:135]
	v_pk_fma_f32 v[136:137], v[4:5], v[54:55], v[136:137]
	v_pk_fma_f32 v[134:135], v[8:9], v[58:59], v[134:135]
	v_pk_fma_f32 v[136:137], v[0:1], v[58:59], v[136:137]
	v_pk_fma_f32 v[134:135], v[10:11], v[60:61], v[134:135]
	v_pk_fma_f32 v[136:137], v[2:3], v[60:61], v[136:137]
	v_add_f32_e32 v134, v134, v135
	v_add_f32_e32 v136, v136, v137
	ds_read_b128 v[54:57], v51 offset:13056
	ds_read_b128 v[58:61], v51 offset:13072
	s_waitcnt lgkmcnt(6)
	v_pk_mul_f32 v[112:113], v[70:71], v[86:87] op_sel_hi:[1,0]
	v_pk_mul_f32 v[120:121], v[70:71], v[86:87] op_sel:[0,1] op_sel_hi:[1,1]
	v_add_f32_dpp v134, v134, v134 quad_perm:[1,0,3,2] row_mask:0xf bank_mask:0xf bound_ctrl:1
	v_add_f32_dpp v136, v136, v136 quad_perm:[1,0,3,2] row_mask:0xf bank_mask:0xf bound_ctrl:1
	v_pk_mul_f32 v[114:115], v[72:73], v[86:87] op_sel_hi:[1,0]
	v_add_f32_dpp v134, v134, v134 quad_perm:[2,3,0,1] row_mask:0xf bank_mask:0xf bound_ctrl:1
	v_add_f32_dpp v136, v136, v136 quad_perm:[2,3,0,1] row_mask:0xf bank_mask:0xf bound_ctrl:1
	v_pk_mul_f32 v[122:123], v[72:73], v[86:87] op_sel:[0,1] op_sel_hi:[1,1]
	v_add_f32_dpp v134, v134, v134 row_half_mirror row_mask:0xf bank_mask:0xf bound_ctrl:1
	v_add_f32_dpp v136, v136, v136 row_half_mirror row_mask:0xf bank_mask:0xf bound_ctrl:1
	v_pk_mul_f32 v[116:117], v[74:75], v[86:87] op_sel_hi:[1,0]
	v_pk_mul_f32 v[124:125], v[74:75], v[86:87] op_sel:[0,1] op_sel_hi:[1,1]
	v_pk_mul_f32 v[118:119], v[76:77], v[86:87] op_sel_hi:[1,0]
	v_pk_mul_f32 v[126:127], v[76:77], v[86:87] op_sel:[0,1] op_sel_hi:[1,1]
	v_pk_fma_f32 v[112:113], v[12:13], v[62:63], v[112:113]
	v_pk_fma_f32 v[120:121], v[4:5], v[62:63], v[120:121]
	v_pk_fma_f32 v[114:115], v[14:15], v[64:65], v[114:115]
	v_pk_fma_f32 v[122:123], v[6:7], v[64:65], v[122:123]
	v_pk_fma_f32 v[116:117], v[8:9], v[66:67], v[116:117]
	v_pk_fma_f32 v[124:125], v[0:1], v[66:67], v[124:125]
	v_pk_fma_f32 v[118:119], v[10:11], v[68:69], v[118:119]
	v_pk_fma_f32 v[126:127], v[2:3], v[68:69], v[126:127]
	ds_read_b128 v[70:73], v51 offset:8960
	ds_read_b128 v[74:77], v51 offset:8976
	ds_read2_b32 v[86:87], v53 offset0:192 offset1:224
	ds_read_b128 v[62:65], v51 offset:4864
	ds_read_b128 v[66:69], v51 offset:4880
	v_mul_f32_e32 v139, v98, v14
	v_mul_f32_e32 v147, v98, v6
	v_fmac_f32_e32 v139, v99, v15
	v_fmac_f32_e32 v147, v99, v7
	v_fmac_f32_e32 v139, v96, v12
	v_fmac_f32_e32 v147, v96, v4
	v_fmac_f32_e32 v139, v97, v13
	v_fmac_f32_e32 v147, v97, v5
	v_fmac_f32_e32 v139, v100, v8
	v_fmac_f32_e32 v147, v100, v0
	v_fmac_f32_e32 v139, v101, v9
	v_fmac_f32_e32 v147, v101, v1
	v_fmac_f32_e32 v139, v102, v10
	v_fmac_f32_e32 v147, v102, v2
	v_fmac_f32_e32 v139, v103, v11
	v_fmac_f32_e32 v147, v103, v3
	s_waitcnt lgkmcnt(9)
	v_pk_fma_f32 v[12:13], v[78:79], v[134:135], v[112:113] op_sel_hi:[1,0,1] neg_lo:[0,1,0] neg_hi:[0,1,0]
	v_pk_fma_f32 v[4:5], v[78:79], v[136:137], v[120:121] op_sel_hi:[1,0,1] neg_lo:[0,1,0] neg_hi:[0,1,0]
	v_pk_fma_f32 v[14:15], v[80:81], v[134:135], v[114:115] op_sel_hi:[1,0,1] neg_lo:[0,1,0] neg_hi:[0,1,0]
	v_pk_fma_f32 v[6:7], v[80:81], v[136:137], v[122:123] op_sel_hi:[1,0,1] neg_lo:[0,1,0] neg_hi:[0,1,0]
	v_pk_fma_f32 v[8:9], v[82:83], v[134:135], v[116:117] op_sel_hi:[1,0,1] neg_lo:[0,1,0] neg_hi:[0,1,0]
	v_pk_fma_f32 v[0:1], v[82:83], v[136:137], v[124:125] op_sel_hi:[1,0,1] neg_lo:[0,1,0] neg_hi:[0,1,0]
	v_pk_fma_f32 v[10:11], v[84:85], v[134:135], v[118:119] op_sel_hi:[1,0,1] neg_lo:[0,1,0] neg_hi:[0,1,0]
	v_pk_fma_f32 v[2:3], v[84:85], v[136:137], v[126:127] op_sel_hi:[1,0,1] neg_lo:[0,1,0] neg_hi:[0,1,0]
	ds_read_b128 v[78:81], v51 offset:17152
	ds_read_b128 v[82:85], v51 offset:17168
	ds_read_b128 v[88:91], v51 offset:768
	ds_read_b128 v[92:95], v51 offset:784
	s_waitcnt lgkmcnt(9)
	v_pk_mul_f32 v[134:135], v[14:15], v[56:57]
	v_pk_mul_f32 v[136:137], v[6:7], v[56:57]
	v_pk_fma_f32 v[134:135], v[12:13], v[54:55], v[134:135]
	v_pk_fma_f32 v[136:137], v[4:5], v[54:55], v[136:137]
	v_pk_fma_f32 v[134:135], v[8:9], v[58:59], v[134:135]
	v_pk_fma_f32 v[136:137], v[0:1], v[58:59], v[136:137]
	v_pk_fma_f32 v[134:135], v[10:11], v[60:61], v[134:135]
	v_pk_fma_f32 v[136:137], v[2:3], v[60:61], v[136:137]
	v_add_f32_e32 v134, v134, v135
	v_add_f32_e32 v136, v136, v137
	ds_read_b128 v[54:57], v51 offset:13312
	ds_read_b128 v[58:61], v51 offset:13328
	s_waitcnt lgkmcnt(6)
	v_pk_mul_f32 v[112:113], v[70:71], v[86:87] op_sel_hi:[1,0]
	v_pk_mul_f32 v[120:121], v[70:71], v[86:87] op_sel:[0,1] op_sel_hi:[1,1]
	v_add_f32_dpp v134, v134, v134 quad_perm:[1,0,3,2] row_mask:0xf bank_mask:0xf bound_ctrl:1
	v_add_f32_dpp v136, v136, v136 quad_perm:[1,0,3,2] row_mask:0xf bank_mask:0xf bound_ctrl:1
	v_pk_mul_f32 v[114:115], v[72:73], v[86:87] op_sel_hi:[1,0]
	v_add_f32_dpp v134, v134, v134 quad_perm:[2,3,0,1] row_mask:0xf bank_mask:0xf bound_ctrl:1
	v_add_f32_dpp v136, v136, v136 quad_perm:[2,3,0,1] row_mask:0xf bank_mask:0xf bound_ctrl:1
	v_pk_mul_f32 v[122:123], v[72:73], v[86:87] op_sel:[0,1] op_sel_hi:[1,1]
	v_add_f32_dpp v134, v134, v134 row_half_mirror row_mask:0xf bank_mask:0xf bound_ctrl:1
	v_add_f32_dpp v136, v136, v136 row_half_mirror row_mask:0xf bank_mask:0xf bound_ctrl:1
	v_pk_mul_f32 v[116:117], v[74:75], v[86:87] op_sel_hi:[1,0]
	v_pk_mul_f32 v[124:125], v[74:75], v[86:87] op_sel:[0,1] op_sel_hi:[1,1]
	v_pk_mul_f32 v[118:119], v[76:77], v[86:87] op_sel_hi:[1,0]
	v_pk_mul_f32 v[126:127], v[76:77], v[86:87] op_sel:[0,1] op_sel_hi:[1,1]
	v_pk_fma_f32 v[112:113], v[12:13], v[62:63], v[112:113]
	v_pk_fma_f32 v[120:121], v[4:5], v[62:63], v[120:121]
	v_pk_fma_f32 v[114:115], v[14:15], v[64:65], v[114:115]
	v_pk_fma_f32 v[122:123], v[6:7], v[64:65], v[122:123]
	v_pk_fma_f32 v[116:117], v[8:9], v[66:67], v[116:117]
	v_pk_fma_f32 v[124:125], v[0:1], v[66:67], v[124:125]
	v_pk_fma_f32 v[118:119], v[10:11], v[68:69], v[118:119]
	v_pk_fma_f32 v[126:127], v[2:3], v[68:69], v[126:127]
	v_add_u32_e32 v53, 0x400, v53
	ds_read_b128 v[70:73], v51 offset:9216
	ds_read_b128 v[74:77], v51 offset:9232
	ds_read2_b32 v[86:87], v53 offset0:0 offset1:32
	ds_read_b128 v[62:65], v51 offset:5120
	ds_read_b128 v[66:69], v51 offset:5136
	v_mul_f32_e32 v140, v106, v14
	v_mul_f32_e32 v148, v106, v6
	v_fmac_f32_e32 v140, v107, v15
	v_fmac_f32_e32 v148, v107, v7
	v_fmac_f32_e32 v140, v104, v12
	v_fmac_f32_e32 v148, v104, v4
	v_fmac_f32_e32 v140, v105, v13
	v_fmac_f32_e32 v148, v105, v5
	v_fmac_f32_e32 v140, v108, v8
	v_fmac_f32_e32 v148, v108, v0
	v_fmac_f32_e32 v140, v109, v9
	v_fmac_f32_e32 v148, v109, v1
	v_fmac_f32_e32 v140, v110, v10
	v_fmac_f32_e32 v148, v110, v2
	v_fmac_f32_e32 v140, v111, v11
	v_fmac_f32_e32 v148, v111, v3
	s_waitcnt lgkmcnt(9)
	v_pk_fma_f32 v[12:13], v[78:79], v[134:135], v[112:113] op_sel_hi:[1,0,1] neg_lo:[0,1,0] neg_hi:[0,1,0]
	v_pk_fma_f32 v[4:5], v[78:79], v[136:137], v[120:121] op_sel_hi:[1,0,1] neg_lo:[0,1,0] neg_hi:[0,1,0]
	v_pk_fma_f32 v[14:15], v[80:81], v[134:135], v[114:115] op_sel_hi:[1,0,1] neg_lo:[0,1,0] neg_hi:[0,1,0]
	v_pk_fma_f32 v[6:7], v[80:81], v[136:137], v[122:123] op_sel_hi:[1,0,1] neg_lo:[0,1,0] neg_hi:[0,1,0]
	v_pk_fma_f32 v[8:9], v[82:83], v[134:135], v[116:117] op_sel_hi:[1,0,1] neg_lo:[0,1,0] neg_hi:[0,1,0]
	v_pk_fma_f32 v[0:1], v[82:83], v[136:137], v[124:125] op_sel_hi:[1,0,1] neg_lo:[0,1,0] neg_hi:[0,1,0]
	v_pk_fma_f32 v[10:11], v[84:85], v[134:135], v[118:119] op_sel_hi:[1,0,1] neg_lo:[0,1,0] neg_hi:[0,1,0]
	v_pk_fma_f32 v[2:3], v[84:85], v[136:137], v[126:127] op_sel_hi:[1,0,1] neg_lo:[0,1,0] neg_hi:[0,1,0]
	ds_read_b128 v[78:81], v51 offset:17408
	ds_read_b128 v[82:85], v51 offset:17424
	ds_read_b128 v[96:99], v51 offset:1024
	ds_read_b128 v[100:103], v51 offset:1040
	s_waitcnt lgkmcnt(9)
	v_pk_mul_f32 v[134:135], v[14:15], v[56:57]
	v_pk_mul_f32 v[136:137], v[6:7], v[56:57]
	v_pk_fma_f32 v[134:135], v[12:13], v[54:55], v[134:135]
	v_pk_fma_f32 v[136:137], v[4:5], v[54:55], v[136:137]
	v_pk_fma_f32 v[134:135], v[8:9], v[58:59], v[134:135]
	v_pk_fma_f32 v[136:137], v[0:1], v[58:59], v[136:137]
	v_pk_fma_f32 v[134:135], v[10:11], v[60:61], v[134:135]
	v_pk_fma_f32 v[136:137], v[2:3], v[60:61], v[136:137]
	v_add_f32_e32 v134, v134, v135
	v_add_f32_e32 v136, v136, v137
	ds_read_b128 v[54:57], v51 offset:13568
	ds_read_b128 v[58:61], v51 offset:13584
	s_waitcnt lgkmcnt(6)
	v_pk_mul_f32 v[112:113], v[70:71], v[86:87] op_sel_hi:[1,0]
	v_pk_mul_f32 v[120:121], v[70:71], v[86:87] op_sel:[0,1] op_sel_hi:[1,1]
	v_add_f32_dpp v134, v134, v134 quad_perm:[1,0,3,2] row_mask:0xf bank_mask:0xf bound_ctrl:1
	v_add_f32_dpp v136, v136, v136 quad_perm:[1,0,3,2] row_mask:0xf bank_mask:0xf bound_ctrl:1
	v_pk_mul_f32 v[114:115], v[72:73], v[86:87] op_sel_hi:[1,0]
	v_add_f32_dpp v134, v134, v134 quad_perm:[2,3,0,1] row_mask:0xf bank_mask:0xf bound_ctrl:1
	v_add_f32_dpp v136, v136, v136 quad_perm:[2,3,0,1] row_mask:0xf bank_mask:0xf bound_ctrl:1
	v_pk_mul_f32 v[122:123], v[72:73], v[86:87] op_sel:[0,1] op_sel_hi:[1,1]
	v_add_f32_dpp v134, v134, v134 row_half_mirror row_mask:0xf bank_mask:0xf bound_ctrl:1
	v_add_f32_dpp v136, v136, v136 row_half_mirror row_mask:0xf bank_mask:0xf bound_ctrl:1
	v_pk_mul_f32 v[116:117], v[74:75], v[86:87] op_sel_hi:[1,0]
	v_pk_mul_f32 v[124:125], v[74:75], v[86:87] op_sel:[0,1] op_sel_hi:[1,1]
	v_pk_mul_f32 v[118:119], v[76:77], v[86:87] op_sel_hi:[1,0]
	v_pk_mul_f32 v[126:127], v[76:77], v[86:87] op_sel:[0,1] op_sel_hi:[1,1]
	v_pk_fma_f32 v[112:113], v[12:13], v[62:63], v[112:113]
	v_pk_fma_f32 v[120:121], v[4:5], v[62:63], v[120:121]
	v_pk_fma_f32 v[114:115], v[14:15], v[64:65], v[114:115]
	v_pk_fma_f32 v[122:123], v[6:7], v[64:65], v[122:123]
	v_pk_fma_f32 v[116:117], v[8:9], v[66:67], v[116:117]
	v_pk_fma_f32 v[124:125], v[0:1], v[66:67], v[124:125]
	v_pk_fma_f32 v[118:119], v[10:11], v[68:69], v[118:119]
	v_pk_fma_f32 v[126:127], v[2:3], v[68:69], v[126:127]
	ds_read_b128 v[70:73], v51 offset:9472
	ds_read_b128 v[74:77], v51 offset:9488
	ds_read2_b32 v[86:87], v53 offset0:64 offset1:96
	ds_read_b128 v[62:65], v51 offset:5376
	ds_read_b128 v[66:69], v51 offset:5392
	v_mul_f32_e32 v141, v90, v14
	v_mul_f32_e32 v149, v90, v6
	v_fmac_f32_e32 v141, v91, v15
	v_fmac_f32_e32 v149, v91, v7
	v_fmac_f32_e32 v141, v88, v12
	v_fmac_f32_e32 v149, v88, v4
	v_fmac_f32_e32 v141, v89, v13
	v_fmac_f32_e32 v149, v89, v5
	v_fmac_f32_e32 v141, v92, v8
	v_fmac_f32_e32 v149, v92, v0
	v_fmac_f32_e32 v141, v93, v9
	v_fmac_f32_e32 v149, v93, v1
	v_fmac_f32_e32 v141, v94, v10
	v_fmac_f32_e32 v149, v94, v2
	v_fmac_f32_e32 v141, v95, v11
	v_fmac_f32_e32 v149, v95, v3
	s_waitcnt lgkmcnt(9)
	v_pk_fma_f32 v[12:13], v[78:79], v[134:135], v[112:113] op_sel_hi:[1,0,1] neg_lo:[0,1,0] neg_hi:[0,1,0]
	v_pk_fma_f32 v[4:5], v[78:79], v[136:137], v[120:121] op_sel_hi:[1,0,1] neg_lo:[0,1,0] neg_hi:[0,1,0]
	v_pk_fma_f32 v[14:15], v[80:81], v[134:135], v[114:115] op_sel_hi:[1,0,1] neg_lo:[0,1,0] neg_hi:[0,1,0]
	v_pk_fma_f32 v[6:7], v[80:81], v[136:137], v[122:123] op_sel_hi:[1,0,1] neg_lo:[0,1,0] neg_hi:[0,1,0]
	v_pk_fma_f32 v[8:9], v[82:83], v[134:135], v[116:117] op_sel_hi:[1,0,1] neg_lo:[0,1,0] neg_hi:[0,1,0]
	v_pk_fma_f32 v[0:1], v[82:83], v[136:137], v[124:125] op_sel_hi:[1,0,1] neg_lo:[0,1,0] neg_hi:[0,1,0]
	v_pk_fma_f32 v[10:11], v[84:85], v[134:135], v[118:119] op_sel_hi:[1,0,1] neg_lo:[0,1,0] neg_hi:[0,1,0]
	v_pk_fma_f32 v[2:3], v[84:85], v[136:137], v[126:127] op_sel_hi:[1,0,1] neg_lo:[0,1,0] neg_hi:[0,1,0]
	ds_read_b128 v[78:81], v51 offset:17664
	ds_read_b128 v[82:85], v51 offset:17680
	ds_read_b128 v[104:107], v51 offset:1280
	ds_read_b128 v[108:111], v51 offset:1296
	s_waitcnt lgkmcnt(9)
	v_pk_mul_f32 v[134:135], v[14:15], v[56:57]
	v_pk_mul_f32 v[136:137], v[6:7], v[56:57]
	v_pk_fma_f32 v[134:135], v[12:13], v[54:55], v[134:135]
	v_pk_fma_f32 v[136:137], v[4:5], v[54:55], v[136:137]
	v_pk_fma_f32 v[134:135], v[8:9], v[58:59], v[134:135]
	v_pk_fma_f32 v[136:137], v[0:1], v[58:59], v[136:137]
	v_pk_fma_f32 v[134:135], v[10:11], v[60:61], v[134:135]
	v_pk_fma_f32 v[136:137], v[2:3], v[60:61], v[136:137]
	v_add_f32_e32 v134, v134, v135
	v_add_f32_e32 v136, v136, v137
	ds_read_b128 v[54:57], v51 offset:13824
	ds_read_b128 v[58:61], v51 offset:13840
	s_waitcnt lgkmcnt(6)
	v_pk_mul_f32 v[112:113], v[70:71], v[86:87] op_sel_hi:[1,0]
	v_pk_mul_f32 v[120:121], v[70:71], v[86:87] op_sel:[0,1] op_sel_hi:[1,1]
	v_add_f32_dpp v134, v134, v134 quad_perm:[1,0,3,2] row_mask:0xf bank_mask:0xf bound_ctrl:1
	v_add_f32_dpp v136, v136, v136 quad_perm:[1,0,3,2] row_mask:0xf bank_mask:0xf bound_ctrl:1
	v_pk_mul_f32 v[114:115], v[72:73], v[86:87] op_sel_hi:[1,0]
	v_add_f32_dpp v134, v134, v134 quad_perm:[2,3,0,1] row_mask:0xf bank_mask:0xf bound_ctrl:1
	v_add_f32_dpp v136, v136, v136 quad_perm:[2,3,0,1] row_mask:0xf bank_mask:0xf bound_ctrl:1
	v_pk_mul_f32 v[122:123], v[72:73], v[86:87] op_sel:[0,1] op_sel_hi:[1,1]
	v_add_f32_dpp v134, v134, v134 row_half_mirror row_mask:0xf bank_mask:0xf bound_ctrl:1
	v_add_f32_dpp v136, v136, v136 row_half_mirror row_mask:0xf bank_mask:0xf bound_ctrl:1
	v_pk_mul_f32 v[116:117], v[74:75], v[86:87] op_sel_hi:[1,0]
	v_pk_mul_f32 v[124:125], v[74:75], v[86:87] op_sel:[0,1] op_sel_hi:[1,1]
	v_pk_mul_f32 v[118:119], v[76:77], v[86:87] op_sel_hi:[1,0]
	v_pk_mul_f32 v[126:127], v[76:77], v[86:87] op_sel:[0,1] op_sel_hi:[1,1]
	v_pk_fma_f32 v[112:113], v[12:13], v[62:63], v[112:113]
	v_pk_fma_f32 v[120:121], v[4:5], v[62:63], v[120:121]
	v_pk_fma_f32 v[114:115], v[14:15], v[64:65], v[114:115]
	v_pk_fma_f32 v[122:123], v[6:7], v[64:65], v[122:123]
	v_pk_fma_f32 v[116:117], v[8:9], v[66:67], v[116:117]
	v_pk_fma_f32 v[124:125], v[0:1], v[66:67], v[124:125]
	v_pk_fma_f32 v[118:119], v[10:11], v[68:69], v[118:119]
	v_pk_fma_f32 v[126:127], v[2:3], v[68:69], v[126:127]
	ds_read_b128 v[70:73], v51 offset:9728
	ds_read_b128 v[74:77], v51 offset:9744
	ds_read2_b32 v[86:87], v53 offset0:128 offset1:160
	ds_read_b128 v[62:65], v51 offset:5632
	ds_read_b128 v[66:69], v51 offset:5648
	v_mul_f32_e32 v142, v98, v14
	v_mul_f32_e32 v150, v98, v6
	v_fmac_f32_e32 v142, v99, v15
	v_fmac_f32_e32 v150, v99, v7
	v_fmac_f32_e32 v142, v96, v12
	v_fmac_f32_e32 v150, v96, v4
	v_fmac_f32_e32 v142, v97, v13
	v_fmac_f32_e32 v150, v97, v5
	v_fmac_f32_e32 v142, v100, v8
	v_fmac_f32_e32 v150, v100, v0
	v_fmac_f32_e32 v142, v101, v9
	v_fmac_f32_e32 v150, v101, v1
	v_fmac_f32_e32 v142, v102, v10
	v_fmac_f32_e32 v150, v102, v2
	v_fmac_f32_e32 v142, v103, v11
	v_fmac_f32_e32 v150, v103, v3
	s_waitcnt lgkmcnt(9)
	v_pk_fma_f32 v[12:13], v[78:79], v[134:135], v[112:113] op_sel_hi:[1,0,1] neg_lo:[0,1,0] neg_hi:[0,1,0]
	v_pk_fma_f32 v[4:5], v[78:79], v[136:137], v[120:121] op_sel_hi:[1,0,1] neg_lo:[0,1,0] neg_hi:[0,1,0]
	v_pk_fma_f32 v[14:15], v[80:81], v[134:135], v[114:115] op_sel_hi:[1,0,1] neg_lo:[0,1,0] neg_hi:[0,1,0]
	v_pk_fma_f32 v[6:7], v[80:81], v[136:137], v[122:123] op_sel_hi:[1,0,1] neg_lo:[0,1,0] neg_hi:[0,1,0]
	v_pk_fma_f32 v[8:9], v[82:83], v[134:135], v[116:117] op_sel_hi:[1,0,1] neg_lo:[0,1,0] neg_hi:[0,1,0]
	v_pk_fma_f32 v[0:1], v[82:83], v[136:137], v[124:125] op_sel_hi:[1,0,1] neg_lo:[0,1,0] neg_hi:[0,1,0]
	v_pk_fma_f32 v[10:11], v[84:85], v[134:135], v[118:119] op_sel_hi:[1,0,1] neg_lo:[0,1,0] neg_hi:[0,1,0]
	v_pk_fma_f32 v[2:3], v[84:85], v[136:137], v[126:127] op_sel_hi:[1,0,1] neg_lo:[0,1,0] neg_hi:[0,1,0]
	ds_read_b128 v[78:81], v51 offset:17920
	ds_read_b128 v[82:85], v51 offset:17936
	ds_read_b128 v[88:91], v51 offset:1536
	ds_read_b128 v[92:95], v51 offset:1552
	s_waitcnt lgkmcnt(9)
	v_pk_mul_f32 v[134:135], v[14:15], v[56:57]
	v_pk_mul_f32 v[136:137], v[6:7], v[56:57]
	v_pk_fma_f32 v[134:135], v[12:13], v[54:55], v[134:135]
	v_pk_fma_f32 v[136:137], v[4:5], v[54:55], v[136:137]
	v_pk_fma_f32 v[134:135], v[8:9], v[58:59], v[134:135]
	v_pk_fma_f32 v[136:137], v[0:1], v[58:59], v[136:137]
	v_pk_fma_f32 v[134:135], v[10:11], v[60:61], v[134:135]
	v_pk_fma_f32 v[136:137], v[2:3], v[60:61], v[136:137]
	v_add_f32_e32 v134, v134, v135
	v_add_f32_e32 v136, v136, v137
	ds_read_b128 v[54:57], v51 offset:14080
	ds_read_b128 v[58:61], v51 offset:14096
	s_waitcnt lgkmcnt(6)
	v_pk_mul_f32 v[112:113], v[70:71], v[86:87] op_sel_hi:[1,0]
	v_pk_mul_f32 v[120:121], v[70:71], v[86:87] op_sel:[0,1] op_sel_hi:[1,1]
	v_add_f32_dpp v134, v134, v134 quad_perm:[1,0,3,2] row_mask:0xf bank_mask:0xf bound_ctrl:1
	v_add_f32_dpp v136, v136, v136 quad_perm:[1,0,3,2] row_mask:0xf bank_mask:0xf bound_ctrl:1
	v_pk_mul_f32 v[114:115], v[72:73], v[86:87] op_sel_hi:[1,0]
	v_add_f32_dpp v134, v134, v134 quad_perm:[2,3,0,1] row_mask:0xf bank_mask:0xf bound_ctrl:1
	v_add_f32_dpp v136, v136, v136 quad_perm:[2,3,0,1] row_mask:0xf bank_mask:0xf bound_ctrl:1
	v_pk_mul_f32 v[122:123], v[72:73], v[86:87] op_sel:[0,1] op_sel_hi:[1,1]
	v_add_f32_dpp v134, v134, v134 row_half_mirror row_mask:0xf bank_mask:0xf bound_ctrl:1
	v_add_f32_dpp v136, v136, v136 row_half_mirror row_mask:0xf bank_mask:0xf bound_ctrl:1
	v_pk_mul_f32 v[116:117], v[74:75], v[86:87] op_sel_hi:[1,0]
	v_pk_mul_f32 v[124:125], v[74:75], v[86:87] op_sel:[0,1] op_sel_hi:[1,1]
	v_pk_mul_f32 v[118:119], v[76:77], v[86:87] op_sel_hi:[1,0]
	v_pk_mul_f32 v[126:127], v[76:77], v[86:87] op_sel:[0,1] op_sel_hi:[1,1]
	v_pk_fma_f32 v[112:113], v[12:13], v[62:63], v[112:113]
	v_pk_fma_f32 v[120:121], v[4:5], v[62:63], v[120:121]
	v_pk_fma_f32 v[114:115], v[14:15], v[64:65], v[114:115]
	v_pk_fma_f32 v[122:123], v[6:7], v[64:65], v[122:123]
	v_pk_fma_f32 v[116:117], v[8:9], v[66:67], v[116:117]
	v_pk_fma_f32 v[124:125], v[0:1], v[66:67], v[124:125]
	v_pk_fma_f32 v[118:119], v[10:11], v[68:69], v[118:119]
	v_pk_fma_f32 v[126:127], v[2:3], v[68:69], v[126:127]
	ds_read_b128 v[70:73], v51 offset:9984
	ds_read_b128 v[74:77], v51 offset:10000
	ds_read2_b32 v[86:87], v53 offset0:192 offset1:224
	ds_read_b128 v[62:65], v51 offset:5888
	ds_read_b128 v[66:69], v51 offset:5904
	v_mul_f32_e32 v143, v106, v14
	v_mul_f32_e32 v151, v106, v6
	v_fmac_f32_e32 v143, v107, v15
	v_fmac_f32_e32 v151, v107, v7
	v_fmac_f32_e32 v143, v104, v12
	v_fmac_f32_e32 v151, v104, v4
	v_fmac_f32_e32 v143, v105, v13
	v_fmac_f32_e32 v151, v105, v5
	v_fmac_f32_e32 v143, v108, v8
	v_fmac_f32_e32 v151, v108, v0
	v_fmac_f32_e32 v143, v109, v9
	v_fmac_f32_e32 v151, v109, v1
	v_fmac_f32_e32 v143, v110, v10
	v_fmac_f32_e32 v151, v110, v2
	v_fmac_f32_e32 v143, v111, v11
	v_fmac_f32_e32 v151, v111, v3
	s_waitcnt lgkmcnt(9)
	v_pk_fma_f32 v[12:13], v[78:79], v[134:135], v[112:113] op_sel_hi:[1,0,1] neg_lo:[0,1,0] neg_hi:[0,1,0]
	v_pk_fma_f32 v[4:5], v[78:79], v[136:137], v[120:121] op_sel_hi:[1,0,1] neg_lo:[0,1,0] neg_hi:[0,1,0]
	v_pk_fma_f32 v[14:15], v[80:81], v[134:135], v[114:115] op_sel_hi:[1,0,1] neg_lo:[0,1,0] neg_hi:[0,1,0]
	v_pk_fma_f32 v[6:7], v[80:81], v[136:137], v[122:123] op_sel_hi:[1,0,1] neg_lo:[0,1,0] neg_hi:[0,1,0]
	v_pk_fma_f32 v[8:9], v[82:83], v[134:135], v[116:117] op_sel_hi:[1,0,1] neg_lo:[0,1,0] neg_hi:[0,1,0]
	v_pk_fma_f32 v[0:1], v[82:83], v[136:137], v[124:125] op_sel_hi:[1,0,1] neg_lo:[0,1,0] neg_hi:[0,1,0]
	v_pk_fma_f32 v[10:11], v[84:85], v[134:135], v[118:119] op_sel_hi:[1,0,1] neg_lo:[0,1,0] neg_hi:[0,1,0]
	v_pk_fma_f32 v[2:3], v[84:85], v[136:137], v[126:127] op_sel_hi:[1,0,1] neg_lo:[0,1,0] neg_hi:[0,1,0]
	ds_read_b128 v[78:81], v51 offset:18176
	ds_read_b128 v[82:85], v51 offset:18192
	ds_read_b128 v[96:99], v51 offset:1792
	ds_read_b128 v[100:103], v51 offset:1808
	s_waitcnt lgkmcnt(9)
	v_pk_mul_f32 v[134:135], v[14:15], v[56:57]
	v_pk_mul_f32 v[136:137], v[6:7], v[56:57]
	v_pk_fma_f32 v[134:135], v[12:13], v[54:55], v[134:135]
	v_pk_fma_f32 v[136:137], v[4:5], v[54:55], v[136:137]
	v_pk_fma_f32 v[134:135], v[8:9], v[58:59], v[134:135]
	v_pk_fma_f32 v[136:137], v[0:1], v[58:59], v[136:137]
	v_pk_fma_f32 v[134:135], v[10:11], v[60:61], v[134:135]
	v_pk_fma_f32 v[136:137], v[2:3], v[60:61], v[136:137]
	v_add_f32_e32 v134, v134, v135
	v_add_f32_e32 v136, v136, v137
	ds_read_b128 v[54:57], v51 offset:14336
	ds_read_b128 v[58:61], v51 offset:14352
	s_waitcnt lgkmcnt(6)
	v_pk_mul_f32 v[112:113], v[70:71], v[86:87] op_sel_hi:[1,0]
	v_pk_mul_f32 v[120:121], v[70:71], v[86:87] op_sel:[0,1] op_sel_hi:[1,1]
	v_add_f32_dpp v134, v134, v134 quad_perm:[1,0,3,2] row_mask:0xf bank_mask:0xf bound_ctrl:1
	v_add_f32_dpp v136, v136, v136 quad_perm:[1,0,3,2] row_mask:0xf bank_mask:0xf bound_ctrl:1
	v_pk_mul_f32 v[114:115], v[72:73], v[86:87] op_sel_hi:[1,0]
	v_add_f32_dpp v134, v134, v134 quad_perm:[2,3,0,1] row_mask:0xf bank_mask:0xf bound_ctrl:1
	v_add_f32_dpp v136, v136, v136 quad_perm:[2,3,0,1] row_mask:0xf bank_mask:0xf bound_ctrl:1
	v_pk_mul_f32 v[122:123], v[72:73], v[86:87] op_sel:[0,1] op_sel_hi:[1,1]
	v_add_f32_dpp v134, v134, v134 row_half_mirror row_mask:0xf bank_mask:0xf bound_ctrl:1
	v_add_f32_dpp v136, v136, v136 row_half_mirror row_mask:0xf bank_mask:0xf bound_ctrl:1
	v_pk_mul_f32 v[116:117], v[74:75], v[86:87] op_sel_hi:[1,0]
	v_pk_mul_f32 v[124:125], v[74:75], v[86:87] op_sel:[0,1] op_sel_hi:[1,1]
	v_pk_mul_f32 v[118:119], v[76:77], v[86:87] op_sel_hi:[1,0]
	v_pk_mul_f32 v[126:127], v[76:77], v[86:87] op_sel:[0,1] op_sel_hi:[1,1]
	v_pk_fma_f32 v[112:113], v[12:13], v[62:63], v[112:113]
	v_pk_fma_f32 v[120:121], v[4:5], v[62:63], v[120:121]
	v_pk_fma_f32 v[114:115], v[14:15], v[64:65], v[114:115]
	v_pk_fma_f32 v[122:123], v[6:7], v[64:65], v[122:123]
	v_pk_fma_f32 v[116:117], v[8:9], v[66:67], v[116:117]
	v_pk_fma_f32 v[124:125], v[0:1], v[66:67], v[124:125]
	v_pk_fma_f32 v[118:119], v[10:11], v[68:69], v[118:119]
	v_pk_fma_f32 v[126:127], v[2:3], v[68:69], v[126:127]
	v_add_u32_e32 v53, 0x400, v53
	ds_read_b128 v[70:73], v51 offset:10240
	ds_read_b128 v[74:77], v51 offset:10256
	ds_read2_b32 v[86:87], v53 offset0:0 offset1:32
	ds_read_b128 v[62:65], v51 offset:6144
	ds_read_b128 v[66:69], v51 offset:6160
	v_mul_f32_e32 v144, v90, v14
	v_mul_f32_e32 v152, v90, v6
	v_fmac_f32_e32 v144, v91, v15
	v_fmac_f32_e32 v152, v91, v7
	v_fmac_f32_e32 v144, v88, v12
	v_fmac_f32_e32 v152, v88, v4
	v_fmac_f32_e32 v144, v89, v13
	v_fmac_f32_e32 v152, v89, v5
	v_fmac_f32_e32 v144, v92, v8
	v_fmac_f32_e32 v152, v92, v0
	v_fmac_f32_e32 v144, v93, v9
	v_fmac_f32_e32 v152, v93, v1
	v_fmac_f32_e32 v144, v94, v10
	v_fmac_f32_e32 v152, v94, v2
	v_fmac_f32_e32 v144, v95, v11
	v_fmac_f32_e32 v152, v95, v3
	s_waitcnt lgkmcnt(9)
	v_pk_fma_f32 v[12:13], v[78:79], v[134:135], v[112:113] op_sel_hi:[1,0,1] neg_lo:[0,1,0] neg_hi:[0,1,0]
	v_pk_fma_f32 v[4:5], v[78:79], v[136:137], v[120:121] op_sel_hi:[1,0,1] neg_lo:[0,1,0] neg_hi:[0,1,0]
	v_pk_fma_f32 v[14:15], v[80:81], v[134:135], v[114:115] op_sel_hi:[1,0,1] neg_lo:[0,1,0] neg_hi:[0,1,0]
	v_pk_fma_f32 v[6:7], v[80:81], v[136:137], v[122:123] op_sel_hi:[1,0,1] neg_lo:[0,1,0] neg_hi:[0,1,0]
	v_pk_fma_f32 v[8:9], v[82:83], v[134:135], v[116:117] op_sel_hi:[1,0,1] neg_lo:[0,1,0] neg_hi:[0,1,0]
	v_pk_fma_f32 v[0:1], v[82:83], v[136:137], v[124:125] op_sel_hi:[1,0,1] neg_lo:[0,1,0] neg_hi:[0,1,0]
	v_pk_fma_f32 v[10:11], v[84:85], v[134:135], v[118:119] op_sel_hi:[1,0,1] neg_lo:[0,1,0] neg_hi:[0,1,0]
	v_pk_fma_f32 v[2:3], v[84:85], v[136:137], v[126:127] op_sel_hi:[1,0,1] neg_lo:[0,1,0] neg_hi:[0,1,0]
	ds_read_b128 v[78:81], v51 offset:18432
	ds_read_b128 v[82:85], v51 offset:18448
	ds_read_b128 v[104:107], v51 offset:2048
	ds_read_b128 v[108:111], v51 offset:2064
	s_waitcnt lgkmcnt(9)
	v_pk_mul_f32 v[134:135], v[14:15], v[56:57]
	v_pk_mul_f32 v[136:137], v[6:7], v[56:57]
	v_pk_fma_f32 v[134:135], v[12:13], v[54:55], v[134:135]
	v_pk_fma_f32 v[136:137], v[4:5], v[54:55], v[136:137]
	v_pk_fma_f32 v[134:135], v[8:9], v[58:59], v[134:135]
	v_pk_fma_f32 v[136:137], v[0:1], v[58:59], v[136:137]
	v_pk_fma_f32 v[134:135], v[10:11], v[60:61], v[134:135]
	v_pk_fma_f32 v[136:137], v[2:3], v[60:61], v[136:137]
	v_add_f32_e32 v134, v134, v135
	v_add_f32_e32 v136, v136, v137
	ds_read_b128 v[54:57], v51 offset:14592
	ds_read_b128 v[58:61], v51 offset:14608
	s_waitcnt lgkmcnt(6)
	v_pk_mul_f32 v[112:113], v[70:71], v[86:87] op_sel_hi:[1,0]
	v_pk_mul_f32 v[120:121], v[70:71], v[86:87] op_sel:[0,1] op_sel_hi:[1,1]
	v_add_f32_dpp v134, v134, v134 quad_perm:[1,0,3,2] row_mask:0xf bank_mask:0xf bound_ctrl:1
	v_add_f32_dpp v136, v136, v136 quad_perm:[1,0,3,2] row_mask:0xf bank_mask:0xf bound_ctrl:1
	v_pk_mul_f32 v[114:115], v[72:73], v[86:87] op_sel_hi:[1,0]
	v_add_f32_dpp v134, v134, v134 quad_perm:[2,3,0,1] row_mask:0xf bank_mask:0xf bound_ctrl:1
	v_add_f32_dpp v136, v136, v136 quad_perm:[2,3,0,1] row_mask:0xf bank_mask:0xf bound_ctrl:1
	v_pk_mul_f32 v[122:123], v[72:73], v[86:87] op_sel:[0,1] op_sel_hi:[1,1]
	v_add_f32_dpp v134, v134, v134 row_half_mirror row_mask:0xf bank_mask:0xf bound_ctrl:1
	v_add_f32_dpp v136, v136, v136 row_half_mirror row_mask:0xf bank_mask:0xf bound_ctrl:1
	v_pk_mul_f32 v[116:117], v[74:75], v[86:87] op_sel_hi:[1,0]
	v_pk_mul_f32 v[124:125], v[74:75], v[86:87] op_sel:[0,1] op_sel_hi:[1,1]
	v_pk_mul_f32 v[118:119], v[76:77], v[86:87] op_sel_hi:[1,0]
	v_pk_mul_f32 v[126:127], v[76:77], v[86:87] op_sel:[0,1] op_sel_hi:[1,1]
	v_pk_fma_f32 v[112:113], v[12:13], v[62:63], v[112:113]
	v_pk_fma_f32 v[120:121], v[4:5], v[62:63], v[120:121]
	v_pk_fma_f32 v[114:115], v[14:15], v[64:65], v[114:115]
	v_pk_fma_f32 v[122:123], v[6:7], v[64:65], v[122:123]
	v_pk_fma_f32 v[116:117], v[8:9], v[66:67], v[116:117]
	v_pk_fma_f32 v[124:125], v[0:1], v[66:67], v[124:125]
	v_pk_fma_f32 v[118:119], v[10:11], v[68:69], v[118:119]
	v_pk_fma_f32 v[126:127], v[2:3], v[68:69], v[126:127]
	ds_read_b128 v[70:73], v51 offset:10496
	ds_read_b128 v[74:77], v51 offset:10512
	ds_read2_b32 v[86:87], v53 offset0:64 offset1:96
	ds_read_b128 v[62:65], v51 offset:6400
	ds_read_b128 v[66:69], v51 offset:6416
	v_mul_f32_e32 v145, v98, v14
	v_mul_f32_e32 v153, v98, v6
	v_fmac_f32_e32 v145, v99, v15
	v_fmac_f32_e32 v153, v99, v7
	v_fmac_f32_e32 v145, v96, v12
	v_fmac_f32_e32 v153, v96, v4
	v_fmac_f32_e32 v145, v97, v13
	v_fmac_f32_e32 v153, v97, v5
	v_fmac_f32_e32 v145, v100, v8
	v_fmac_f32_e32 v153, v100, v0
	v_fmac_f32_e32 v145, v101, v9
	v_fmac_f32_e32 v153, v101, v1
	v_fmac_f32_e32 v145, v102, v10
	v_fmac_f32_e32 v153, v102, v2
	v_fmac_f32_e32 v145, v103, v11
	v_fmac_f32_e32 v153, v103, v3
	s_waitcnt lgkmcnt(9)
	v_pk_fma_f32 v[12:13], v[78:79], v[134:135], v[112:113] op_sel_hi:[1,0,1] neg_lo:[0,1,0] neg_hi:[0,1,0]
	v_pk_fma_f32 v[4:5], v[78:79], v[136:137], v[120:121] op_sel_hi:[1,0,1] neg_lo:[0,1,0] neg_hi:[0,1,0]
	v_pk_fma_f32 v[14:15], v[80:81], v[134:135], v[114:115] op_sel_hi:[1,0,1] neg_lo:[0,1,0] neg_hi:[0,1,0]
	v_pk_fma_f32 v[6:7], v[80:81], v[136:137], v[122:123] op_sel_hi:[1,0,1] neg_lo:[0,1,0] neg_hi:[0,1,0]
	v_pk_fma_f32 v[8:9], v[82:83], v[134:135], v[116:117] op_sel_hi:[1,0,1] neg_lo:[0,1,0] neg_hi:[0,1,0]
	v_pk_fma_f32 v[0:1], v[82:83], v[136:137], v[124:125] op_sel_hi:[1,0,1] neg_lo:[0,1,0] neg_hi:[0,1,0]
	v_pk_fma_f32 v[10:11], v[84:85], v[134:135], v[118:119] op_sel_hi:[1,0,1] neg_lo:[0,1,0] neg_hi:[0,1,0]
	v_pk_fma_f32 v[2:3], v[84:85], v[136:137], v[126:127] op_sel_hi:[1,0,1] neg_lo:[0,1,0] neg_hi:[0,1,0]
	ds_read_b128 v[78:81], v51 offset:18688
	ds_read_b128 v[82:85], v51 offset:18704
	ds_read_b128 v[88:91], v51 offset:2304
	ds_read_b128 v[92:95], v51 offset:2320
	v_cndmask_b32_e64 v112, v138, v139, s[4:5]
	v_cndmask_b32_e64 v113, v139, v138, s[4:5]
	v_cndmask_b32_e64 v114, v140, v141, s[4:5]
	v_cndmask_b32_e64 v115, v141, v140, s[4:5]
	s_nop 0
	v_add_f32_dpp v138, v113, v112 quad_perm:[1,0,3,2] row_mask:0xf bank_mask:0xf bound_ctrl:1
	v_add_f32_dpp v140, v115, v114 quad_perm:[1,0,3,2] row_mask:0xf bank_mask:0xf bound_ctrl:1
	v_cndmask_b32_e64 v112, v142, v143, s[4:5]
	v_cndmask_b32_e64 v113, v143, v142, s[4:5]
	v_cndmask_b32_e64 v114, v144, v145, s[4:5]
	v_cndmask_b32_e64 v115, v145, v144, s[4:5]
	s_nop 0
	v_add_f32_dpp v142, v113, v112 quad_perm:[1,0,3,2] row_mask:0xf bank_mask:0xf bound_ctrl:1
	v_add_f32_dpp v144, v115, v114 quad_perm:[1,0,3,2] row_mask:0xf bank_mask:0xf bound_ctrl:1
	v_cndmask_b32_e64 v112, v138, v140, s[6:7]
	v_cndmask_b32_e64 v113, v140, v138, s[6:7]
	v_cndmask_b32_e64 v114, v142, v144, s[6:7]
	v_cndmask_b32_e64 v115, v144, v142, s[6:7]
	s_nop 0
	v_add_f32_dpp v138, v113, v112 quad_perm:[2,3,0,1] row_mask:0xf bank_mask:0xf bound_ctrl:1
	v_add_f32_dpp v142, v115, v114 quad_perm:[2,3,0,1] row_mask:0xf bank_mask:0xf bound_ctrl:1
	s_nop 1
	v_add_f32_dpp v154, v138, v138 row_shl:4 row_mask:0xf bank_mask:0x5 bound_ctrl:1
	s_nop 1
	v_add_f32_dpp v154, v142, v142 row_shr:4 row_mask:0xf bank_mask:0xa bound_ctrl:1
	v_cndmask_b32_e64 v112, v146, v147, s[4:5]
	v_cndmask_b32_e64 v113, v147, v146, s[4:5]
	v_cndmask_b32_e64 v114, v148, v149, s[4:5]
	v_cndmask_b32_e64 v115, v149, v148, s[4:5]
	s_nop 0
	v_add_f32_dpp v146, v113, v112 quad_perm:[1,0,3,2] row_mask:0xf bank_mask:0xf bound_ctrl:1
	v_add_f32_dpp v148, v115, v114 quad_perm:[1,0,3,2] row_mask:0xf bank_mask:0xf bound_ctrl:1
	v_cndmask_b32_e64 v112, v150, v151, s[4:5]
	v_cndmask_b32_e64 v113, v151, v150, s[4:5]
	v_cndmask_b32_e64 v114, v152, v153, s[4:5]
	v_cndmask_b32_e64 v115, v153, v152, s[4:5]
	s_nop 0
	v_add_f32_dpp v150, v113, v112 quad_perm:[1,0,3,2] row_mask:0xf bank_mask:0xf bound_ctrl:1
	v_add_f32_dpp v152, v115, v114 quad_perm:[1,0,3,2] row_mask:0xf bank_mask:0xf bound_ctrl:1
	v_cndmask_b32_e64 v112, v146, v148, s[6:7]
	v_cndmask_b32_e64 v113, v148, v146, s[6:7]
	v_cndmask_b32_e64 v114, v150, v152, s[6:7]
	v_cndmask_b32_e64 v115, v152, v150, s[6:7]
	s_nop 0
	v_add_f32_dpp v146, v113, v112 quad_perm:[2,3,0,1] row_mask:0xf bank_mask:0xf bound_ctrl:1
	v_add_f32_dpp v150, v115, v114 quad_perm:[2,3,0,1] row_mask:0xf bank_mask:0xf bound_ctrl:1
	s_nop 1
	v_add_f32_dpp v155, v146, v146 row_shl:4 row_mask:0xf bank_mask:0x5 bound_ctrl:1
	s_nop 1
	v_add_f32_dpp v155, v150, v150 row_shr:4 row_mask:0xf bank_mask:0xa bound_ctrl:1
	s_waitcnt lgkmcnt(9)
	v_pk_mul_f32 v[134:135], v[14:15], v[56:57]
	v_pk_mul_f32 v[136:137], v[6:7], v[56:57]
	v_pk_fma_f32 v[134:135], v[12:13], v[54:55], v[134:135]
	v_pk_fma_f32 v[136:137], v[4:5], v[54:55], v[136:137]
	v_pk_fma_f32 v[134:135], v[8:9], v[58:59], v[134:135]
	v_pk_fma_f32 v[136:137], v[0:1], v[58:59], v[136:137]
	v_pk_fma_f32 v[134:135], v[10:11], v[60:61], v[134:135]
	v_pk_fma_f32 v[136:137], v[2:3], v[60:61], v[136:137]
	v_add_f32_e32 v134, v134, v135
	v_add_f32_e32 v136, v136, v137
	ds_read_b128 v[54:57], v51 offset:14848
	ds_read_b128 v[58:61], v51 offset:14864
	s_waitcnt lgkmcnt(6)
	v_pk_mul_f32 v[112:113], v[70:71], v[86:87] op_sel_hi:[1,0]
	v_pk_mul_f32 v[120:121], v[70:71], v[86:87] op_sel:[0,1] op_sel_hi:[1,1]
	v_add_f32_dpp v134, v134, v134 quad_perm:[1,0,3,2] row_mask:0xf bank_mask:0xf bound_ctrl:1
	v_add_f32_dpp v136, v136, v136 quad_perm:[1,0,3,2] row_mask:0xf bank_mask:0xf bound_ctrl:1
	v_pk_mul_f32 v[114:115], v[72:73], v[86:87] op_sel_hi:[1,0]
	v_add_f32_dpp v134, v134, v134 quad_perm:[2,3,0,1] row_mask:0xf bank_mask:0xf bound_ctrl:1
	v_add_f32_dpp v136, v136, v136 quad_perm:[2,3,0,1] row_mask:0xf bank_mask:0xf bound_ctrl:1
	v_pk_mul_f32 v[122:123], v[72:73], v[86:87] op_sel:[0,1] op_sel_hi:[1,1]
	v_add_f32_dpp v134, v134, v134 row_half_mirror row_mask:0xf bank_mask:0xf bound_ctrl:1
	v_add_f32_dpp v136, v136, v136 row_half_mirror row_mask:0xf bank_mask:0xf bound_ctrl:1
	v_pk_mul_f32 v[116:117], v[74:75], v[86:87] op_sel_hi:[1,0]
	v_pk_mul_f32 v[124:125], v[74:75], v[86:87] op_sel:[0,1] op_sel_hi:[1,1]
	v_pk_mul_f32 v[118:119], v[76:77], v[86:87] op_sel_hi:[1,0]
	v_pk_mul_f32 v[126:127], v[76:77], v[86:87] op_sel:[0,1] op_sel_hi:[1,1]
	v_pk_fma_f32 v[112:113], v[12:13], v[62:63], v[112:113]
	v_pk_fma_f32 v[120:121], v[4:5], v[62:63], v[120:121]
	v_pk_fma_f32 v[114:115], v[14:15], v[64:65], v[114:115]
	v_pk_fma_f32 v[122:123], v[6:7], v[64:65], v[122:123]
	v_pk_fma_f32 v[116:117], v[8:9], v[66:67], v[116:117]
	v_pk_fma_f32 v[124:125], v[0:1], v[66:67], v[124:125]
	v_pk_fma_f32 v[118:119], v[10:11], v[68:69], v[118:119]
	v_pk_fma_f32 v[126:127], v[2:3], v[68:69], v[126:127]
	ds_read_b128 v[70:73], v51 offset:10752
	ds_read_b128 v[74:77], v51 offset:10768
	ds_read2_b32 v[86:87], v53 offset0:128 offset1:160
	ds_read_b128 v[62:65], v51 offset:6656
	ds_read_b128 v[66:69], v51 offset:6672
	v_mul_f32_e32 v138, v106, v14
	v_mul_f32_e32 v146, v106, v6
	v_fmac_f32_e32 v138, v107, v15
	v_fmac_f32_e32 v146, v107, v7
	v_fmac_f32_e32 v138, v104, v12
	v_fmac_f32_e32 v146, v104, v4
	v_fmac_f32_e32 v138, v105, v13
	v_fmac_f32_e32 v146, v105, v5
	v_fmac_f32_e32 v138, v108, v8
	v_fmac_f32_e32 v146, v108, v0
	v_fmac_f32_e32 v138, v109, v9
	v_fmac_f32_e32 v146, v109, v1
	v_fmac_f32_e32 v138, v110, v10
	v_fmac_f32_e32 v146, v110, v2
	v_fmac_f32_e32 v138, v111, v11
	v_fmac_f32_e32 v146, v111, v3
	s_waitcnt lgkmcnt(9)
	v_pk_fma_f32 v[12:13], v[78:79], v[134:135], v[112:113] op_sel_hi:[1,0,1] neg_lo:[0,1,0] neg_hi:[0,1,0]
	v_pk_fma_f32 v[4:5], v[78:79], v[136:137], v[120:121] op_sel_hi:[1,0,1] neg_lo:[0,1,0] neg_hi:[0,1,0]
	v_pk_fma_f32 v[14:15], v[80:81], v[134:135], v[114:115] op_sel_hi:[1,0,1] neg_lo:[0,1,0] neg_hi:[0,1,0]
	v_pk_fma_f32 v[6:7], v[80:81], v[136:137], v[122:123] op_sel_hi:[1,0,1] neg_lo:[0,1,0] neg_hi:[0,1,0]
	v_pk_fma_f32 v[8:9], v[82:83], v[134:135], v[116:117] op_sel_hi:[1,0,1] neg_lo:[0,1,0] neg_hi:[0,1,0]
	v_pk_fma_f32 v[0:1], v[82:83], v[136:137], v[124:125] op_sel_hi:[1,0,1] neg_lo:[0,1,0] neg_hi:[0,1,0]
	v_pk_fma_f32 v[10:11], v[84:85], v[134:135], v[118:119] op_sel_hi:[1,0,1] neg_lo:[0,1,0] neg_hi:[0,1,0]
	v_pk_fma_f32 v[2:3], v[84:85], v[136:137], v[126:127] op_sel_hi:[1,0,1] neg_lo:[0,1,0] neg_hi:[0,1,0]
	ds_read_b128 v[78:81], v51 offset:18944
	ds_read_b128 v[82:85], v51 offset:18960
	ds_read_b128 v[96:99], v51 offset:2560
	ds_read_b128 v[100:103], v51 offset:2576
	s_waitcnt lgkmcnt(9)
	v_pk_mul_f32 v[134:135], v[14:15], v[56:57]
	v_pk_mul_f32 v[136:137], v[6:7], v[56:57]
	v_pk_fma_f32 v[134:135], v[12:13], v[54:55], v[134:135]
	v_pk_fma_f32 v[136:137], v[4:5], v[54:55], v[136:137]
	v_pk_fma_f32 v[134:135], v[8:9], v[58:59], v[134:135]
	v_pk_fma_f32 v[136:137], v[0:1], v[58:59], v[136:137]
	v_pk_fma_f32 v[134:135], v[10:11], v[60:61], v[134:135]
	v_pk_fma_f32 v[136:137], v[2:3], v[60:61], v[136:137]
	v_add_f32_e32 v134, v134, v135
	v_add_f32_e32 v136, v136, v137
	ds_read_b128 v[54:57], v51 offset:15104
	ds_read_b128 v[58:61], v51 offset:15120
	s_waitcnt lgkmcnt(6)
	v_pk_mul_f32 v[112:113], v[70:71], v[86:87] op_sel_hi:[1,0]
	v_pk_mul_f32 v[120:121], v[70:71], v[86:87] op_sel:[0,1] op_sel_hi:[1,1]
	v_add_f32_dpp v134, v134, v134 quad_perm:[1,0,3,2] row_mask:0xf bank_mask:0xf bound_ctrl:1
	v_add_f32_dpp v136, v136, v136 quad_perm:[1,0,3,2] row_mask:0xf bank_mask:0xf bound_ctrl:1
	v_pk_mul_f32 v[114:115], v[72:73], v[86:87] op_sel_hi:[1,0]
	v_add_f32_dpp v134, v134, v134 quad_perm:[2,3,0,1] row_mask:0xf bank_mask:0xf bound_ctrl:1
	v_add_f32_dpp v136, v136, v136 quad_perm:[2,3,0,1] row_mask:0xf bank_mask:0xf bound_ctrl:1
	v_pk_mul_f32 v[122:123], v[72:73], v[86:87] op_sel:[0,1] op_sel_hi:[1,1]
	v_add_f32_dpp v134, v134, v134 row_half_mirror row_mask:0xf bank_mask:0xf bound_ctrl:1
	v_add_f32_dpp v136, v136, v136 row_half_mirror row_mask:0xf bank_mask:0xf bound_ctrl:1
	v_pk_mul_f32 v[116:117], v[74:75], v[86:87] op_sel_hi:[1,0]
	v_pk_mul_f32 v[124:125], v[74:75], v[86:87] op_sel:[0,1] op_sel_hi:[1,1]
	v_pk_mul_f32 v[118:119], v[76:77], v[86:87] op_sel_hi:[1,0]
	v_pk_mul_f32 v[126:127], v[76:77], v[86:87] op_sel:[0,1] op_sel_hi:[1,1]
	v_pk_fma_f32 v[112:113], v[12:13], v[62:63], v[112:113]
	v_pk_fma_f32 v[120:121], v[4:5], v[62:63], v[120:121]
	v_pk_fma_f32 v[114:115], v[14:15], v[64:65], v[114:115]
	v_pk_fma_f32 v[122:123], v[6:7], v[64:65], v[122:123]
	v_pk_fma_f32 v[116:117], v[8:9], v[66:67], v[116:117]
	v_pk_fma_f32 v[124:125], v[0:1], v[66:67], v[124:125]
	v_pk_fma_f32 v[118:119], v[10:11], v[68:69], v[118:119]
	v_pk_fma_f32 v[126:127], v[2:3], v[68:69], v[126:127]
	ds_read_b128 v[70:73], v51 offset:11008
	ds_read_b128 v[74:77], v51 offset:11024
	ds_read2_b32 v[86:87], v53 offset0:192 offset1:224
	ds_read_b128 v[62:65], v51 offset:6912
	ds_read_b128 v[66:69], v51 offset:6928
	v_mul_f32_e32 v139, v90, v14
	v_mul_f32_e32 v147, v90, v6
	v_fmac_f32_e32 v139, v91, v15
	v_fmac_f32_e32 v147, v91, v7
	v_fmac_f32_e32 v139, v88, v12
	v_fmac_f32_e32 v147, v88, v4
	v_fmac_f32_e32 v139, v89, v13
	v_fmac_f32_e32 v147, v89, v5
	v_fmac_f32_e32 v139, v92, v8
	v_fmac_f32_e32 v147, v92, v0
	v_fmac_f32_e32 v139, v93, v9
	v_fmac_f32_e32 v147, v93, v1
	v_fmac_f32_e32 v139, v94, v10
	v_fmac_f32_e32 v147, v94, v2
	v_fmac_f32_e32 v139, v95, v11
	v_fmac_f32_e32 v147, v95, v3
	s_waitcnt lgkmcnt(9)
	v_pk_fma_f32 v[12:13], v[78:79], v[134:135], v[112:113] op_sel_hi:[1,0,1] neg_lo:[0,1,0] neg_hi:[0,1,0]
	v_pk_fma_f32 v[4:5], v[78:79], v[136:137], v[120:121] op_sel_hi:[1,0,1] neg_lo:[0,1,0] neg_hi:[0,1,0]
	v_pk_fma_f32 v[14:15], v[80:81], v[134:135], v[114:115] op_sel_hi:[1,0,1] neg_lo:[0,1,0] neg_hi:[0,1,0]
	v_pk_fma_f32 v[6:7], v[80:81], v[136:137], v[122:123] op_sel_hi:[1,0,1] neg_lo:[0,1,0] neg_hi:[0,1,0]
	v_pk_fma_f32 v[8:9], v[82:83], v[134:135], v[116:117] op_sel_hi:[1,0,1] neg_lo:[0,1,0] neg_hi:[0,1,0]
	v_pk_fma_f32 v[0:1], v[82:83], v[136:137], v[124:125] op_sel_hi:[1,0,1] neg_lo:[0,1,0] neg_hi:[0,1,0]
	v_pk_fma_f32 v[10:11], v[84:85], v[134:135], v[118:119] op_sel_hi:[1,0,1] neg_lo:[0,1,0] neg_hi:[0,1,0]
	v_pk_fma_f32 v[2:3], v[84:85], v[136:137], v[126:127] op_sel_hi:[1,0,1] neg_lo:[0,1,0] neg_hi:[0,1,0]
	ds_read_b128 v[78:81], v51 offset:19200
	ds_read_b128 v[82:85], v51 offset:19216
	ds_read_b128 v[104:107], v51 offset:2816
	ds_read_b128 v[108:111], v51 offset:2832
	s_waitcnt lgkmcnt(9)
	v_pk_mul_f32 v[134:135], v[14:15], v[56:57]
	v_pk_mul_f32 v[136:137], v[6:7], v[56:57]
	v_pk_fma_f32 v[134:135], v[12:13], v[54:55], v[134:135]
	v_pk_fma_f32 v[136:137], v[4:5], v[54:55], v[136:137]
	v_pk_fma_f32 v[134:135], v[8:9], v[58:59], v[134:135]
	v_pk_fma_f32 v[136:137], v[0:1], v[58:59], v[136:137]
	v_pk_fma_f32 v[134:135], v[10:11], v[60:61], v[134:135]
	v_pk_fma_f32 v[136:137], v[2:3], v[60:61], v[136:137]
	v_add_f32_e32 v134, v134, v135
	v_add_f32_e32 v136, v136, v137
	ds_read_b128 v[54:57], v51 offset:15360
	ds_read_b128 v[58:61], v51 offset:15376
	s_waitcnt lgkmcnt(6)
	v_pk_mul_f32 v[112:113], v[70:71], v[86:87] op_sel_hi:[1,0]
	v_pk_mul_f32 v[120:121], v[70:71], v[86:87] op_sel:[0,1] op_sel_hi:[1,1]
	v_add_f32_dpp v134, v134, v134 quad_perm:[1,0,3,2] row_mask:0xf bank_mask:0xf bound_ctrl:1
	v_add_f32_dpp v136, v136, v136 quad_perm:[1,0,3,2] row_mask:0xf bank_mask:0xf bound_ctrl:1
	v_pk_mul_f32 v[114:115], v[72:73], v[86:87] op_sel_hi:[1,0]
	v_add_f32_dpp v134, v134, v134 quad_perm:[2,3,0,1] row_mask:0xf bank_mask:0xf bound_ctrl:1
	v_add_f32_dpp v136, v136, v136 quad_perm:[2,3,0,1] row_mask:0xf bank_mask:0xf bound_ctrl:1
	v_pk_mul_f32 v[122:123], v[72:73], v[86:87] op_sel:[0,1] op_sel_hi:[1,1]
	v_add_f32_dpp v134, v134, v134 row_half_mirror row_mask:0xf bank_mask:0xf bound_ctrl:1
	v_add_f32_dpp v136, v136, v136 row_half_mirror row_mask:0xf bank_mask:0xf bound_ctrl:1
	v_pk_mul_f32 v[116:117], v[74:75], v[86:87] op_sel_hi:[1,0]
	v_pk_mul_f32 v[124:125], v[74:75], v[86:87] op_sel:[0,1] op_sel_hi:[1,1]
	v_pk_mul_f32 v[118:119], v[76:77], v[86:87] op_sel_hi:[1,0]
	v_pk_mul_f32 v[126:127], v[76:77], v[86:87] op_sel:[0,1] op_sel_hi:[1,1]
	v_pk_fma_f32 v[112:113], v[12:13], v[62:63], v[112:113]
	v_pk_fma_f32 v[120:121], v[4:5], v[62:63], v[120:121]
	v_pk_fma_f32 v[114:115], v[14:15], v[64:65], v[114:115]
	v_pk_fma_f32 v[122:123], v[6:7], v[64:65], v[122:123]
	v_pk_fma_f32 v[116:117], v[8:9], v[66:67], v[116:117]
	v_pk_fma_f32 v[124:125], v[0:1], v[66:67], v[124:125]
	v_pk_fma_f32 v[118:119], v[10:11], v[68:69], v[118:119]
	v_pk_fma_f32 v[126:127], v[2:3], v[68:69], v[126:127]
	v_add_u32_e32 v53, 0x400, v53
	ds_read_b128 v[70:73], v51 offset:11264
	ds_read_b128 v[74:77], v51 offset:11280
	ds_read2_b32 v[86:87], v53 offset0:0 offset1:32
	ds_read_b128 v[62:65], v51 offset:7168
	ds_read_b128 v[66:69], v51 offset:7184
	v_mul_f32_e32 v140, v98, v14
	v_mul_f32_e32 v148, v98, v6
	v_fmac_f32_e32 v140, v99, v15
	v_fmac_f32_e32 v148, v99, v7
	v_fmac_f32_e32 v140, v96, v12
	v_fmac_f32_e32 v148, v96, v4
	v_fmac_f32_e32 v140, v97, v13
	v_fmac_f32_e32 v148, v97, v5
	v_fmac_f32_e32 v140, v100, v8
	v_fmac_f32_e32 v148, v100, v0
	v_fmac_f32_e32 v140, v101, v9
	v_fmac_f32_e32 v148, v101, v1
	v_fmac_f32_e32 v140, v102, v10
	v_fmac_f32_e32 v148, v102, v2
	v_fmac_f32_e32 v140, v103, v11
	v_fmac_f32_e32 v148, v103, v3
	s_waitcnt lgkmcnt(9)
	v_pk_fma_f32 v[12:13], v[78:79], v[134:135], v[112:113] op_sel_hi:[1,0,1] neg_lo:[0,1,0] neg_hi:[0,1,0]
	v_pk_fma_f32 v[4:5], v[78:79], v[136:137], v[120:121] op_sel_hi:[1,0,1] neg_lo:[0,1,0] neg_hi:[0,1,0]
	v_pk_fma_f32 v[14:15], v[80:81], v[134:135], v[114:115] op_sel_hi:[1,0,1] neg_lo:[0,1,0] neg_hi:[0,1,0]
	v_pk_fma_f32 v[6:7], v[80:81], v[136:137], v[122:123] op_sel_hi:[1,0,1] neg_lo:[0,1,0] neg_hi:[0,1,0]
	v_pk_fma_f32 v[8:9], v[82:83], v[134:135], v[116:117] op_sel_hi:[1,0,1] neg_lo:[0,1,0] neg_hi:[0,1,0]
	v_pk_fma_f32 v[0:1], v[82:83], v[136:137], v[124:125] op_sel_hi:[1,0,1] neg_lo:[0,1,0] neg_hi:[0,1,0]
	v_pk_fma_f32 v[10:11], v[84:85], v[134:135], v[118:119] op_sel_hi:[1,0,1] neg_lo:[0,1,0] neg_hi:[0,1,0]
	v_pk_fma_f32 v[2:3], v[84:85], v[136:137], v[126:127] op_sel_hi:[1,0,1] neg_lo:[0,1,0] neg_hi:[0,1,0]
	ds_read_b128 v[78:81], v51 offset:19456
	ds_read_b128 v[82:85], v51 offset:19472
	ds_read_b128 v[88:91], v51 offset:3072
	ds_read_b128 v[92:95], v51 offset:3088
	s_waitcnt lgkmcnt(9)
	v_pk_mul_f32 v[134:135], v[14:15], v[56:57]
	v_pk_mul_f32 v[136:137], v[6:7], v[56:57]
	v_pk_fma_f32 v[134:135], v[12:13], v[54:55], v[134:135]
	v_pk_fma_f32 v[136:137], v[4:5], v[54:55], v[136:137]
	v_pk_fma_f32 v[134:135], v[8:9], v[58:59], v[134:135]
	v_pk_fma_f32 v[136:137], v[0:1], v[58:59], v[136:137]
	v_pk_fma_f32 v[134:135], v[10:11], v[60:61], v[134:135]
	v_pk_fma_f32 v[136:137], v[2:3], v[60:61], v[136:137]
	v_add_f32_e32 v134, v134, v135
	v_add_f32_e32 v136, v136, v137
	ds_read_b128 v[54:57], v51 offset:15616
	ds_read_b128 v[58:61], v51 offset:15632
	s_waitcnt lgkmcnt(6)
	v_pk_mul_f32 v[112:113], v[70:71], v[86:87] op_sel_hi:[1,0]
	v_pk_mul_f32 v[120:121], v[70:71], v[86:87] op_sel:[0,1] op_sel_hi:[1,1]
	v_add_f32_dpp v134, v134, v134 quad_perm:[1,0,3,2] row_mask:0xf bank_mask:0xf bound_ctrl:1
	v_add_f32_dpp v136, v136, v136 quad_perm:[1,0,3,2] row_mask:0xf bank_mask:0xf bound_ctrl:1
	v_pk_mul_f32 v[114:115], v[72:73], v[86:87] op_sel_hi:[1,0]
	v_add_f32_dpp v134, v134, v134 quad_perm:[2,3,0,1] row_mask:0xf bank_mask:0xf bound_ctrl:1
	v_add_f32_dpp v136, v136, v136 quad_perm:[2,3,0,1] row_mask:0xf bank_mask:0xf bound_ctrl:1
	v_pk_mul_f32 v[122:123], v[72:73], v[86:87] op_sel:[0,1] op_sel_hi:[1,1]
	v_add_f32_dpp v134, v134, v134 row_half_mirror row_mask:0xf bank_mask:0xf bound_ctrl:1
	v_add_f32_dpp v136, v136, v136 row_half_mirror row_mask:0xf bank_mask:0xf bound_ctrl:1
	v_pk_mul_f32 v[116:117], v[74:75], v[86:87] op_sel_hi:[1,0]
	v_pk_mul_f32 v[124:125], v[74:75], v[86:87] op_sel:[0,1] op_sel_hi:[1,1]
	v_pk_mul_f32 v[118:119], v[76:77], v[86:87] op_sel_hi:[1,0]
	v_pk_mul_f32 v[126:127], v[76:77], v[86:87] op_sel:[0,1] op_sel_hi:[1,1]
	v_pk_fma_f32 v[112:113], v[12:13], v[62:63], v[112:113]
	v_pk_fma_f32 v[120:121], v[4:5], v[62:63], v[120:121]
	v_pk_fma_f32 v[114:115], v[14:15], v[64:65], v[114:115]
	v_pk_fma_f32 v[122:123], v[6:7], v[64:65], v[122:123]
	v_pk_fma_f32 v[116:117], v[8:9], v[66:67], v[116:117]
	v_pk_fma_f32 v[124:125], v[0:1], v[66:67], v[124:125]
	v_pk_fma_f32 v[118:119], v[10:11], v[68:69], v[118:119]
	v_pk_fma_f32 v[126:127], v[2:3], v[68:69], v[126:127]
	ds_read_b128 v[70:73], v51 offset:11520
	ds_read_b128 v[74:77], v51 offset:11536
	ds_read2_b32 v[86:87], v53 offset0:64 offset1:96
	ds_read_b128 v[62:65], v51 offset:7424
	ds_read_b128 v[66:69], v51 offset:7440
	v_mul_f32_e32 v141, v106, v14
	v_mul_f32_e32 v149, v106, v6
	v_fmac_f32_e32 v141, v107, v15
	v_fmac_f32_e32 v149, v107, v7
	v_fmac_f32_e32 v141, v104, v12
	v_fmac_f32_e32 v149, v104, v4
	v_fmac_f32_e32 v141, v105, v13
	v_fmac_f32_e32 v149, v105, v5
	v_fmac_f32_e32 v141, v108, v8
	v_fmac_f32_e32 v149, v108, v0
	v_fmac_f32_e32 v141, v109, v9
	v_fmac_f32_e32 v149, v109, v1
	v_fmac_f32_e32 v141, v110, v10
	v_fmac_f32_e32 v149, v110, v2
	v_fmac_f32_e32 v141, v111, v11
	v_fmac_f32_e32 v149, v111, v3
	s_waitcnt lgkmcnt(9)
	v_pk_fma_f32 v[12:13], v[78:79], v[134:135], v[112:113] op_sel_hi:[1,0,1] neg_lo:[0,1,0] neg_hi:[0,1,0]
	v_pk_fma_f32 v[4:5], v[78:79], v[136:137], v[120:121] op_sel_hi:[1,0,1] neg_lo:[0,1,0] neg_hi:[0,1,0]
	v_pk_fma_f32 v[14:15], v[80:81], v[134:135], v[114:115] op_sel_hi:[1,0,1] neg_lo:[0,1,0] neg_hi:[0,1,0]
	v_pk_fma_f32 v[6:7], v[80:81], v[136:137], v[122:123] op_sel_hi:[1,0,1] neg_lo:[0,1,0] neg_hi:[0,1,0]
	v_pk_fma_f32 v[8:9], v[82:83], v[134:135], v[116:117] op_sel_hi:[1,0,1] neg_lo:[0,1,0] neg_hi:[0,1,0]
	v_pk_fma_f32 v[0:1], v[82:83], v[136:137], v[124:125] op_sel_hi:[1,0,1] neg_lo:[0,1,0] neg_hi:[0,1,0]
	v_pk_fma_f32 v[10:11], v[84:85], v[134:135], v[118:119] op_sel_hi:[1,0,1] neg_lo:[0,1,0] neg_hi:[0,1,0]
	v_pk_fma_f32 v[2:3], v[84:85], v[136:137], v[126:127] op_sel_hi:[1,0,1] neg_lo:[0,1,0] neg_hi:[0,1,0]
	ds_read_b128 v[78:81], v51 offset:19712
	ds_read_b128 v[82:85], v51 offset:19728
	ds_read_b128 v[96:99], v51 offset:3328
	ds_read_b128 v[100:103], v51 offset:3344
	s_waitcnt lgkmcnt(9)
	v_pk_mul_f32 v[134:135], v[14:15], v[56:57]
	v_pk_mul_f32 v[136:137], v[6:7], v[56:57]
	v_pk_fma_f32 v[134:135], v[12:13], v[54:55], v[134:135]
	v_pk_fma_f32 v[136:137], v[4:5], v[54:55], v[136:137]
	v_pk_fma_f32 v[134:135], v[8:9], v[58:59], v[134:135]
	v_pk_fma_f32 v[136:137], v[0:1], v[58:59], v[136:137]
	v_pk_fma_f32 v[134:135], v[10:11], v[60:61], v[134:135]
	v_pk_fma_f32 v[136:137], v[2:3], v[60:61], v[136:137]
	v_add_f32_e32 v134, v134, v135
	v_add_f32_e32 v136, v136, v137
	ds_read_b128 v[54:57], v51 offset:15872
	ds_read_b128 v[58:61], v51 offset:15888
	s_waitcnt lgkmcnt(6)
	v_pk_mul_f32 v[112:113], v[70:71], v[86:87] op_sel_hi:[1,0]
	v_pk_mul_f32 v[120:121], v[70:71], v[86:87] op_sel:[0,1] op_sel_hi:[1,1]
	v_add_f32_dpp v134, v134, v134 quad_perm:[1,0,3,2] row_mask:0xf bank_mask:0xf bound_ctrl:1
	v_add_f32_dpp v136, v136, v136 quad_perm:[1,0,3,2] row_mask:0xf bank_mask:0xf bound_ctrl:1
	v_pk_mul_f32 v[114:115], v[72:73], v[86:87] op_sel_hi:[1,0]
	v_add_f32_dpp v134, v134, v134 quad_perm:[2,3,0,1] row_mask:0xf bank_mask:0xf bound_ctrl:1
	v_add_f32_dpp v136, v136, v136 quad_perm:[2,3,0,1] row_mask:0xf bank_mask:0xf bound_ctrl:1
	v_pk_mul_f32 v[122:123], v[72:73], v[86:87] op_sel:[0,1] op_sel_hi:[1,1]
	v_add_f32_dpp v134, v134, v134 row_half_mirror row_mask:0xf bank_mask:0xf bound_ctrl:1
	v_add_f32_dpp v136, v136, v136 row_half_mirror row_mask:0xf bank_mask:0xf bound_ctrl:1
	v_pk_mul_f32 v[116:117], v[74:75], v[86:87] op_sel_hi:[1,0]
	v_pk_mul_f32 v[124:125], v[74:75], v[86:87] op_sel:[0,1] op_sel_hi:[1,1]
	v_pk_mul_f32 v[118:119], v[76:77], v[86:87] op_sel_hi:[1,0]
	v_pk_mul_f32 v[126:127], v[76:77], v[86:87] op_sel:[0,1] op_sel_hi:[1,1]
	v_pk_fma_f32 v[112:113], v[12:13], v[62:63], v[112:113]
	v_pk_fma_f32 v[120:121], v[4:5], v[62:63], v[120:121]
	v_pk_fma_f32 v[114:115], v[14:15], v[64:65], v[114:115]
	v_pk_fma_f32 v[122:123], v[6:7], v[64:65], v[122:123]
	v_pk_fma_f32 v[116:117], v[8:9], v[66:67], v[116:117]
	v_pk_fma_f32 v[124:125], v[0:1], v[66:67], v[124:125]
	v_pk_fma_f32 v[118:119], v[10:11], v[68:69], v[118:119]
	v_pk_fma_f32 v[126:127], v[2:3], v[68:69], v[126:127]
	ds_read_b128 v[70:73], v51 offset:11776
	ds_read_b128 v[74:77], v51 offset:11792
	ds_read2_b32 v[86:87], v53 offset0:128 offset1:160
	ds_read_b128 v[62:65], v51 offset:7680
	ds_read_b128 v[66:69], v51 offset:7696
	v_mul_f32_e32 v142, v90, v14
	v_mul_f32_e32 v150, v90, v6
	v_fmac_f32_e32 v142, v91, v15
	v_fmac_f32_e32 v150, v91, v7
	v_fmac_f32_e32 v142, v88, v12
	v_fmac_f32_e32 v150, v88, v4
	v_fmac_f32_e32 v142, v89, v13
	v_fmac_f32_e32 v150, v89, v5
	v_fmac_f32_e32 v142, v92, v8
	v_fmac_f32_e32 v150, v92, v0
	v_fmac_f32_e32 v142, v93, v9
	v_fmac_f32_e32 v150, v93, v1
	v_fmac_f32_e32 v142, v94, v10
	v_fmac_f32_e32 v150, v94, v2
	v_fmac_f32_e32 v142, v95, v11
	v_fmac_f32_e32 v150, v95, v3
	s_waitcnt lgkmcnt(9)
	v_pk_fma_f32 v[12:13], v[78:79], v[134:135], v[112:113] op_sel_hi:[1,0,1] neg_lo:[0,1,0] neg_hi:[0,1,0]
	v_pk_fma_f32 v[4:5], v[78:79], v[136:137], v[120:121] op_sel_hi:[1,0,1] neg_lo:[0,1,0] neg_hi:[0,1,0]
	v_pk_fma_f32 v[14:15], v[80:81], v[134:135], v[114:115] op_sel_hi:[1,0,1] neg_lo:[0,1,0] neg_hi:[0,1,0]
	v_pk_fma_f32 v[6:7], v[80:81], v[136:137], v[122:123] op_sel_hi:[1,0,1] neg_lo:[0,1,0] neg_hi:[0,1,0]
	v_pk_fma_f32 v[8:9], v[82:83], v[134:135], v[116:117] op_sel_hi:[1,0,1] neg_lo:[0,1,0] neg_hi:[0,1,0]
	v_pk_fma_f32 v[0:1], v[82:83], v[136:137], v[124:125] op_sel_hi:[1,0,1] neg_lo:[0,1,0] neg_hi:[0,1,0]
	v_pk_fma_f32 v[10:11], v[84:85], v[134:135], v[118:119] op_sel_hi:[1,0,1] neg_lo:[0,1,0] neg_hi:[0,1,0]
	v_pk_fma_f32 v[2:3], v[84:85], v[136:137], v[126:127] op_sel_hi:[1,0,1] neg_lo:[0,1,0] neg_hi:[0,1,0]
	ds_read_b128 v[78:81], v51 offset:19968
	ds_read_b128 v[82:85], v51 offset:19984
	ds_read_b128 v[104:107], v51 offset:3584
	ds_read_b128 v[108:111], v51 offset:3600
	s_waitcnt lgkmcnt(9)
	v_pk_mul_f32 v[134:135], v[14:15], v[56:57]
	v_pk_mul_f32 v[136:137], v[6:7], v[56:57]
	v_pk_fma_f32 v[134:135], v[12:13], v[54:55], v[134:135]
	v_pk_fma_f32 v[136:137], v[4:5], v[54:55], v[136:137]
	v_pk_fma_f32 v[134:135], v[8:9], v[58:59], v[134:135]
	v_pk_fma_f32 v[136:137], v[0:1], v[58:59], v[136:137]
	v_pk_fma_f32 v[134:135], v[10:11], v[60:61], v[134:135]
	v_pk_fma_f32 v[136:137], v[2:3], v[60:61], v[136:137]
	v_add_f32_e32 v134, v134, v135
	v_add_f32_e32 v136, v136, v137
	ds_read_b128 v[54:57], v51 offset:16128
	ds_read_b128 v[58:61], v51 offset:16144
	s_waitcnt lgkmcnt(6)
	v_pk_mul_f32 v[112:113], v[70:71], v[86:87] op_sel_hi:[1,0]
	v_pk_mul_f32 v[120:121], v[70:71], v[86:87] op_sel:[0,1] op_sel_hi:[1,1]
	v_add_f32_dpp v134, v134, v134 quad_perm:[1,0,3,2] row_mask:0xf bank_mask:0xf bound_ctrl:1
	v_add_f32_dpp v136, v136, v136 quad_perm:[1,0,3,2] row_mask:0xf bank_mask:0xf bound_ctrl:1
	v_pk_mul_f32 v[114:115], v[72:73], v[86:87] op_sel_hi:[1,0]
	v_add_f32_dpp v134, v134, v134 quad_perm:[2,3,0,1] row_mask:0xf bank_mask:0xf bound_ctrl:1
	v_add_f32_dpp v136, v136, v136 quad_perm:[2,3,0,1] row_mask:0xf bank_mask:0xf bound_ctrl:1
	v_pk_mul_f32 v[122:123], v[72:73], v[86:87] op_sel:[0,1] op_sel_hi:[1,1]
	v_add_f32_dpp v134, v134, v134 row_half_mirror row_mask:0xf bank_mask:0xf bound_ctrl:1
	v_add_f32_dpp v136, v136, v136 row_half_mirror row_mask:0xf bank_mask:0xf bound_ctrl:1
	v_pk_mul_f32 v[116:117], v[74:75], v[86:87] op_sel_hi:[1,0]
	v_pk_mul_f32 v[124:125], v[74:75], v[86:87] op_sel:[0,1] op_sel_hi:[1,1]
	v_pk_mul_f32 v[118:119], v[76:77], v[86:87] op_sel_hi:[1,0]
	v_pk_mul_f32 v[126:127], v[76:77], v[86:87] op_sel:[0,1] op_sel_hi:[1,1]
	v_pk_fma_f32 v[112:113], v[12:13], v[62:63], v[112:113]
	v_pk_fma_f32 v[120:121], v[4:5], v[62:63], v[120:121]
	v_pk_fma_f32 v[114:115], v[14:15], v[64:65], v[114:115]
	v_pk_fma_f32 v[122:123], v[6:7], v[64:65], v[122:123]
	v_pk_fma_f32 v[116:117], v[8:9], v[66:67], v[116:117]
	v_pk_fma_f32 v[124:125], v[0:1], v[66:67], v[124:125]
	v_pk_fma_f32 v[118:119], v[10:11], v[68:69], v[118:119]
	v_pk_fma_f32 v[126:127], v[2:3], v[68:69], v[126:127]
	ds_read_b128 v[70:73], v51 offset:12032
	ds_read_b128 v[74:77], v51 offset:12048
	ds_read2_b32 v[86:87], v53 offset0:192 offset1:224
	ds_read_b128 v[62:65], v51 offset:7936
	ds_read_b128 v[66:69], v51 offset:7952
	v_mul_f32_e32 v143, v98, v14
	v_mul_f32_e32 v151, v98, v6
	v_fmac_f32_e32 v143, v99, v15
	v_fmac_f32_e32 v151, v99, v7
	v_fmac_f32_e32 v143, v96, v12
	v_fmac_f32_e32 v151, v96, v4
	v_fmac_f32_e32 v143, v97, v13
	v_fmac_f32_e32 v151, v97, v5
	v_fmac_f32_e32 v143, v100, v8
	v_fmac_f32_e32 v151, v100, v0
	v_fmac_f32_e32 v143, v101, v9
	v_fmac_f32_e32 v151, v101, v1
	v_fmac_f32_e32 v143, v102, v10
	v_fmac_f32_e32 v151, v102, v2
	v_fmac_f32_e32 v143, v103, v11
	v_fmac_f32_e32 v151, v103, v3
	s_waitcnt lgkmcnt(9)
	v_pk_fma_f32 v[12:13], v[78:79], v[134:135], v[112:113] op_sel_hi:[1,0,1] neg_lo:[0,1,0] neg_hi:[0,1,0]
	v_pk_fma_f32 v[4:5], v[78:79], v[136:137], v[120:121] op_sel_hi:[1,0,1] neg_lo:[0,1,0] neg_hi:[0,1,0]
	v_pk_fma_f32 v[14:15], v[80:81], v[134:135], v[114:115] op_sel_hi:[1,0,1] neg_lo:[0,1,0] neg_hi:[0,1,0]
	v_pk_fma_f32 v[6:7], v[80:81], v[136:137], v[122:123] op_sel_hi:[1,0,1] neg_lo:[0,1,0] neg_hi:[0,1,0]
	v_pk_fma_f32 v[8:9], v[82:83], v[134:135], v[116:117] op_sel_hi:[1,0,1] neg_lo:[0,1,0] neg_hi:[0,1,0]
	v_pk_fma_f32 v[0:1], v[82:83], v[136:137], v[124:125] op_sel_hi:[1,0,1] neg_lo:[0,1,0] neg_hi:[0,1,0]
	v_pk_fma_f32 v[10:11], v[84:85], v[134:135], v[118:119] op_sel_hi:[1,0,1] neg_lo:[0,1,0] neg_hi:[0,1,0]
	v_pk_fma_f32 v[2:3], v[84:85], v[136:137], v[126:127] op_sel_hi:[1,0,1] neg_lo:[0,1,0] neg_hi:[0,1,0]
	ds_read_b128 v[78:81], v51 offset:20224
	ds_read_b128 v[82:85], v51 offset:20240
	ds_read_b128 v[88:91], v51 offset:3840
	ds_read_b128 v[92:95], v51 offset:3856
	s_waitcnt lgkmcnt(9)
	v_pk_mul_f32 v[134:135], v[14:15], v[56:57]
	v_pk_mul_f32 v[136:137], v[6:7], v[56:57]
	v_pk_fma_f32 v[134:135], v[12:13], v[54:55], v[134:135]
	v_pk_fma_f32 v[136:137], v[4:5], v[54:55], v[136:137]
	v_pk_fma_f32 v[134:135], v[8:9], v[58:59], v[134:135]
	v_pk_fma_f32 v[136:137], v[0:1], v[58:59], v[136:137]
	v_pk_fma_f32 v[134:135], v[10:11], v[60:61], v[134:135]
	v_pk_fma_f32 v[136:137], v[2:3], v[60:61], v[136:137]
	v_add_f32_e32 v134, v134, v135
	v_add_f32_e32 v136, v136, v137
	s_waitcnt lgkmcnt(4)
	v_pk_mul_f32 v[112:113], v[70:71], v[86:87] op_sel_hi:[1,0]
	v_pk_mul_f32 v[120:121], v[70:71], v[86:87] op_sel:[0,1] op_sel_hi:[1,1]
	v_add_f32_dpp v134, v134, v134 quad_perm:[1,0,3,2] row_mask:0xf bank_mask:0xf bound_ctrl:1
	v_add_f32_dpp v136, v136, v136 quad_perm:[1,0,3,2] row_mask:0xf bank_mask:0xf bound_ctrl:1
	v_pk_mul_f32 v[114:115], v[72:73], v[86:87] op_sel_hi:[1,0]
	v_add_f32_dpp v134, v134, v134 quad_perm:[2,3,0,1] row_mask:0xf bank_mask:0xf bound_ctrl:1
	v_add_f32_dpp v136, v136, v136 quad_perm:[2,3,0,1] row_mask:0xf bank_mask:0xf bound_ctrl:1
	v_pk_mul_f32 v[122:123], v[72:73], v[86:87] op_sel:[0,1] op_sel_hi:[1,1]
	v_add_f32_dpp v134, v134, v134 row_half_mirror row_mask:0xf bank_mask:0xf bound_ctrl:1
	v_add_f32_dpp v136, v136, v136 row_half_mirror row_mask:0xf bank_mask:0xf bound_ctrl:1
	v_pk_mul_f32 v[116:117], v[74:75], v[86:87] op_sel_hi:[1,0]
	v_pk_mul_f32 v[124:125], v[74:75], v[86:87] op_sel:[0,1] op_sel_hi:[1,1]
	v_pk_mul_f32 v[118:119], v[76:77], v[86:87] op_sel_hi:[1,0]
	v_pk_mul_f32 v[126:127], v[76:77], v[86:87] op_sel:[0,1] op_sel_hi:[1,1]
	v_pk_fma_f32 v[112:113], v[12:13], v[62:63], v[112:113]
	v_pk_fma_f32 v[120:121], v[4:5], v[62:63], v[120:121]
	v_pk_fma_f32 v[114:115], v[14:15], v[64:65], v[114:115]
	v_pk_fma_f32 v[122:123], v[6:7], v[64:65], v[122:123]
	v_pk_fma_f32 v[116:117], v[8:9], v[66:67], v[116:117]
	v_pk_fma_f32 v[124:125], v[0:1], v[66:67], v[124:125]
	v_pk_fma_f32 v[118:119], v[10:11], v[68:69], v[118:119]
	v_pk_fma_f32 v[126:127], v[2:3], v[68:69], v[126:127]
	s_waitcnt lgkmcnt(11)
	v_mul_f32_e32 v144, v106, v14
	v_mul_f32_e32 v152, v106, v6
	v_fmac_f32_e32 v144, v107, v15
	v_fmac_f32_e32 v152, v107, v7
	v_fmac_f32_e32 v144, v104, v12
	v_fmac_f32_e32 v152, v104, v4
	v_fmac_f32_e32 v144, v105, v13
	v_fmac_f32_e32 v152, v105, v5
	v_fmac_f32_e32 v144, v108, v8
	v_fmac_f32_e32 v152, v108, v0
	v_fmac_f32_e32 v144, v109, v9
	v_fmac_f32_e32 v152, v109, v1
	v_fmac_f32_e32 v144, v110, v10
	v_fmac_f32_e32 v152, v110, v2
	v_fmac_f32_e32 v144, v111, v11
	v_fmac_f32_e32 v152, v111, v3
	s_waitcnt lgkmcnt(2)
	v_pk_fma_f32 v[12:13], v[78:79], v[134:135], v[112:113] op_sel_hi:[1,0,1] neg_lo:[0,1,0] neg_hi:[0,1,0]
	v_pk_fma_f32 v[4:5], v[78:79], v[136:137], v[120:121] op_sel_hi:[1,0,1] neg_lo:[0,1,0] neg_hi:[0,1,0]
	v_pk_fma_f32 v[14:15], v[80:81], v[134:135], v[114:115] op_sel_hi:[1,0,1] neg_lo:[0,1,0] neg_hi:[0,1,0]
	v_pk_fma_f32 v[6:7], v[80:81], v[136:137], v[122:123] op_sel_hi:[1,0,1] neg_lo:[0,1,0] neg_hi:[0,1,0]
	v_pk_fma_f32 v[8:9], v[82:83], v[134:135], v[116:117] op_sel_hi:[1,0,1] neg_lo:[0,1,0] neg_hi:[0,1,0]
	v_pk_fma_f32 v[0:1], v[82:83], v[136:137], v[124:125] op_sel_hi:[1,0,1] neg_lo:[0,1,0] neg_hi:[0,1,0]
	v_pk_fma_f32 v[10:11], v[84:85], v[134:135], v[118:119] op_sel_hi:[1,0,1] neg_lo:[0,1,0] neg_hi:[0,1,0]
	v_pk_fma_f32 v[2:3], v[84:85], v[136:137], v[126:127] op_sel_hi:[1,0,1] neg_lo:[0,1,0] neg_hi:[0,1,0]
	s_waitcnt lgkmcnt(0)
	v_mul_f32_e32 v145, v90, v14
	v_mul_f32_e32 v153, v90, v6
	v_fmac_f32_e32 v145, v91, v15
	v_fmac_f32_e32 v153, v91, v7
	v_fmac_f32_e32 v145, v88, v12
	v_fmac_f32_e32 v153, v88, v4
	v_fmac_f32_e32 v145, v89, v13
	v_fmac_f32_e32 v153, v89, v5
	v_fmac_f32_e32 v145, v92, v8
	v_fmac_f32_e32 v153, v92, v0
	v_fmac_f32_e32 v145, v93, v9
	v_fmac_f32_e32 v153, v93, v1
	v_fmac_f32_e32 v145, v94, v10
	v_fmac_f32_e32 v153, v94, v2
	v_fmac_f32_e32 v145, v95, v11
	v_fmac_f32_e32 v153, v95, v3
	v_cndmask_b32_e64 v112, v138, v139, s[4:5]
	v_cndmask_b32_e64 v113, v139, v138, s[4:5]
	v_cndmask_b32_e64 v114, v140, v141, s[4:5]
	v_cndmask_b32_e64 v115, v141, v140, s[4:5]
	s_nop 0
	v_add_f32_dpp v138, v113, v112 quad_perm:[1,0,3,2] row_mask:0xf bank_mask:0xf bound_ctrl:1
	v_add_f32_dpp v140, v115, v114 quad_perm:[1,0,3,2] row_mask:0xf bank_mask:0xf bound_ctrl:1
	v_cndmask_b32_e64 v112, v142, v143, s[4:5]
	v_cndmask_b32_e64 v113, v143, v142, s[4:5]
	v_cndmask_b32_e64 v114, v144, v145, s[4:5]
	v_cndmask_b32_e64 v115, v145, v144, s[4:5]
	s_nop 0
	v_add_f32_dpp v142, v113, v112 quad_perm:[1,0,3,2] row_mask:0xf bank_mask:0xf bound_ctrl:1
	v_add_f32_dpp v144, v115, v114 quad_perm:[1,0,3,2] row_mask:0xf bank_mask:0xf bound_ctrl:1
	v_cndmask_b32_e64 v112, v138, v140, s[6:7]
	v_cndmask_b32_e64 v113, v140, v138, s[6:7]
	v_cndmask_b32_e64 v114, v142, v144, s[6:7]
	v_cndmask_b32_e64 v115, v144, v142, s[6:7]
	s_nop 0
	v_add_f32_dpp v138, v113, v112 quad_perm:[2,3,0,1] row_mask:0xf bank_mask:0xf bound_ctrl:1
	v_add_f32_dpp v142, v115, v114 quad_perm:[2,3,0,1] row_mask:0xf bank_mask:0xf bound_ctrl:1
	s_nop 1
	v_add_f32_dpp v156, v138, v138 row_shl:4 row_mask:0xf bank_mask:0x5 bound_ctrl:1
	s_nop 1
	v_add_f32_dpp v156, v142, v142 row_shr:4 row_mask:0xf bank_mask:0xa bound_ctrl:1
	v_cndmask_b32_e64 v112, v146, v147, s[4:5]
	v_cndmask_b32_e64 v113, v147, v146, s[4:5]
	v_cndmask_b32_e64 v114, v148, v149, s[4:5]
	v_cndmask_b32_e64 v115, v149, v148, s[4:5]
	s_nop 0
	v_add_f32_dpp v146, v113, v112 quad_perm:[1,0,3,2] row_mask:0xf bank_mask:0xf bound_ctrl:1
	v_add_f32_dpp v148, v115, v114 quad_perm:[1,0,3,2] row_mask:0xf bank_mask:0xf bound_ctrl:1
	v_cndmask_b32_e64 v112, v150, v151, s[4:5]
	v_cndmask_b32_e64 v113, v151, v150, s[4:5]
	v_cndmask_b32_e64 v114, v152, v153, s[4:5]
	v_cndmask_b32_e64 v115, v153, v152, s[4:5]
	s_nop 0
	v_add_f32_dpp v150, v113, v112 quad_perm:[1,0,3,2] row_mask:0xf bank_mask:0xf bound_ctrl:1
	v_add_f32_dpp v152, v115, v114 quad_perm:[1,0,3,2] row_mask:0xf bank_mask:0xf bound_ctrl:1
	v_cndmask_b32_e64 v112, v146, v148, s[6:7]
	v_cndmask_b32_e64 v113, v148, v146, s[6:7]
	v_cndmask_b32_e64 v114, v150, v152, s[6:7]
	v_cndmask_b32_e64 v115, v152, v150, s[6:7]
	s_nop 0
	v_add_f32_dpp v146, v113, v112 quad_perm:[2,3,0,1] row_mask:0xf bank_mask:0xf bound_ctrl:1
	v_add_f32_dpp v150, v115, v114 quad_perm:[2,3,0,1] row_mask:0xf bank_mask:0xf bound_ctrl:1
	s_nop 1
	v_add_f32_dpp v157, v146, v146 row_shl:4 row_mask:0xf bank_mask:0x5 bound_ctrl:1
	s_nop 1
	v_add_f32_dpp v157, v150, v150 row_shr:4 row_mask:0xf bank_mask:0xa bound_ctrl:1
	s_andn2_b64 vcc, exec, s[18:19]
	v_add_u32_e32 v56, 8, v17
	v_add_u32_e32 v52, s24, v46
	v_cndmask_b32_e64 v56, v56, v52, s[36:37]
	v_add_u32_e32 v52, 8, v52
	v_add_lshl_u32 v128, v56, s20, 10
	v_cndmask_b32_e64 v52, v17, v52, s[36:37]
	v_lshl_add_u64 v[56:57], v[42:43], 0, v[128:129]
	v_add_lshl_u32 v128, v52, s20, 10
	v_lshl_add_u64 v[52:53], v[42:43], 0, v[128:129]
	global_store_dword v[56:57], v154, off
	global_store_dword v[56:57], v155, off offset:128
	global_store_dword v[52:53], v156, off
	global_store_dword v[52:53], v157, off offset:128
	s_cbranch_vccnz .LBB0_422
	s_bitcmp1_b32 s25, 0
	s_cselect_b32 s18, 0x6000, 0
	s_add_i32 s18, s78, s18
	s_waitcnt vmcnt(9)
	v_lshlrev_b32_e32 v52, 16, v18
	v_and_b32_e32 v53, 0xffff0000, v18
	v_lshlrev_b32_e32 v54, 16, v19
	v_and_b32_e32 v55, 0xffff0000, v19
	v_lshl_add_u32 v51, v45, 4, s18
	ds_write_b128 v51, v[52:55]
	s_waitcnt vmcnt(8)
	v_lshlrev_b32_e32 v52, 16, v20
	v_and_b32_e32 v53, 0xffff0000, v20
	v_lshlrev_b32_e32 v54, 16, v21
	v_and_b32_e32 v55, 0xffff0000, v21
	ds_write_b128 v51, v[52:55] offset:4096
	s_waitcnt vmcnt(7)
	v_lshlrev_b32_e32 v52, 16, v22
	v_and_b32_e32 v53, 0xffff0000, v22
	v_lshlrev_b32_e32 v54, 16, v23
	v_and_b32_e32 v55, 0xffff0000, v23
	ds_write_b128 v51, v[52:55] offset:8192
	s_waitcnt vmcnt(6)
	v_lshlrev_b32_e32 v52, 16, v24
	v_and_b32_e32 v53, 0xffff0000, v24
	v_lshlrev_b32_e32 v54, 16, v25
	v_and_b32_e32 v55, 0xffff0000, v25
	ds_write_b128 v51, v[52:55] offset:12288
	s_waitcnt vmcnt(5)
	v_lshlrev_b32_e32 v52, 16, v26
	v_and_b32_e32 v53, 0xffff0000, v26
	v_lshlrev_b32_e32 v54, 16, v27
	v_and_b32_e32 v55, 0xffff0000, v27
	ds_write_b128 v51, v[52:55] offset:16384
	s_waitcnt vmcnt(4)
	v_lshlrev_b32_e32 v52, 16, v28
	v_and_b32_e32 v53, 0xffff0000, v28
	v_lshlrev_b32_e32 v54, 16, v29
	v_and_b32_e32 v55, 0xffff0000, v29
	v_add3_u32 v51, s18, v49, v50
	ds_write_b128 v51, v[52:55] offset:20480
	s_branch .LBB0_422

.LBB0_453:
	s_bitcmp1_b32 s46, 0
	s_cselect_b32 s46, 0x6000, 0
	s_add_i32 s46, s78, s46
	v_lshl_add_u32 v41, v6, 4, s46
	v_lshl_add_u32 v42, v34, 2, s46
	v_add_u32_e32 v42, 0x5000, v42
	v_and_b32_e32 v30, 1, v6
	v_and_b32_e32 v31, 2, v6
	ds_read_b128 v[52:55], v41 offset:12288
	ds_read_b128 v[48:51], v41 offset:8192
	ds_read_b32 v60, v42 offset:0
	ds_read_b128 v[44:47], v41 offset:4096
	ds_read_b128 v[56:59], v41 offset:16384
	ds_read_b128 v[112:115], v41 offset:0
	v_cmp_ne_u32_e64 s[4:5], 0, v30
	v_cmp_ne_u32_e64 s[6:7], 0, v31
	ds_read_b128 v[76:79], v41 offset:12544
	ds_read_b128 v[72:75], v41 offset:8448
	ds_read_b32 v84, v42 offset:64
	ds_read_b128 v[68:71], v41 offset:4352
	ds_read_b128 v[80:83], v41 offset:16640
	ds_read_b128 v[116:119], v41 offset:256
	s_waitcnt lgkmcnt(6)
	v_pk_mul_f32 v[30:31], v[0:1], v[52:53]
	v_pk_fma_f32 v[30:31], v[2:3], v[54:55], v[30:31]
	v_add_f32_e32 v30, v30, v31
	v_pk_mul_f32 v[92:93], v[48:49], v[60:61] op_sel_hi:[1,0]
	v_pk_mul_f32 v[94:95], v[50:51], v[60:61] op_sel_hi:[1,0]
	v_add_f32_dpp v30, v30, v30 quad_perm:[1,0,3,2] row_mask:0xf bank_mask:0xf bound_ctrl:1
	v_pk_fma_f32 v[32:33], v[0:1], v[44:45], v[92:93]
	v_pk_fma_f32 v[90:91], v[2:3], v[46:47], v[94:95]
	v_add_f32_dpp v30, v30, v30 quad_perm:[2,3,0,1] row_mask:0xf bank_mask:0xf bound_ctrl:1
	s_nop 1
	v_add_f32_dpp v30, v30, v30 row_half_mirror row_mask:0xf bank_mask:0xf bound_ctrl:1
	s_nop 1
	v_add_f32_dpp v86, v30, v30 row_mirror row_mask:0xf bank_mask:0xf bound_ctrl:1
	v_pk_fma_f32 v[0:1], v[56:57], v[86:87], v[32:33] op_sel_hi:[1,0,1] neg_lo:[0,1,0] neg_hi:[0,1,0]
	v_pk_fma_f32 v[2:3], v[58:59], v[86:87], v[90:91] op_sel_hi:[1,0,1] neg_lo:[0,1,0] neg_hi:[0,1,0]
	ds_read_b128 v[52:55], v41 offset:12800
	ds_read_b128 v[48:51], v41 offset:8704
	ds_read_b32 v60, v42 offset:128
	ds_read_b128 v[44:47], v41 offset:4608
	ds_read_b128 v[56:59], v41 offset:16896
	ds_read_b128 v[120:123], v41 offset:512
	s_waitcnt lgkmcnt(6)
	v_pk_mul_f32 v[30:31], v[0:1], v[76:77]
	v_pk_fma_f32 v[30:31], v[2:3], v[78:79], v[30:31]
	v_add_f32_e32 v30, v30, v31
	v_pk_mul_f32 v[92:93], v[72:73], v[84:85] op_sel_hi:[1,0]
	v_pk_mul_f32 v[94:95], v[74:75], v[84:85] op_sel_hi:[1,0]
	v_add_f32_dpp v30, v30, v30 quad_perm:[1,0,3,2] row_mask:0xf bank_mask:0xf bound_ctrl:1
	v_pk_fma_f32 v[32:33], v[0:1], v[68:69], v[92:93]
	v_pk_fma_f32 v[90:91], v[2:3], v[70:71], v[94:95]
	v_add_f32_dpp v30, v30, v30 quad_perm:[2,3,0,1] row_mask:0xf bank_mask:0xf bound_ctrl:1
	v_mul_f32_e32 v96, v113, v1
	v_fmac_f32_e32 v96, v112, v0
	v_add_f32_dpp v30, v30, v30 row_half_mirror row_mask:0xf bank_mask:0xf bound_ctrl:1
	v_fmac_f32_e32 v96, v114, v2
	v_fmac_f32_e32 v96, v115, v3
	v_add_f32_dpp v86, v30, v30 row_mirror row_mask:0xf bank_mask:0xf bound_ctrl:1
	v_pk_fma_f32 v[0:1], v[80:81], v[86:87], v[32:33] op_sel_hi:[1,0,1] neg_lo:[0,1,0] neg_hi:[0,1,0]
	v_pk_fma_f32 v[2:3], v[82:83], v[86:87], v[90:91] op_sel_hi:[1,0,1] neg_lo:[0,1,0] neg_hi:[0,1,0]
	ds_read_b128 v[76:79], v41 offset:13056
	ds_read_b128 v[72:75], v41 offset:8960
	ds_read_b32 v84, v42 offset:192
	ds_read_b128 v[68:71], v41 offset:4864
	ds_read_b128 v[80:83], v41 offset:17152
	ds_read_b128 v[112:115], v41 offset:768
	s_waitcnt lgkmcnt(6)
	v_pk_mul_f32 v[30:31], v[0:1], v[52:53]
	v_pk_fma_f32 v[30:31], v[2:3], v[54:55], v[30:31]
	v_add_f32_e32 v30, v30, v31
	v_pk_mul_f32 v[92:93], v[48:49], v[60:61] op_sel_hi:[1,0]
	v_pk_mul_f32 v[94:95], v[50:51], v[60:61] op_sel_hi:[1,0]
	v_add_f32_dpp v30, v30, v30 quad_perm:[1,0,3,2] row_mask:0xf bank_mask:0xf bound_ctrl:1
	v_pk_fma_f32 v[32:33], v[0:1], v[44:45], v[92:93]
	v_pk_fma_f32 v[90:91], v[2:3], v[46:47], v[94:95]
	v_add_f32_dpp v30, v30, v30 quad_perm:[2,3,0,1] row_mask:0xf bank_mask:0xf bound_ctrl:1
	v_mul_f32_e32 v97, v117, v1
	v_fmac_f32_e32 v97, v116, v0
	v_add_f32_dpp v30, v30, v30 row_half_mirror row_mask:0xf bank_mask:0xf bound_ctrl:1
	v_fmac_f32_e32 v97, v118, v2
	v_fmac_f32_e32 v97, v119, v3
	v_add_f32_dpp v86, v30, v30 row_mirror row_mask:0xf bank_mask:0xf bound_ctrl:1
	v_pk_fma_f32 v[0:1], v[56:57], v[86:87], v[32:33] op_sel_hi:[1,0,1] neg_lo:[0,1,0] neg_hi:[0,1,0]
	v_pk_fma_f32 v[2:3], v[58:59], v[86:87], v[90:91] op_sel_hi:[1,0,1] neg_lo:[0,1,0] neg_hi:[0,1,0]
	ds_read_b128 v[52:55], v41 offset:13312
	ds_read_b128 v[48:51], v41 offset:9216
	ds_read_b32 v60, v42 offset:256
	ds_read_b128 v[44:47], v41 offset:5120
	ds_read_b128 v[56:59], v41 offset:17408
	ds_read_b128 v[116:119], v41 offset:1024
	s_waitcnt lgkmcnt(6)
	v_pk_mul_f32 v[30:31], v[0:1], v[76:77]
	v_pk_fma_f32 v[30:31], v[2:3], v[78:79], v[30:31]
	v_add_f32_e32 v30, v30, v31
	v_pk_mul_f32 v[92:93], v[72:73], v[84:85] op_sel_hi:[1,0]
	v_pk_mul_f32 v[94:95], v[74:75], v[84:85] op_sel_hi:[1,0]
	v_add_f32_dpp v30, v30, v30 quad_perm:[1,0,3,2] row_mask:0xf bank_mask:0xf bound_ctrl:1
	v_pk_fma_f32 v[32:33], v[0:1], v[68:69], v[92:93]
	v_pk_fma_f32 v[90:91], v[2:3], v[70:71], v[94:95]
	v_add_f32_dpp v30, v30, v30 quad_perm:[2,3,0,1] row_mask:0xf bank_mask:0xf bound_ctrl:1
	v_mul_f32_e32 v98, v121, v1
	v_fmac_f32_e32 v98, v120, v0
	v_add_f32_dpp v30, v30, v30 row_half_mirror row_mask:0xf bank_mask:0xf bound_ctrl:1
	v_fmac_f32_e32 v98, v122, v2
	v_fmac_f32_e32 v98, v123, v3
	v_add_f32_dpp v86, v30, v30 row_mirror row_mask:0xf bank_mask:0xf bound_ctrl:1
	v_pk_fma_f32 v[0:1], v[80:81], v[86:87], v[32:33] op_sel_hi:[1,0,1] neg_lo:[0,1,0] neg_hi:[0,1,0]
	v_pk_fma_f32 v[2:3], v[82:83], v[86:87], v[90:91] op_sel_hi:[1,0,1] neg_lo:[0,1,0] neg_hi:[0,1,0]
	ds_read_b128 v[76:79], v41 offset:13568
	ds_read_b128 v[72:75], v41 offset:9472
	ds_read_b32 v84, v42 offset:320
	ds_read_b128 v[68:71], v41 offset:5376
	ds_read_b128 v[80:83], v41 offset:17664
	ds_read_b128 v[120:123], v41 offset:1280
	s_waitcnt lgkmcnt(6)
	v_pk_mul_f32 v[30:31], v[0:1], v[52:53]
	v_pk_fma_f32 v[30:31], v[2:3], v[54:55], v[30:31]
	v_add_f32_e32 v30, v30, v31
	v_pk_mul_f32 v[92:93], v[48:49], v[60:61] op_sel_hi:[1,0]
	v_pk_mul_f32 v[94:95], v[50:51], v[60:61] op_sel_hi:[1,0]
	v_add_f32_dpp v30, v30, v30 quad_perm:[1,0,3,2] row_mask:0xf bank_mask:0xf bound_ctrl:1
	v_pk_fma_f32 v[32:33], v[0:1], v[44:45], v[92:93]
	v_pk_fma_f32 v[90:91], v[2:3], v[46:47], v[94:95]
	v_add_f32_dpp v30, v30, v30 quad_perm:[2,3,0,1] row_mask:0xf bank_mask:0xf bound_ctrl:1
	v_mul_f32_e32 v99, v113, v1
	v_fmac_f32_e32 v99, v112, v0
	v_add_f32_dpp v30, v30, v30 row_half_mirror row_mask:0xf bank_mask:0xf bound_ctrl:1
	v_fmac_f32_e32 v99, v114, v2
	v_fmac_f32_e32 v99, v115, v3
	v_add_f32_dpp v86, v30, v30 row_mirror row_mask:0xf bank_mask:0xf bound_ctrl:1
	v_pk_fma_f32 v[0:1], v[56:57], v[86:87], v[32:33] op_sel_hi:[1,0,1] neg_lo:[0,1,0] neg_hi:[0,1,0]
	v_pk_fma_f32 v[2:3], v[58:59], v[86:87], v[90:91] op_sel_hi:[1,0,1] neg_lo:[0,1,0] neg_hi:[0,1,0]
	ds_read_b128 v[52:55], v41 offset:13824
	ds_read_b128 v[48:51], v41 offset:9728
	ds_read_b32 v60, v42 offset:384
	ds_read_b128 v[44:47], v41 offset:5632
	ds_read_b128 v[56:59], v41 offset:17920
	ds_read_b128 v[112:115], v41 offset:1536
	s_waitcnt lgkmcnt(6)
	v_pk_mul_f32 v[30:31], v[0:1], v[76:77]
	v_pk_fma_f32 v[30:31], v[2:3], v[78:79], v[30:31]
	v_add_f32_e32 v30, v30, v31
	v_pk_mul_f32 v[92:93], v[72:73], v[84:85] op_sel_hi:[1,0]
	v_pk_mul_f32 v[94:95], v[74:75], v[84:85] op_sel_hi:[1,0]
	v_add_f32_dpp v30, v30, v30 quad_perm:[1,0,3,2] row_mask:0xf bank_mask:0xf bound_ctrl:1
	v_pk_fma_f32 v[32:33], v[0:1], v[68:69], v[92:93]
	v_pk_fma_f32 v[90:91], v[2:3], v[70:71], v[94:95]
	v_add_f32_dpp v30, v30, v30 quad_perm:[2,3,0,1] row_mask:0xf bank_mask:0xf bound_ctrl:1
	v_mul_f32_e32 v100, v117, v1
	v_fmac_f32_e32 v100, v116, v0
	v_add_f32_dpp v30, v30, v30 row_half_mirror row_mask:0xf bank_mask:0xf bound_ctrl:1
	v_fmac_f32_e32 v100, v118, v2
	v_fmac_f32_e32 v100, v119, v3
	v_add_f32_dpp v86, v30, v30 row_mirror row_mask:0xf bank_mask:0xf bound_ctrl:1
	v_pk_fma_f32 v[0:1], v[80:81], v[86:87], v[32:33] op_sel_hi:[1,0,1] neg_lo:[0,1,0] neg_hi:[0,1,0]
	v_pk_fma_f32 v[2:3], v[82:83], v[86:87], v[90:91] op_sel_hi:[1,0,1] neg_lo:[0,1,0] neg_hi:[0,1,0]
	ds_read_b128 v[76:79], v41 offset:14080
	ds_read_b128 v[72:75], v41 offset:9984
	ds_read_b32 v84, v42 offset:448
	ds_read_b128 v[68:71], v41 offset:5888
	ds_read_b128 v[80:83], v41 offset:18176
	ds_read_b128 v[116:119], v41 offset:1792
	s_waitcnt lgkmcnt(6)
	v_pk_mul_f32 v[30:31], v[0:1], v[52:53]
	v_pk_fma_f32 v[30:31], v[2:3], v[54:55], v[30:31]
	v_add_f32_e32 v30, v30, v31
	v_pk_mul_f32 v[92:93], v[48:49], v[60:61] op_sel_hi:[1,0]
	v_pk_mul_f32 v[94:95], v[50:51], v[60:61] op_sel_hi:[1,0]
	v_add_f32_dpp v30, v30, v30 quad_perm:[1,0,3,2] row_mask:0xf bank_mask:0xf bound_ctrl:1
	v_pk_fma_f32 v[32:33], v[0:1], v[44:45], v[92:93]
	v_pk_fma_f32 v[90:91], v[2:3], v[46:47], v[94:95]
	v_add_f32_dpp v30, v30, v30 quad_perm:[2,3,0,1] row_mask:0xf bank_mask:0xf bound_ctrl:1
	v_mul_f32_e32 v101, v121, v1
	v_fmac_f32_e32 v101, v120, v0
	v_add_f32_dpp v30, v30, v30 row_half_mirror row_mask:0xf bank_mask:0xf bound_ctrl:1
	v_fmac_f32_e32 v101, v122, v2
	v_fmac_f32_e32 v101, v123, v3
	v_add_f32_dpp v86, v30, v30 row_mirror row_mask:0xf bank_mask:0xf bound_ctrl:1
	v_pk_fma_f32 v[0:1], v[56:57], v[86:87], v[32:33] op_sel_hi:[1,0,1] neg_lo:[0,1,0] neg_hi:[0,1,0]
	v_pk_fma_f32 v[2:3], v[58:59], v[86:87], v[90:91] op_sel_hi:[1,0,1] neg_lo:[0,1,0] neg_hi:[0,1,0]
	ds_read_b128 v[52:55], v41 offset:14336
	ds_read_b128 v[48:51], v41 offset:10240
	ds_read_b32 v60, v42 offset:512
	ds_read_b128 v[44:47], v41 offset:6144
	ds_read_b128 v[56:59], v41 offset:18432
	ds_read_b128 v[120:123], v41 offset:2048
	s_waitcnt lgkmcnt(6)
	v_pk_mul_f32 v[30:31], v[0:1], v[76:77]
	v_pk_fma_f32 v[30:31], v[2:3], v[78:79], v[30:31]
	v_add_f32_e32 v30, v30, v31
	v_pk_mul_f32 v[92:93], v[72:73], v[84:85] op_sel_hi:[1,0]
	v_pk_mul_f32 v[94:95], v[74:75], v[84:85] op_sel_hi:[1,0]
	v_add_f32_dpp v30, v30, v30 quad_perm:[1,0,3,2] row_mask:0xf bank_mask:0xf bound_ctrl:1
	v_pk_fma_f32 v[32:33], v[0:1], v[68:69], v[92:93]
	v_pk_fma_f32 v[90:91], v[2:3], v[70:71], v[94:95]
	v_add_f32_dpp v30, v30, v30 quad_perm:[2,3,0,1] row_mask:0xf bank_mask:0xf bound_ctrl:1
	v_mul_f32_e32 v102, v113, v1
	v_fmac_f32_e32 v102, v112, v0
	v_add_f32_dpp v30, v30, v30 row_half_mirror row_mask:0xf bank_mask:0xf bound_ctrl:1
	v_fmac_f32_e32 v102, v114, v2
	v_fmac_f32_e32 v102, v115, v3
	v_add_f32_dpp v86, v30, v30 row_mirror row_mask:0xf bank_mask:0xf bound_ctrl:1
	v_pk_fma_f32 v[0:1], v[80:81], v[86:87], v[32:33] op_sel_hi:[1,0,1] neg_lo:[0,1,0] neg_hi:[0,1,0]
	v_pk_fma_f32 v[2:3], v[82:83], v[86:87], v[90:91] op_sel_hi:[1,0,1] neg_lo:[0,1,0] neg_hi:[0,1,0]
	ds_read_b128 v[76:79], v41 offset:14592
	ds_read_b128 v[72:75], v41 offset:10496
	ds_read_b32 v84, v42 offset:576
	ds_read_b128 v[68:71], v41 offset:6400
	ds_read_b128 v[80:83], v41 offset:18688
	ds_read_b128 v[112:115], v41 offset:2304
	s_waitcnt lgkmcnt(6)
	v_pk_mul_f32 v[30:31], v[0:1], v[52:53]
	v_pk_fma_f32 v[30:31], v[2:3], v[54:55], v[30:31]
	v_add_f32_e32 v30, v30, v31
	v_pk_mul_f32 v[92:93], v[48:49], v[60:61] op_sel_hi:[1,0]
	v_pk_mul_f32 v[94:95], v[50:51], v[60:61] op_sel_hi:[1,0]
	v_add_f32_dpp v30, v30, v30 quad_perm:[1,0,3,2] row_mask:0xf bank_mask:0xf bound_ctrl:1
	v_pk_fma_f32 v[32:33], v[0:1], v[44:45], v[92:93]
	v_pk_fma_f32 v[90:91], v[2:3], v[46:47], v[94:95]
	v_add_f32_dpp v30, v30, v30 quad_perm:[2,3,0,1] row_mask:0xf bank_mask:0xf bound_ctrl:1
	v_mul_f32_e32 v103, v117, v1
	v_fmac_f32_e32 v103, v116, v0
	v_add_f32_dpp v30, v30, v30 row_half_mirror row_mask:0xf bank_mask:0xf bound_ctrl:1
	v_fmac_f32_e32 v103, v118, v2
	v_fmac_f32_e32 v103, v119, v3
	v_add_f32_dpp v86, v30, v30 row_mirror row_mask:0xf bank_mask:0xf bound_ctrl:1
	v_pk_fma_f32 v[0:1], v[56:57], v[86:87], v[32:33] op_sel_hi:[1,0,1] neg_lo:[0,1,0] neg_hi:[0,1,0]
	v_pk_fma_f32 v[2:3], v[58:59], v[86:87], v[90:91] op_sel_hi:[1,0,1] neg_lo:[0,1,0] neg_hi:[0,1,0]
	ds_read_b128 v[52:55], v41 offset:14848
	ds_read_b128 v[48:51], v41 offset:10752
	ds_read_b32 v60, v42 offset:640
	ds_read_b128 v[44:47], v41 offset:6656
	ds_read_b128 v[56:59], v41 offset:18944
	ds_read_b128 v[116:119], v41 offset:2560
	s_waitcnt lgkmcnt(6)
	v_pk_mul_f32 v[30:31], v[0:1], v[76:77]
	v_pk_fma_f32 v[30:31], v[2:3], v[78:79], v[30:31]
	v_add_f32_e32 v30, v30, v31
	v_pk_mul_f32 v[92:93], v[72:73], v[84:85] op_sel_hi:[1,0]
	v_pk_mul_f32 v[94:95], v[74:75], v[84:85] op_sel_hi:[1,0]
	v_add_f32_dpp v30, v30, v30 quad_perm:[1,0,3,2] row_mask:0xf bank_mask:0xf bound_ctrl:1
	v_pk_fma_f32 v[32:33], v[0:1], v[68:69], v[92:93]
	v_pk_fma_f32 v[90:91], v[2:3], v[70:71], v[94:95]
	v_add_f32_dpp v30, v30, v30 quad_perm:[2,3,0,1] row_mask:0xf bank_mask:0xf bound_ctrl:1
	v_mul_f32_e32 v104, v121, v1
	v_fmac_f32_e32 v104, v120, v0
	v_add_f32_dpp v30, v30, v30 row_half_mirror row_mask:0xf bank_mask:0xf bound_ctrl:1
	v_fmac_f32_e32 v104, v122, v2
	v_fmac_f32_e32 v104, v123, v3
	v_add_f32_dpp v86, v30, v30 row_mirror row_mask:0xf bank_mask:0xf bound_ctrl:1
	v_pk_fma_f32 v[0:1], v[80:81], v[86:87], v[32:33] op_sel_hi:[1,0,1] neg_lo:[0,1,0] neg_hi:[0,1,0]
	v_pk_fma_f32 v[2:3], v[82:83], v[86:87], v[90:91] op_sel_hi:[1,0,1] neg_lo:[0,1,0] neg_hi:[0,1,0]
	ds_read_b128 v[76:79], v41 offset:15104
	ds_read_b128 v[72:75], v41 offset:11008
	ds_read_b32 v84, v42 offset:704
	ds_read_b128 v[68:71], v41 offset:6912
	ds_read_b128 v[80:83], v41 offset:19200
	ds_read_b128 v[120:123], v41 offset:2816
	s_waitcnt lgkmcnt(6)
	v_pk_mul_f32 v[30:31], v[0:1], v[52:53]
	v_pk_fma_f32 v[30:31], v[2:3], v[54:55], v[30:31]
	v_add_f32_e32 v30, v30, v31
	v_pk_mul_f32 v[92:93], v[48:49], v[60:61] op_sel_hi:[1,0]
	v_pk_mul_f32 v[94:95], v[50:51], v[60:61] op_sel_hi:[1,0]
	v_add_f32_dpp v30, v30, v30 quad_perm:[1,0,3,2] row_mask:0xf bank_mask:0xf bound_ctrl:1
	v_pk_fma_f32 v[32:33], v[0:1], v[44:45], v[92:93]
	v_pk_fma_f32 v[90:91], v[2:3], v[46:47], v[94:95]
	v_add_f32_dpp v30, v30, v30 quad_perm:[2,3,0,1] row_mask:0xf bank_mask:0xf bound_ctrl:1
	v_mul_f32_e32 v105, v113, v1
	v_fmac_f32_e32 v105, v112, v0
	v_add_f32_dpp v30, v30, v30 row_half_mirror row_mask:0xf bank_mask:0xf bound_ctrl:1
	v_fmac_f32_e32 v105, v114, v2
	v_fmac_f32_e32 v105, v115, v3
	v_add_f32_dpp v86, v30, v30 row_mirror row_mask:0xf bank_mask:0xf bound_ctrl:1
	v_pk_fma_f32 v[0:1], v[56:57], v[86:87], v[32:33] op_sel_hi:[1,0,1] neg_lo:[0,1,0] neg_hi:[0,1,0]
	v_pk_fma_f32 v[2:3], v[58:59], v[86:87], v[90:91] op_sel_hi:[1,0,1] neg_lo:[0,1,0] neg_hi:[0,1,0]
	ds_read_b128 v[52:55], v41 offset:15360
	ds_read_b128 v[48:51], v41 offset:11264
	ds_read_b32 v60, v42 offset:768
	ds_read_b128 v[44:47], v41 offset:7168
	ds_read_b128 v[56:59], v41 offset:19456
	ds_read_b128 v[112:115], v41 offset:3072
	s_waitcnt lgkmcnt(6)
	v_pk_mul_f32 v[30:31], v[0:1], v[76:77]
	v_pk_fma_f32 v[30:31], v[2:3], v[78:79], v[30:31]
	v_add_f32_e32 v30, v30, v31
	v_pk_mul_f32 v[92:93], v[72:73], v[84:85] op_sel_hi:[1,0]
	v_pk_mul_f32 v[94:95], v[74:75], v[84:85] op_sel_hi:[1,0]
	v_add_f32_dpp v30, v30, v30 quad_perm:[1,0,3,2] row_mask:0xf bank_mask:0xf bound_ctrl:1
	v_pk_fma_f32 v[32:33], v[0:1], v[68:69], v[92:93]
	v_pk_fma_f32 v[90:91], v[2:3], v[70:71], v[94:95]
	v_add_f32_dpp v30, v30, v30 quad_perm:[2,3,0,1] row_mask:0xf bank_mask:0xf bound_ctrl:1
	v_mul_f32_e32 v106, v117, v1
	v_fmac_f32_e32 v106, v116, v0
	v_add_f32_dpp v30, v30, v30 row_half_mirror row_mask:0xf bank_mask:0xf bound_ctrl:1
	v_fmac_f32_e32 v106, v118, v2
	v_fmac_f32_e32 v106, v119, v3
	v_add_f32_dpp v86, v30, v30 row_mirror row_mask:0xf bank_mask:0xf bound_ctrl:1
	v_pk_fma_f32 v[0:1], v[80:81], v[86:87], v[32:33] op_sel_hi:[1,0,1] neg_lo:[0,1,0] neg_hi:[0,1,0]
	v_pk_fma_f32 v[2:3], v[82:83], v[86:87], v[90:91] op_sel_hi:[1,0,1] neg_lo:[0,1,0] neg_hi:[0,1,0]
	ds_read_b128 v[76:79], v41 offset:15616
	ds_read_b128 v[72:75], v41 offset:11520
	ds_read_b32 v84, v42 offset:832
	ds_read_b128 v[68:71], v41 offset:7424
	ds_read_b128 v[80:83], v41 offset:19712
	ds_read_b128 v[116:119], v41 offset:3328
	s_waitcnt lgkmcnt(6)
	v_pk_mul_f32 v[30:31], v[0:1], v[52:53]
	v_pk_fma_f32 v[30:31], v[2:3], v[54:55], v[30:31]
	v_add_f32_e32 v30, v30, v31
	v_pk_mul_f32 v[92:93], v[48:49], v[60:61] op_sel_hi:[1,0]
	v_pk_mul_f32 v[94:95], v[50:51], v[60:61] op_sel_hi:[1,0]
	v_add_f32_dpp v30, v30, v30 quad_perm:[1,0,3,2] row_mask:0xf bank_mask:0xf bound_ctrl:1
	v_pk_fma_f32 v[32:33], v[0:1], v[44:45], v[92:93]
	v_pk_fma_f32 v[90:91], v[2:3], v[46:47], v[94:95]
	v_add_f32_dpp v30, v30, v30 quad_perm:[2,3,0,1] row_mask:0xf bank_mask:0xf bound_ctrl:1
	v_mul_f32_e32 v107, v121, v1
	v_fmac_f32_e32 v107, v120, v0
	v_add_f32_dpp v30, v30, v30 row_half_mirror row_mask:0xf bank_mask:0xf bound_ctrl:1
	v_fmac_f32_e32 v107, v122, v2
	v_fmac_f32_e32 v107, v123, v3
	v_add_f32_dpp v86, v30, v30 row_mirror row_mask:0xf bank_mask:0xf bound_ctrl:1
	v_pk_fma_f32 v[0:1], v[56:57], v[86:87], v[32:33] op_sel_hi:[1,0,1] neg_lo:[0,1,0] neg_hi:[0,1,0]
	v_pk_fma_f32 v[2:3], v[58:59], v[86:87], v[90:91] op_sel_hi:[1,0,1] neg_lo:[0,1,0] neg_hi:[0,1,0]
	ds_read_b128 v[52:55], v41 offset:15872
	ds_read_b128 v[48:51], v41 offset:11776
	ds_read_b32 v60, v42 offset:896
	ds_read_b128 v[44:47], v41 offset:7680
	ds_read_b128 v[56:59], v41 offset:19968
	ds_read_b128 v[120:123], v41 offset:3584
	s_waitcnt lgkmcnt(6)
	v_pk_mul_f32 v[30:31], v[0:1], v[76:77]
	v_pk_fma_f32 v[30:31], v[2:3], v[78:79], v[30:31]
	v_add_f32_e32 v30, v30, v31
	v_pk_mul_f32 v[92:93], v[72:73], v[84:85] op_sel_hi:[1,0]
	v_pk_mul_f32 v[94:95], v[74:75], v[84:85] op_sel_hi:[1,0]
	v_add_f32_dpp v30, v30, v30 quad_perm:[1,0,3,2] row_mask:0xf bank_mask:0xf bound_ctrl:1
	v_pk_fma_f32 v[32:33], v[0:1], v[68:69], v[92:93]
	v_pk_fma_f32 v[90:91], v[2:3], v[70:71], v[94:95]
	v_add_f32_dpp v30, v30, v30 quad_perm:[2,3,0,1] row_mask:0xf bank_mask:0xf bound_ctrl:1
	v_mul_f32_e32 v108, v113, v1
	v_fmac_f32_e32 v108, v112, v0
	v_add_f32_dpp v30, v30, v30 row_half_mirror row_mask:0xf bank_mask:0xf bound_ctrl:1
	v_fmac_f32_e32 v108, v114, v2
	v_fmac_f32_e32 v108, v115, v3
	v_add_f32_dpp v86, v30, v30 row_mirror row_mask:0xf bank_mask:0xf bound_ctrl:1
	v_pk_fma_f32 v[0:1], v[80:81], v[86:87], v[32:33] op_sel_hi:[1,0,1] neg_lo:[0,1,0] neg_hi:[0,1,0]
	v_pk_fma_f32 v[2:3], v[82:83], v[86:87], v[90:91] op_sel_hi:[1,0,1] neg_lo:[0,1,0] neg_hi:[0,1,0]
	ds_read_b128 v[76:79], v41 offset:16128
	ds_read_b128 v[72:75], v41 offset:12032
	ds_read_b32 v84, v42 offset:960
	ds_read_b128 v[68:71], v41 offset:7936
	ds_read_b128 v[80:83], v41 offset:20224
	ds_read_b128 v[112:115], v41 offset:3840
	s_waitcnt lgkmcnt(6)
	v_pk_mul_f32 v[30:31], v[0:1], v[52:53]
	v_pk_fma_f32 v[30:31], v[2:3], v[54:55], v[30:31]
	v_add_f32_e32 v30, v30, v31
	v_pk_mul_f32 v[92:93], v[48:49], v[60:61] op_sel_hi:[1,0]
	v_pk_mul_f32 v[94:95], v[50:51], v[60:61] op_sel_hi:[1,0]
	v_add_f32_dpp v30, v30, v30 quad_perm:[1,0,3,2] row_mask:0xf bank_mask:0xf bound_ctrl:1
	v_pk_fma_f32 v[32:33], v[0:1], v[44:45], v[92:93]
	v_pk_fma_f32 v[90:91], v[2:3], v[46:47], v[94:95]
	v_add_f32_dpp v30, v30, v30 quad_perm:[2,3,0,1] row_mask:0xf bank_mask:0xf bound_ctrl:1
	v_mul_f32_e32 v109, v117, v1
	v_fmac_f32_e32 v109, v116, v0
	v_add_f32_dpp v30, v30, v30 row_half_mirror row_mask:0xf bank_mask:0xf bound_ctrl:1
	v_fmac_f32_e32 v109, v118, v2
	v_fmac_f32_e32 v109, v119, v3
	v_add_f32_dpp v86, v30, v30 row_mirror row_mask:0xf bank_mask:0xf bound_ctrl:1
	v_pk_fma_f32 v[0:1], v[56:57], v[86:87], v[32:33] op_sel_hi:[1,0,1] neg_lo:[0,1,0] neg_hi:[0,1,0]
	v_pk_fma_f32 v[2:3], v[58:59], v[86:87], v[90:91] op_sel_hi:[1,0,1] neg_lo:[0,1,0] neg_hi:[0,1,0]
	s_waitcnt lgkmcnt(0)
	v_pk_mul_f32 v[30:31], v[0:1], v[76:77]
	v_pk_fma_f32 v[30:31], v[2:3], v[78:79], v[30:31]
	v_add_f32_e32 v30, v30, v31
	v_pk_mul_f32 v[92:93], v[72:73], v[84:85] op_sel_hi:[1,0]
	v_pk_mul_f32 v[94:95], v[74:75], v[84:85] op_sel_hi:[1,0]
	v_add_f32_dpp v30, v30, v30 quad_perm:[1,0,3,2] row_mask:0xf bank_mask:0xf bound_ctrl:1
	v_pk_fma_f32 v[32:33], v[0:1], v[68:69], v[92:93]
	v_pk_fma_f32 v[90:91], v[2:3], v[70:71], v[94:95]
	v_add_f32_dpp v30, v30, v30 quad_perm:[2,3,0,1] row_mask:0xf bank_mask:0xf bound_ctrl:1
	v_mul_f32_e32 v110, v121, v1
	v_fmac_f32_e32 v110, v120, v0
	v_add_f32_dpp v30, v30, v30 row_half_mirror row_mask:0xf bank_mask:0xf bound_ctrl:1
	v_fmac_f32_e32 v110, v122, v2
	v_fmac_f32_e32 v110, v123, v3
	v_add_f32_dpp v86, v30, v30 row_mirror row_mask:0xf bank_mask:0xf bound_ctrl:1
	v_pk_fma_f32 v[0:1], v[80:81], v[86:87], v[32:33] op_sel_hi:[1,0,1] neg_lo:[0,1,0] neg_hi:[0,1,0]
	v_pk_fma_f32 v[2:3], v[82:83], v[86:87], v[90:91] op_sel_hi:[1,0,1] neg_lo:[0,1,0] neg_hi:[0,1,0]
	v_mul_f32_e32 v111, v113, v1
	v_fmac_f32_e32 v111, v112, v0
	v_fmac_f32_e32 v111, v114, v2
	v_fmac_f32_e32 v111, v115, v3
	v_cndmask_b32_e64 v124, v96, v97, s[4:5]
	v_cndmask_b32_e64 v88, v97, v96, s[4:5]
	v_cndmask_b32_e64 v125, v98, v99, s[4:5]
	v_cndmask_b32_e64 v89, v99, v98, s[4:5]
	v_cndmask_b32_e64 v126, v100, v101, s[4:5]
	v_cndmask_b32_e64 v66, v101, v100, s[4:5]
	v_cndmask_b32_e64 v127, v102, v103, s[4:5]
	v_cndmask_b32_e64 v67, v103, v102, s[4:5]
	v_cndmask_b32_e64 v62, v104, v105, s[4:5]
	v_cndmask_b32_e64 v84, v105, v104, s[4:5]
	v_cndmask_b32_e64 v63, v106, v107, s[4:5]
	v_cndmask_b32_e64 v85, v107, v106, s[4:5]
	v_cndmask_b32_e64 v64, v108, v109, s[4:5]
	v_cndmask_b32_e64 v41, v109, v108, s[4:5]
	v_cndmask_b32_e64 v65, v110, v111, s[4:5]
	v_cndmask_b32_e64 v43, v111, v110, s[4:5]
	v_add_f32_dpp v96, v88, v124 quad_perm:[1,0,3,2] row_mask:0xf bank_mask:0xf bound_ctrl:1
	v_add_f32_dpp v97, v89, v125 quad_perm:[1,0,3,2] row_mask:0xf bank_mask:0xf bound_ctrl:1
	v_add_f32_dpp v98, v66, v126 quad_perm:[1,0,3,2] row_mask:0xf bank_mask:0xf bound_ctrl:1
	v_add_f32_dpp v99, v67, v127 quad_perm:[1,0,3,2] row_mask:0xf bank_mask:0xf bound_ctrl:1
	v_add_f32_dpp v100, v84, v62 quad_perm:[1,0,3,2] row_mask:0xf bank_mask:0xf bound_ctrl:1
	v_add_f32_dpp v101, v85, v63 quad_perm:[1,0,3,2] row_mask:0xf bank_mask:0xf bound_ctrl:1
	v_add_f32_dpp v102, v41, v64 quad_perm:[1,0,3,2] row_mask:0xf bank_mask:0xf bound_ctrl:1
	v_add_f32_dpp v103, v43, v65 quad_perm:[1,0,3,2] row_mask:0xf bank_mask:0xf bound_ctrl:1
	v_cndmask_b32_e64 v124, v96, v97, s[6:7]
	v_cndmask_b32_e64 v88, v97, v96, s[6:7]
	v_cndmask_b32_e64 v125, v98, v99, s[6:7]
	v_cndmask_b32_e64 v89, v99, v98, s[6:7]
	v_cndmask_b32_e64 v126, v100, v101, s[6:7]
	v_cndmask_b32_e64 v66, v101, v100, s[6:7]
	v_cndmask_b32_e64 v127, v102, v103, s[6:7]
	v_cndmask_b32_e64 v67, v103, v102, s[6:7]
	v_add_f32_dpp v104, v88, v124 quad_perm:[2,3,0,1] row_mask:0xf bank_mask:0xf bound_ctrl:1
	v_add_f32_dpp v105, v89, v125 quad_perm:[2,3,0,1] row_mask:0xf bank_mask:0xf bound_ctrl:1
	v_add_f32_dpp v106, v66, v126 quad_perm:[2,3,0,1] row_mask:0xf bank_mask:0xf bound_ctrl:1
	v_add_f32_dpp v107, v67, v127 quad_perm:[2,3,0,1] row_mask:0xf bank_mask:0xf bound_ctrl:1
	s_nop 0
	v_add_f32_dpp v108, v104, v104 row_shl:4 row_mask:0xf bank_mask:0x5 bound_ctrl:1
	v_add_f32_dpp v109, v106, v106 row_shl:4 row_mask:0xf bank_mask:0x5 bound_ctrl:1
	s_nop 0
	v_add_f32_dpp v108, v105, v105 row_shr:4 row_mask:0xf bank_mask:0xa bound_ctrl:1
	v_add_f32_dpp v109, v107, v107 row_shr:4 row_mask:0xf bank_mask:0xa bound_ctrl:1
	s_nop 1
	v_add_f32_dpp v32, v108, v108 row_shl:8 row_mask:0xf bank_mask:0x3 bound_ctrl:1
	s_nop 1
	v_add_f32_dpp v32, v109, v109 row_shr:8 row_mask:0xf bank_mask:0xc bound_ctrl:1
	s_andn2_b64 vcc, exec, s[96:97]
	v_cndmask_b32_e64 v30, v5, v40, s[0:1]
	v_add_u32_e32 v30, s82, v30
	v_ashrrev_i32_e32 v31, 31, v30
	v_lshlrev_b64 v[30:31], 10, v[30:31]
	v_lshl_add_u64 v[30:31], v[28:29], 0, v[30:31]
	global_store_dword v[30:31], v32, off
	s_cbranch_vccnz .LBB0_455
	s_bitcmp1_b32 s33, 0
	s_cselect_b32 s46, 0x6000, 0
	s_add_i32 s46, s78, s46
	s_waitcnt vmcnt(6)
	v_lshlrev_b32_e32 v30, 16, v10
	v_and_b32_e32 v31, 0xffff0000, v10
	v_lshlrev_b32_e32 v32, 16, v11
	v_and_b32_e32 v33, 0xffff0000, v11
	v_lshl_add_u32 v41, v7, 4, s46
	ds_write_b128 v41, v[30:33]
	s_waitcnt vmcnt(5)
	v_lshlrev_b32_e32 v30, 16, v12
	v_and_b32_e32 v31, 0xffff0000, v12
	v_lshlrev_b32_e32 v32, 16, v13
	v_and_b32_e32 v33, 0xffff0000, v13
	v_lshl_add_u32 v42, v36, 4, s46
	ds_write_b128 v42, v[30:33] offset:4096
	s_waitcnt vmcnt(4)
	v_lshlrev_b32_e32 v30, 16, v14
	v_and_b32_e32 v31, 0xffff0000, v14
	v_lshlrev_b32_e32 v32, 16, v15
	v_and_b32_e32 v33, 0xffff0000, v15
	ds_write_b128 v42, v[30:33] offset:8192
	s_waitcnt vmcnt(3)
	v_lshlrev_b32_e32 v30, 16, v16
	v_and_b32_e32 v31, 0xffff0000, v16
	v_lshlrev_b32_e32 v32, 16, v17
	v_and_b32_e32 v33, 0xffff0000, v17
	ds_write_b128 v42, v[30:33] offset:12288
	s_waitcnt vmcnt(2)
	v_lshlrev_b32_e32 v30, 16, v18
	v_and_b32_e32 v31, 0xffff0000, v18
	v_lshlrev_b32_e32 v32, 16, v19
	v_and_b32_e32 v33, 0xffff0000, v19
	ds_write_b128 v42, v[30:33] offset:16384
	s_waitcnt vmcnt(1)
	v_lshlrev_b32_e32 v30, 16, v35
	v_add_u32_e32 v31, v41, v37
	ds_write_b32 v31, v30 offset:20480

.LBB0_477:
	s_and_b64 s[0:1], s[16:17], exec
	s_movk_i32 s0, 0x380
	s_cselect_b32 s0, s0, 0x400
	v_or_b32_e32 v0, s0, v76
	v_lshl_or_b32 v2, s22, 7, v126
	v_readlane_b32 s60, v253, 46
	v_lshlrev_b32_e32 v128, 1, v0
	v_ashrrev_i32_e32 v3, 31, v2
	v_readlane_b32 s72, v253, 58
	v_readlane_b32 s73, v253, 59
	v_lshl_add_u64 v[0:1], s[4:5], 0, v[128:129]
	s_waitcnt vmcnt(0)
	v_lshl_add_u64 v[2:3], v[2:3], 2, s[72:73]
	s_barrier
	global_load_dword v2, v[2:3], off
	s_cselect_b32 s45, -1, 1
	v_readlane_b32 s61, v253, 47
	v_readlane_b32 s62, v253, 48
	v_readlane_b32 s63, v253, 49
	v_readlane_b32 s64, v253, 50
	v_readlane_b32 s65, v253, 51
	v_readlane_b32 s66, v253, 52
	v_readlane_b32 s67, v253, 53
	v_readlane_b32 s68, v253, 54
	v_readlane_b32 s69, v253, 55
	v_readlane_b32 s70, v253, 56
	v_readlane_b32 s71, v253, 57
	v_readlane_b32 s74, v253, 60
	v_readlane_b32 s75, v253, 61
	v_mov_b32_e32 v3, s45
	v_cndmask_b32_e64 v4, v83, 0, s[16:17]
	v_cmp_eq_u32_e32 vcc, v84, v4
	v_lshl_add_u64 v[4:5], v[0:1], 0, v[40:41]
	global_load_ushort v138, v[4:5], off
	v_cndmask_b32_e64 v4, v3, 0, vcc
	v_cndmask_b32_e64 v16, 1.0, 0, vcc
	v_add_u32_e32 v4, v4, v82
	v_mad_i64_i32 v[4:5], s[0:1], v4, s87, v[0:1]
	global_load_ushort v148, v[4:5], off
	v_cndmask_b32_e64 v4, v87, 0, s[16:17]
	v_cmp_eq_u32_e32 vcc, v88, v4
	v_lshl_add_u64 v[4:5], v[0:1], 0, v[42:43]
	global_load_ushort v139, v[4:5], off
	v_cndmask_b32_e64 v4, v3, 0, vcc
	v_cndmask_b32_e64 v17, 1.0, 0, vcc
	v_add_u32_e32 v4, v4, v86
	v_mad_i64_i32 v[4:5], s[0:1], v4, s87, v[0:1]
	global_load_ushort v149, v[4:5], off
	v_cndmask_b32_e64 v4, v91, 0, s[16:17]
	v_cmp_eq_u32_e32 vcc, v92, v4
	v_lshl_add_u64 v[4:5], v[0:1], 0, v[44:45]
	global_load_ushort v140, v[4:5], off
	v_cndmask_b32_e64 v4, v3, 0, vcc
	v_cndmask_b32_e64 v18, 1.0, 0, vcc
	v_add_u32_e32 v4, v4, v90
	v_mad_i64_i32 v[4:5], s[0:1], v4, s87, v[0:1]
	global_load_ushort v150, v[4:5], off
	v_cndmask_b32_e64 v4, v95, 0, s[16:17]
	v_cmp_eq_u32_e32 vcc, v96, v4
	v_lshl_add_u64 v[4:5], v[0:1], 0, v[46:47]
	global_load_ushort v141, v[4:5], off
	v_cndmask_b32_e64 v4, v3, 0, vcc
	v_cndmask_b32_e64 v19, 1.0, 0, vcc
	v_add_u32_e32 v4, v4, v94
	v_mad_i64_i32 v[4:5], s[0:1], v4, s87, v[0:1]
	global_load_ushort v151, v[4:5], off
	v_cndmask_b32_e64 v4, v99, 0, s[16:17]
	v_cmp_eq_u32_e32 vcc, v100, v4
	v_lshl_add_u64 v[4:5], v[0:1], 0, v[48:49]
	global_load_ushort v142, v[4:5], off
	v_cndmask_b32_e64 v4, v3, 0, vcc
	v_cndmask_b32_e64 v20, 1.0, 0, vcc
	v_add_u32_e32 v4, v4, v98
	v_mad_i64_i32 v[4:5], s[0:1], v4, s87, v[0:1]
	global_load_ushort v152, v[4:5], off
	v_cndmask_b32_e64 v4, v103, 0, s[16:17]
	v_cmp_eq_u32_e32 vcc, v104, v4
	v_lshl_add_u64 v[4:5], v[0:1], 0, v[50:51]
	global_load_ushort v143, v[4:5], off
	v_cndmask_b32_e64 v4, v3, 0, vcc
	v_cndmask_b32_e64 v21, 1.0, 0, vcc
	v_add_u32_e32 v4, v4, v102
	v_mad_i64_i32 v[4:5], s[0:1], v4, s87, v[0:1]
	global_load_ushort v153, v[4:5], off
	v_cndmask_b32_e64 v4, v107, 0, s[16:17]
	v_cmp_eq_u32_e32 vcc, v108, v4
	v_lshl_add_u64 v[4:5], v[0:1], 0, v[52:53]
	global_load_ushort v144, v[4:5], off
	v_cndmask_b32_e64 v4, v3, 0, vcc
	v_cndmask_b32_e64 v22, 1.0, 0, vcc
	v_add_u32_e32 v4, v4, v106
	v_mad_i64_i32 v[4:5], s[0:1], v4, s87, v[0:1]
	global_load_ushort v154, v[4:5], off
	v_cndmask_b32_e64 v4, v111, 0, s[16:17]
	v_cmp_eq_u32_e32 vcc, v112, v4
	v_lshl_add_u64 v[4:5], v[0:1], 0, v[54:55]
	global_load_ushort v145, v[4:5], off
	v_cndmask_b32_e64 v4, v3, 0, vcc
	v_cndmask_b32_e64 v23, 1.0, 0, vcc
	v_add_u32_e32 v4, v4, v110
	v_mad_i64_i32 v[4:5], s[0:1], v4, s87, v[0:1]
	global_load_ushort v155, v[4:5], off
	v_cndmask_b32_e64 v4, v115, 0, s[16:17]
	v_cmp_eq_u32_e32 vcc, v116, v4
	v_lshl_add_u64 v[4:5], v[0:1], 0, v[56:57]
	global_load_ushort v146, v[4:5], off
	v_cndmask_b32_e64 v4, v3, 0, vcc
	v_cndmask_b32_e64 v24, 1.0, 0, vcc
	v_add_u32_e32 v4, v4, v114
	v_mad_i64_i32 v[4:5], s[0:1], v4, s87, v[0:1]
	global_load_ushort v156, v[4:5], off
	v_cndmask_b32_e64 v4, v119, 0, s[16:17]
	v_cmp_eq_u32_e32 vcc, v120, v4
	v_lshl_add_u64 v[4:5], v[0:1], 0, v[58:59]
	global_load_ushort v147, v[4:5], off
	v_cndmask_b32_e64 v4, v3, 0, vcc
	v_cndmask_b32_e64 v25, 1.0, 0, vcc
	v_add_u32_e32 v4, v4, v118
	v_mad_i64_i32 v[4:5], s[0:1], v4, s87, v[0:1]
	global_load_ushort v157, v[4:5], off
	s_waitcnt vmcnt(0)
	v_lshlrev_b32_e32 v6, 16, v138
	v_lshlrev_b32_e32 v7, 16, v139
	v_lshlrev_b32_e32 v4, 16, v148
	v_lshlrev_b32_e32 v5, 16, v149
	v_fma_f32 v4, v16, v4, -v6
	v_fma_f32 v5, v17, v5, -v7
	v_fmac_f32_e32 v6, v2, v4
	v_fmac_f32_e32 v7, v2, v5
	v_add_f32_e32 v4, v6, v6
	v_add_f32_e32 v5, v7, v7
	v_mul_f32_e32 v4, 0x3fb8aa3b, v4
	v_mul_f32_e32 v5, 0x3fb8aa3b, v5
	v_exp_f32_e32 v4, v4
	v_exp_f32_e32 v5, v5
	s_nop 0
	v_add_f32_e32 v4, 1.0, v4
	v_add_f32_e32 v5, 1.0, v5
	v_rcp_f32_e32 v4, v4
	v_rcp_f32_e32 v5, v5
	s_nop 0
	v_fma_f32 v4, v4, -2.0, 1.0
	v_fma_f32 v5, v5, -2.0, 1.0
	v_cndmask_b32_e64 v4, v6, v4, s[36:37]
	v_cndmask_b32_e64 v5, v7, v5, s[36:37]
	v_cvt_pk_bf16_f32 v4, v4, s0
	v_cvt_pk_bf16_f32 v5, v5, s0
	ds_write_b16 v85, v4
	ds_write_b16 v89, v5
	v_lshlrev_b32_e32 v6, 16, v140
	v_lshlrev_b32_e32 v7, 16, v141
	v_lshlrev_b32_e32 v4, 16, v150
	v_lshlrev_b32_e32 v5, 16, v151
	v_fma_f32 v4, v18, v4, -v6
	v_fma_f32 v5, v19, v5, -v7
	v_fmac_f32_e32 v6, v2, v4
	v_fmac_f32_e32 v7, v2, v5
	v_add_f32_e32 v4, v6, v6
	v_add_f32_e32 v5, v7, v7
	v_mul_f32_e32 v4, 0x3fb8aa3b, v4
	v_mul_f32_e32 v5, 0x3fb8aa3b, v5
	v_exp_f32_e32 v4, v4
	v_exp_f32_e32 v5, v5
	s_nop 0
	v_add_f32_e32 v4, 1.0, v4
	v_add_f32_e32 v5, 1.0, v5
	v_rcp_f32_e32 v4, v4
	v_rcp_f32_e32 v5, v5
	s_nop 0
	v_fma_f32 v4, v4, -2.0, 1.0
	v_fma_f32 v5, v5, -2.0, 1.0
	v_cndmask_b32_e64 v4, v6, v4, s[36:37]
	v_cndmask_b32_e64 v5, v7, v5, s[36:37]
	v_cvt_pk_bf16_f32 v4, v4, s0
	v_cvt_pk_bf16_f32 v5, v5, s0
	ds_write_b16 v93, v4
	ds_write_b16 v97, v5
	v_lshlrev_b32_e32 v6, 16, v142
	v_lshlrev_b32_e32 v7, 16, v143
	v_lshlrev_b32_e32 v4, 16, v152
	v_lshlrev_b32_e32 v5, 16, v153
	v_fma_f32 v4, v20, v4, -v6
	v_fma_f32 v5, v21, v5, -v7
	v_fmac_f32_e32 v6, v2, v4
	v_fmac_f32_e32 v7, v2, v5
	v_add_f32_e32 v4, v6, v6
	v_add_f32_e32 v5, v7, v7
	v_mul_f32_e32 v4, 0x3fb8aa3b, v4
	v_mul_f32_e32 v5, 0x3fb8aa3b, v5
	v_exp_f32_e32 v4, v4
	v_exp_f32_e32 v5, v5
	s_nop 0
	v_add_f32_e32 v4, 1.0, v4
	v_add_f32_e32 v5, 1.0, v5
	v_rcp_f32_e32 v4, v4
	v_rcp_f32_e32 v5, v5
	s_nop 0
	v_fma_f32 v4, v4, -2.0, 1.0
	v_fma_f32 v5, v5, -2.0, 1.0
	v_cndmask_b32_e64 v4, v6, v4, s[36:37]
	v_cndmask_b32_e64 v5, v7, v5, s[36:37]
	v_cvt_pk_bf16_f32 v4, v4, s0
	v_cvt_pk_bf16_f32 v5, v5, s0
	ds_write_b16 v101, v4
	ds_write_b16 v105, v5
	v_lshlrev_b32_e32 v6, 16, v144
	v_lshlrev_b32_e32 v7, 16, v145
	v_lshlrev_b32_e32 v4, 16, v154
	v_lshlrev_b32_e32 v5, 16, v155
	v_fma_f32 v4, v22, v4, -v6
	v_fma_f32 v5, v23, v5, -v7
	v_fmac_f32_e32 v6, v2, v4
	v_fmac_f32_e32 v7, v2, v5
	v_add_f32_e32 v4, v6, v6
	v_add_f32_e32 v5, v7, v7
	v_mul_f32_e32 v4, 0x3fb8aa3b, v4
	v_mul_f32_e32 v5, 0x3fb8aa3b, v5
	v_exp_f32_e32 v4, v4
	v_exp_f32_e32 v5, v5
	s_nop 0
	v_add_f32_e32 v4, 1.0, v4
	v_add_f32_e32 v5, 1.0, v5
	v_rcp_f32_e32 v4, v4
	v_rcp_f32_e32 v5, v5
	s_nop 0
	v_fma_f32 v4, v4, -2.0, 1.0
	v_fma_f32 v5, v5, -2.0, 1.0
	v_cndmask_b32_e64 v4, v6, v4, s[36:37]
	v_cndmask_b32_e64 v5, v7, v5, s[36:37]
	v_cvt_pk_bf16_f32 v4, v4, s0
	v_cvt_pk_bf16_f32 v5, v5, s0
	ds_write_b16 v109, v4
	ds_write_b16 v113, v5
	v_lshlrev_b32_e32 v6, 16, v146
	v_lshlrev_b32_e32 v7, 16, v147
	v_lshlrev_b32_e32 v4, 16, v156
	v_lshlrev_b32_e32 v5, 16, v157
	v_fma_f32 v4, v24, v4, -v6
	v_fma_f32 v5, v25, v5, -v7
	v_fmac_f32_e32 v6, v2, v4
	v_fmac_f32_e32 v7, v2, v5
	v_add_f32_e32 v4, v6, v6
	v_add_f32_e32 v5, v7, v7
	v_mul_f32_e32 v4, 0x3fb8aa3b, v4
	v_mul_f32_e32 v5, 0x3fb8aa3b, v5
	v_exp_f32_e32 v4, v4
	v_exp_f32_e32 v5, v5
	s_nop 0
	v_add_f32_e32 v4, 1.0, v4
	v_add_f32_e32 v5, 1.0, v5
	v_rcp_f32_e32 v4, v4
	v_rcp_f32_e32 v5, v5
	s_nop 0
	v_fma_f32 v4, v4, -2.0, 1.0
	v_fma_f32 v5, v5, -2.0, 1.0
	v_cndmask_b32_e64 v4, v6, v4, s[36:37]
	v_cndmask_b32_e64 v5, v7, v5, s[36:37]
	v_cvt_pk_bf16_f32 v4, v4, s0
	v_cvt_pk_bf16_f32 v5, v5, s0
	ds_write_b16 v117, v4
	ds_write_b16 v121, v5
	s_or_b32 s0, s22, s33
	s_ashr_i32 s1, s0, 31
	s_lshl_b64 s[6:7], s[0:1], 15
	v_lshl_add_u64 v[72:73], v[64:65], 0, s[6:7]
	s_mov_b64 s[6:7], 0x17bce000
	v_lshl_add_u64 v[74:75], v[72:73], 0, s[6:7]
	v_lshl_add_u64 v[134:135], v[74:75], 0, v[60:61]
	s_waitcnt lgkmcnt(0)
	s_barrier
	ds_read_b128 v[28:31], v77
	ds_read_b128 v[24:27], v77 offset:32
	ds_read_b128 v[20:23], v77 offset:64
	ds_read_b128 v[16:19], v77 offset:96
	global_load_dwordx4 v[0:3], v[134:135], off
	global_load_dwordx4 v[138:141], v[134:135], off offset:32
	s_waitcnt vmcnt(1) lgkmcnt(3)
	v_mfma_f32_32x32x16_bf16 v[0:15], v[28:31], v[0:3], 0
	s_waitcnt vmcnt(0) lgkmcnt(2)
	v_mfma_f32_32x32x16_bf16 v[0:15], v[24:27], v[138:141], v[0:15]
	global_load_dwordx4 v[138:141], v[134:135], off offset:64
	s_waitcnt vmcnt(0) lgkmcnt(1)
	v_mfma_f32_32x32x16_bf16 v[0:15], v[20:23], v[138:141], v[0:15]
	global_load_dwordx4 v[138:141], v[134:135], off offset:96
	s_waitcnt vmcnt(0) lgkmcnt(0)
	v_mfma_f32_32x32x16_bf16 v[0:15], v[16:19], v[138:141], v[0:15]
	s_nop 11
	ds_write2st64_b32 v122, v0, v1 offset0:34 offset1:38
	ds_write2st64_b32 v122, v2, v3 offset0:42 offset1:46
	ds_write2st64_b32 v122, v4, v5 offset0:66 offset1:70
	ds_write2st64_b32 v122, v6, v7 offset0:74 offset1:78
	s_and_saveexec_b64 s[6:7], s[38:39]
	s_cbranch_execz .LBB0_479
	ds_write2st64_b32 v123, v8, v9 offset0:98 offset1:102
	ds_write2st64_b32 v123, v10, v11 offset0:106 offset1:110

.LBB0_487:
	s_add_u32 s40, s8, s24
	s_addc_u32 s41, 0, s25
	s_cmpk_lt_i32 s40, 0x2000
	s_cselect_b32 s6, 0xff, s91
	s_and_b32 s7, s6, s40
	s_and_b64 s[0:1], s[16:17], exec
	s_cselect_b32 s0, 0, s6
	s_cmp_eq_u32 s7, s0
	s_cselect_b64 s[96:97], -1, 0
	s_and_b64 s[0:1], s[96:97], exec
	s_cselect_b32 s0, 0, s45
	s_ashr_i32 s1, s0, 31
	s_add_u32 s6, s8, s24
	s_addc_u32 s7, s9, s25
	s_add_u32 s0, s6, s0
	s_addc_u32 s1, s7, s1
	s_add_u32 s30, s40, 1
	s_addc_u32 s31, s41, 0
	s_mul_i32 s6, s1, 0x1d00
	v_mad_u64_u32 v[2:3], s[0:1], s0, v173, v[36:37]
	s_cmpk_lt_i32 s30, 0x2000
	v_add_u32_e32 v3, s6, v3
	s_cselect_b32 s6, 0xff, s91
	s_and_b32 s7, s6, s30
	s_and_b64 s[0:1], s[16:17], exec
	s_cselect_b32 s0, 0, s6
	s_cmp_eq_u32 s7, s0
	v_lshl_add_u64 v[0:1], s[26:27], 0, v[34:35]
	s_cselect_b64 s[6:7], -1, 0
	global_load_ushort v22, v[0:1], off offset:-512
	global_load_ushort v23, v[0:1], off
	global_load_ushort v25, v[0:1], off offset:512
	global_load_ushort v29, v[2:3], off
	global_load_ushort v30, v[2:3], off offset:512
	global_load_ushort v31, v[2:3], off offset:1024
	v_mad_i64_i32 v[0:1], s[0:1], s30, v173, v[36:37]
	s_and_b64 s[0:1], s[6:7], exec
	s_cselect_b32 s0, 0, s45
	s_add_i32 s0, s40, s0
	s_add_i32 s0, s0, 1
	s_add_u32 s34, s40, 2
	s_addc_u32 s35, s41, 0
	s_cmpk_lt_i32 s34, 0x2000
	s_cselect_b32 s42, 0xff, s91
	s_and_b32 s43, s42, s34
	v_mad_i64_i32 v[2:3], s[0:1], s0, v173, v[36:37]
	s_and_b64 s[0:1], s[16:17], exec
	s_cselect_b32 s0, 0, s42
	s_cmp_eq_u32 s43, s0
	s_cselect_b64 s[76:77], -1, 0
	v_mad_i64_i32 v[4:5], s[0:1], s34, v173, v[36:37]
	s_and_b64 s[0:1], s[76:77], exec
	s_cselect_b32 s0, 0, s45
	s_add_i32 s0, s40, s0
	s_add_i32 s0, s0, 2
	s_add_u32 s82, s40, 3
	s_addc_u32 s83, s41, 0
	s_cmpk_lt_i32 s82, 0x2000
	s_cselect_b32 s42, 0xff, s91
	s_and_b32 s43, s42, s82
	v_mad_i64_i32 v[6:7], s[0:1], s0, v173, v[36:37]
	s_and_b64 s[0:1], s[16:17], exec
	s_cselect_b32 s0, 0, s42
	s_cmp_eq_u32 s43, s0
	s_cselect_b64 s[78:79], -1, 0
	global_load_ushort v74, v[0:1], off
	global_load_ushort v75, v[0:1], off offset:512
	global_load_ushort v128, v[0:1], off offset:1024
	global_load_ushort v138, v[2:3], off
	global_load_ushort v139, v[2:3], off offset:512
	global_load_ushort v140, v[2:3], off offset:1024
	global_load_ushort v72, v[4:5], off
	global_load_ushort v73, v[4:5], off offset:512
	v_mad_i64_i32 v[0:1], s[0:1], s82, v173, v[36:37]
	s_and_b64 s[0:1], s[78:79], exec
	s_cselect_b32 s0, 0, s45
	s_add_i32 s0, s40, s0
	s_add_i32 s0, s0, 3
	s_add_u32 s84, s40, 4
	s_addc_u32 s85, s41, 0
	s_cmpk_lt_i32 s84, 0x2000
	s_cselect_b32 s41, 0xff, s91
	s_and_b32 s42, s41, s84
	v_mad_i64_i32 v[2:3], s[0:1], s0, v173, v[36:37]
	s_and_b64 s[0:1], s[16:17], exec
	s_cselect_b32 s0, 0, s41
	s_cmp_eq_u32 s42, s0
	s_cselect_b64 s[80:81], -1, 0
	global_load_ushort v145, v[4:5], off offset:1024
	global_load_ushort v146, v[6:7], off
	global_load_ushort v147, v[6:7], off offset:512
	global_load_ushort v148, v[6:7], off offset:1024
	global_load_ushort v141, v[0:1], off
	global_load_ushort v142, v[0:1], off offset:512
	global_load_ushort v143, v[0:1], off offset:1024
	global_load_ushort v144, v[2:3], off
	v_mad_i64_i32 v[0:1], s[0:1], s84, v173, v[36:37]
	s_and_b64 s[0:1], s[80:81], exec
	s_cselect_b32 s0, 0, s45
	s_add_i32 s0, s40, s0
	s_add_i32 s0, s0, 4
	v_mad_i64_i32 v[4:5], s[0:1], s0, v173, v[36:37]
	global_load_ushort v155, v[2:3], off offset:512
	global_load_ushort v156, v[2:3], off offset:1024
	global_load_ushort v149, v[0:1], off
	global_load_ushort v150, v[0:1], off offset:512
	global_load_ushort v151, v[0:1], off offset:1024
	global_load_ushort v152, v[4:5], off
	global_load_ushort v153, v[4:5], off offset:512
	global_load_ushort v154, v[4:5], off offset:1024
	ds_read2st64_b32 v[8:9], v20 offset1:4
	ds_read2st64_b32 v[0:1], v20 offset0:16 offset1:80
	ds_read2st64_b32 v[6:7], v20 offset0:84 offset1:88
	ds_read2st64_b32 v[4:5], v20 offset0:8 offset1:12
	ds_read2st64_b32 v[2:3], v20 offset0:92 offset1:96
	s_bfe_i64 s[42:43], s[30:31], 0x200000
	s_bfe_i64 s[40:41], s[34:35], 0x200000
	s_bfe_i64 s[34:35], s[82:83], 0x200000
	s_bfe_i64 s[30:31], s[84:85], 0x200000
	v_mov_b32_e32 v28, 0
	v_mov_b32_e32 v27, 0
	v_mov_b32_e32 v26, 0
	v_mov_b32_e32 v24, 0
	v_mov_b32_e32 v21, 0
	v_lshl_add_u64 v[10:11], s[28:29], 0, v[34:35]
	s_andn2_b64 vcc, exec, s[14:15]
	s_cbranch_vccnz .LBB0_486
	global_load_ushort v28, v[10:11], off
	s_lshl_b64 s[0:1], s[42:43], 9
	v_lshl_add_u64 v[134:135], v[38:39], 0, s[0:1]
	global_load_ushort v27, v[134:135], off
	s_lshl_b64 s[0:1], s[40:41], 9
	v_lshl_add_u64 v[134:135], v[38:39], 0, s[0:1]
	global_load_ushort v26, v[134:135], off
	s_lshl_b64 s[0:1], s[34:35], 9
	v_lshl_add_u64 v[134:135], v[38:39], 0, s[0:1]
	global_load_ushort v24, v[134:135], off
	s_lshl_b64 s[0:1], s[30:31], 9
	v_lshl_add_u64 v[134:135], v[38:39], 0, s[0:1]
	global_load_ushort v21, v[134:135], off
	s_waitcnt vmcnt(0)
	v_lshlrev_b32_e32 v28, 16, v28
	v_lshlrev_b32_e32 v27, 16, v27
	v_lshlrev_b32_e32 v26, 16, v26
	v_lshlrev_b32_e32 v24, 16, v24
	v_lshlrev_b32_e32 v21, 16, v21
	s_branch .LBB0_486
